# FoX fast path: c0 folded into QK MFMA accumulator init (f32), removed redundant setprio flips in GEMM segments, DPP in DN-prep transposes
# speedup vs baseline: 1.0145x; 1.0006x over previous
; #define PG8_STAGE(bufoff, gbase, voff) do { _Pragma("unroll") for (int _i = 0; _i < 2; ++_i) \
;         __builtin_amdgcn_global_load_lds((const unsigned*)((const char*)(gbase) + (voff)[_i]), (LAS unsigned*)(lds + (bufoff) + ldsw + _i * 8192), 16, 0, 0); } while (0)
; #define PG8_LDA(dst, b, h) do { _Pragma("unroll") for (int m = 0; m < 4; ++m) _Pragma("unroll") for (int k = 0; k < 2; ++k) dst[m][k] = *(const LAS bf16x8*)(lds + PG8_SA(b, h) + aoff + m * 2048 + k * 1024); } while (0)
; #define PG8_LDB(dst, b, h) do { _Pragma("unroll") for (int n = 0; n < 2; ++n) _Pragma("unroll") for (int k = 0; k < 2; ++k) dst[n][k] = *(const LAS bf16x8*)(lds + PG8_SB(b, h) + boff + n * 2048 + k * 1024); } while (0)
; #define PG8_MMA(ai, bj, At, Bt) do { __builtin_amdgcn_s_setprio(1); _Pragma("unroll") for (int m = 0; m < 4; ++m) _Pragma("unroll") for (int n = 0; n < 2; ++n) _Pragma("unroll") for (int k = 0; k < 2; ++k) \
;         acc[ai][bj][m][n] = __builtin_amdgcn_mfma_f32_16x16x32_bf16(Bt[n][k], At[m][k], acc[ai][bj][m][n], 0, 0, 0); __builtin_amdgcn_s_setprio(0); } while (0)
; #define PG8_WAIT_V(n) asm volatile("s_waitcnt vmcnt(" #n ")" ::: "memory")
; #define PG8_WAIT_L(n) asm volatile("s_waitcnt lgkmcnt(" #n ")" ::: "memory")
; #define PG8_BAR __builtin_amdgcn_s_barrier()
; #define PG8_SCHED __builtin_amdgcn_sched_barrier(0)
; template <class Epi>
; DI void gemm_phase(LAS unsigned char* lds, const Gemm g, const Epi& E, const int tid) {
;     ...
;         for (int t = 0; t < nt; t += 2) {
;             const bool last = (t == nt - 2);
;             const char* a1 = cA + (size_t)(t + 1) * kstepA;
;             const char* a2 = last ? nA : cA + (size_t)(t + 2) * kstepA; const char* b2 = last ? nB : cB + (size_t)(t + 2) * kstep;
;             const char* a3 = a2 + kstepA; const char* b3 = b2 + kstep;
;             PG8_LDB(B0, 0, 0); PG8_LDB(B1, 0, 1); PG8_SCHED; PG8_LDA(At, 0, 0); PG8_STAGE(PG8_SA(1, 1), a1 + hstepA, voffA);
;             PG8_WAIT_V(8); PG8_WAIT_L(0); PG8_BAR; PG8_MMA(0, 0, At, B0); PG8_MMA(0, 1, At, B1); PG8_BAR; PG8_SCHED;
;             PG8_LDA(At, 0, 1); PG8_STAGE(PG8_SB(0, 0), b2, voffB); PG8_STAGE(PG8_SB(0, 1), b2 + hstepB, voffB); PG8_STAGE(PG8_SA(0, 0), a2, voffA);
;             PG8_WAIT_V(8); PG8_WAIT_L(0); PG8_BAR; PG8_MMA(1, 0, At, B0); PG8_MMA(1, 1, At, B1); PG8_BAR; PG8_SCHED;
.LBB0_92:
	s_add_u32 s12, s46, 0x7fc000
	s_addc_u32 s48, s47, 0
	s_cmp_eq_u32 s67, 60
	s_cselect_b32 s52, s63, s12
	s_cselect_b32 s53, s35, s48
	s_cselect_b32 s50, s64, s65
	s_cselect_b32 s51, s41, s66
	s_add_u32 s48, s52, 0x800000
	s_addc_u32 s49, s53, 0
	s_add_i32 s12, 0, 0x10000
	v_add_u32_e32 v144, s12, v147
	s_add_i32 s70, 0, 0x14000
	ds_read_b128 v[140:143], v144
	ds_read_b128 v[150:153], v144 offset:1024
	ds_read_b128 v[154:157], v144 offset:2048
	ds_read_b128 v[158:161], v144 offset:3072
	v_add_u32_e32 v144, s70, v147
	ds_read_b128 v[162:165], v144
	ds_read_b128 v[166:169], v144 offset:1024
	ds_read_b128 v[170:173], v144 offset:2048
	ds_read_b128 v[174:177], v144 offset:3072
	v_lshl_add_u64 v[144:145], s[46:47], 0, v[136:137]
	s_add_i32 m0, s54, 0xc000
	ds_read_b128 v[178:181], v149
	ds_read_b128 v[196:199], v149 offset:1024
	ds_read_b128 v[200:203], v149 offset:2048
	ds_read_b128 v[204:207], v149 offset:3072
	ds_read_b128 v[208:211], v149 offset:4096
	ds_read_b128 v[226:229], v149 offset:5120
	ds_read_b128 v[230:233], v149 offset:6144
	ds_read_b128 v[234:237], v149 offset:7168
	global_load_lds_dwordx4 v[144:145], off
	v_lshl_add_u64 v[144:145], s[46:47], 0, v[138:139]
	s_add_i32 m0, s54, 0xe000
	s_nop 0
	global_load_lds_dwordx4 v[144:145], off
	s_waitcnt vmcnt(8)
	s_waitcnt lgkmcnt(0)
	s_barrier
	s_setprio 1
	s_waitcnt lgkmcnt(0)
	v_mfma_f32_16x16x32_bf16 v[126:129], v[140:143], v[178:181], v[126:129]
	v_mfma_f32_16x16x32_bf16 v[122:125], v[154:157], v[178:181], v[122:125]
	v_mfma_f32_16x16x32_bf16 v[118:121], v[140:143], v[200:203], v[118:121]
	v_mfma_f32_16x16x32_bf16 v[110:113], v[154:157], v[200:203], v[110:113]
	v_mfma_f32_16x16x32_bf16 v[94:97], v[140:143], v[208:211], v[94:97]
	v_mfma_f32_16x16x32_bf16 v[90:93], v[154:157], v[208:211], v[90:93]
	v_mfma_f32_16x16x32_bf16 v[86:89], v[140:143], v[230:233], v[86:89]
	v_mfma_f32_16x16x32_bf16 v[78:81], v[154:157], v[230:233], v[78:81]
	v_mfma_f32_16x16x32_bf16 v[126:129], v[150:153], v[196:199], v[126:129]
	v_mfma_f32_16x16x32_bf16 v[122:125], v[158:161], v[196:199], v[122:125]
	v_mfma_f32_16x16x32_bf16 v[118:121], v[150:153], v[204:207], v[118:121]
	v_mfma_f32_16x16x32_bf16 v[110:113], v[158:161], v[204:207], v[110:113]
	v_mfma_f32_16x16x32_bf16 v[94:97], v[150:153], v[226:229], v[94:97]
	v_mfma_f32_16x16x32_bf16 v[90:93], v[158:161], v[226:229], v[90:93]
	v_mfma_f32_16x16x32_bf16 v[86:89], v[150:153], v[234:237], v[86:89]
	v_mfma_f32_16x16x32_bf16 v[78:81], v[158:161], v[234:237], v[78:81]
	v_mfma_f32_16x16x32_bf16 v[114:117], v[162:165], v[178:181], v[114:117]
	v_mfma_f32_16x16x32_bf16 v[106:109], v[170:173], v[178:181], v[106:109]
	v_mfma_f32_16x16x32_bf16 v[102:105], v[162:165], v[200:203], v[102:105]
	v_mfma_f32_16x16x32_bf16 v[98:101], v[170:173], v[200:203], v[98:101]
	v_mfma_f32_16x16x32_bf16 v[82:85], v[162:165], v[208:211], v[82:85]
	v_mfma_f32_16x16x32_bf16 v[74:77], v[170:173], v[208:211], v[74:77]
	v_mfma_f32_16x16x32_bf16 v[70:73], v[162:165], v[230:233], v[70:73]
	v_mfma_f32_16x16x32_bf16 v[66:69], v[170:173], v[230:233], v[66:69]
	v_mfma_f32_16x16x32_bf16 v[114:117], v[166:169], v[196:199], v[114:117]
	v_mfma_f32_16x16x32_bf16 v[106:109], v[174:177], v[196:199], v[106:109]
	v_mfma_f32_16x16x32_bf16 v[102:105], v[166:169], v[204:207], v[102:105]
	v_mfma_f32_16x16x32_bf16 v[98:101], v[174:177], v[204:207], v[98:101]
	v_mfma_f32_16x16x32_bf16 v[82:85], v[166:169], v[226:229], v[82:85]
	v_mfma_f32_16x16x32_bf16 v[74:77], v[174:177], v[226:229], v[74:77]
	v_mfma_f32_16x16x32_bf16 v[70:73], v[166:169], v[234:237], v[70:73]
	v_mfma_f32_16x16x32_bf16 v[66:69], v[174:177], v[234:237], v[66:69]
	s_setprio 0
	s_barrier
	s_add_i32 s12, s12, s13
	v_lshl_add_u64 v[144:145], s[50:51], 0, v[0:1]
	s_mov_b32 m0, s12
	ds_read_b128 v[178:181], v149 offset:16384
	ds_read_b128 v[196:199], v149 offset:17408
	ds_read_b128 v[200:203], v149 offset:18432
	ds_read_b128 v[204:207], v149 offset:19456
	ds_read_b128 v[208:211], v149 offset:20480
	ds_read_b128 v[226:229], v149 offset:21504
	ds_read_b128 v[230:233], v149 offset:22528
	ds_read_b128 v[234:237], v149 offset:23552
	global_load_lds_dwordx4 v[144:145], off
	s_add_i32 m0, s12, 0x2000
	s_add_u32 s68, s50, 0x100000
	v_lshl_add_u64 v[182:183], s[50:51], 0, v[130:131]
	s_addc_u32 s69, s51, 0
	s_add_i32 s12, s70, s13
	global_load_lds_dwordx4 v[182:183], off
	v_lshl_add_u64 v[186:187], s[68:69], 0, v[0:1]
	s_mov_b32 m0, s12
	s_nop 0
	global_load_lds_dwordx4 v[186:187], off
	v_lshl_add_u64 v[186:187], s[68:69], 0, v[130:131]
	s_add_i32 m0, s12, 0x2000
	s_nop 0
	global_load_lds_dwordx4 v[186:187], off
	v_lshl_add_u64 v[186:187], s[52:53], 0, v[134:135]
	s_mov_b32 m0, s54
	s_nop 0
	global_load_lds_dwordx4 v[186:187], off
	v_lshl_add_u64 v[186:187], s[52:53], 0, v[132:133]
	s_mov_b32 m0, s55
	s_nop 0
	global_load_lds_dwordx4 v[186:187], off
	s_waitcnt vmcnt(8)
	s_waitcnt lgkmcnt(0)
	s_barrier
; #define PG8_STAGE(bufoff, gbase, voff) do { _Pragma("unroll") for (int _i = 0; _i < 2; ++_i) \
;         __builtin_amdgcn_global_load_lds((const unsigned*)((const char*)(gbase) + (voff)[_i]), (LAS unsigned*)(lds + (bufoff) + ldsw + _i * 8192), 16, 0, 0); } while (0)
; #define PG8_LDA(dst, b, h) do { _Pragma("unroll") for (int m = 0; m < 4; ++m) _Pragma("unroll") for (int k = 0; k < 2; ++k) dst[m][k] = *(const LAS bf16x8*)(lds + PG8_SA(b, h) + aoff + m * 2048 + k * 1024); } while (0)
; #define PG8_LDB(dst, b, h) do { _Pragma("unroll") for (int n = 0; n < 2; ++n) _Pragma("unroll") for (int k = 0; k < 2; ++k) dst[n][k] = *(const LAS bf16x8*)(lds + PG8_SB(b, h) + boff + n * 2048 + k * 1024); } while (0)
; #define PG8_MMA(ai, bj, At, Bt) do { __builtin_amdgcn_s_setprio(1); _Pragma("unroll") for (int m = 0; m < 4; ++m) _Pragma("unroll") for (int n = 0; n < 2; ++n) _Pragma("unroll") for (int k = 0; k < 2; ++k) \
;         acc[ai][bj][m][n] = __builtin_amdgcn_mfma_f32_16x16x32_bf16(Bt[n][k], At[m][k], acc[ai][bj][m][n], 0, 0, 0); __builtin_amdgcn_s_setprio(0); } while (0)
; #define PG8_WAIT_V(n) asm volatile("s_waitcnt vmcnt(" #n ")" ::: "memory")
; #define PG8_WAIT_L(n) asm volatile("s_waitcnt lgkmcnt(" #n ")" ::: "memory")
; #define PG8_BAR __builtin_amdgcn_s_barrier()
; #define PG8_SCHED __builtin_amdgcn_sched_barrier(0)
; template <class Epi>
; DI void gemm_phase(LAS unsigned char* lds, const Gemm g, const Epi& E, const int tid) {
;     ...
;             PG8_WAIT_V(8); PG8_WAIT_L(0); PG8_BAR; PG8_MMA(1, 0, At, B0); PG8_MMA(1, 1, At, B1); PG8_BAR; PG8_SCHED;
;             PG8_LDB(B0, 1, 0); PG8_LDB(B1, 1, 1); PG8_SCHED; PG8_LDA(At, 1, 0); PG8_STAGE(PG8_SA(0, 1), a2 + hstepA, voffA);
;             PG8_WAIT_V(8); PG8_WAIT_L(0); PG8_BAR; PG8_MMA(0, 0, At, B0); PG8_MMA(0, 1, At, B1); PG8_BAR; PG8_SCHED;
;             PG8_LDA(At, 1, 1); PG8_STAGE(PG8_SB(1, 0), b3, voffB); PG8_STAGE(PG8_SB(1, 1), b3 + hstepB, voffB); PG8_STAGE(PG8_SA(1, 0), a3, voffA);
	s_setprio 1
	s_waitcnt lgkmcnt(0)
	v_mfma_f32_16x16x32_bf16 v[62:65], v[140:143], v[178:181], v[62:65]
	v_mfma_f32_16x16x32_bf16 v[58:61], v[154:157], v[178:181], v[58:61]
	v_mfma_f32_16x16x32_bf16 v[54:57], v[140:143], v[200:203], v[54:57]
	v_mfma_f32_16x16x32_bf16 v[46:49], v[154:157], v[200:203], v[46:49]
	v_mfma_f32_16x16x32_bf16 v[34:37], v[140:143], v[208:211], v[34:37]
	v_mfma_f32_16x16x32_bf16 v[26:29], v[154:157], v[208:211], v[26:29]
	v_mfma_f32_16x16x32_bf16 v[22:25], v[140:143], v[230:233], v[22:25]
	v_mfma_f32_16x16x32_bf16 v[14:17], v[154:157], v[230:233], v[14:17]
	v_mfma_f32_16x16x32_bf16 v[62:65], v[150:153], v[196:199], v[62:65]
	v_mfma_f32_16x16x32_bf16 v[58:61], v[158:161], v[196:199], v[58:61]
	v_mfma_f32_16x16x32_bf16 v[54:57], v[150:153], v[204:207], v[54:57]
	v_mfma_f32_16x16x32_bf16 v[46:49], v[158:161], v[204:207], v[46:49]
	v_mfma_f32_16x16x32_bf16 v[34:37], v[150:153], v[226:229], v[34:37]
	v_mfma_f32_16x16x32_bf16 v[26:29], v[158:161], v[226:229], v[26:29]
	v_mfma_f32_16x16x32_bf16 v[22:25], v[150:153], v[234:237], v[22:25]
	v_mfma_f32_16x16x32_bf16 v[14:17], v[158:161], v[234:237], v[14:17]
	v_mfma_f32_16x16x32_bf16 v[50:53], v[162:165], v[178:181], v[50:53]
	v_mfma_f32_16x16x32_bf16 v[42:45], v[170:173], v[178:181], v[42:45]
	v_mfma_f32_16x16x32_bf16 v[38:41], v[162:165], v[200:203], v[38:41]
	v_mfma_f32_16x16x32_bf16 v[30:33], v[170:173], v[200:203], v[30:33]
	v_mfma_f32_16x16x32_bf16 v[18:21], v[162:165], v[208:211], v[18:21]
	v_mfma_f32_16x16x32_bf16 v[10:13], v[170:173], v[208:211], v[10:13]
	v_mfma_f32_16x16x32_bf16 v[6:9], v[162:165], v[230:233], v[6:9]
	v_mfma_f32_16x16x32_bf16 v[2:5], v[170:173], v[230:233], v[2:5]
	v_mfma_f32_16x16x32_bf16 v[50:53], v[166:169], v[196:199], v[50:53]
	v_mfma_f32_16x16x32_bf16 v[42:45], v[174:177], v[196:199], v[42:45]
	v_mfma_f32_16x16x32_bf16 v[38:41], v[166:169], v[204:207], v[38:41]
	v_mfma_f32_16x16x32_bf16 v[30:33], v[174:177], v[204:207], v[30:33]
	v_mfma_f32_16x16x32_bf16 v[18:21], v[166:169], v[226:229], v[18:21]
	v_mfma_f32_16x16x32_bf16 v[10:13], v[174:177], v[226:229], v[10:13]
	v_mfma_f32_16x16x32_bf16 v[6:9], v[166:169], v[234:237], v[6:9]
	v_mfma_f32_16x16x32_bf16 v[2:5], v[174:177], v[234:237], v[2:5]
	s_setprio 0
	s_barrier
	s_add_i32 s12, 0, 0x18000
	s_add_i32 s68, 0, 0x1c000
	v_add_u32_e32 v158, s12, v147
	v_add_u32_e32 v174, s68, v147
	ds_read_b128 v[140:143], v158
	ds_read_b128 v[150:153], v158 offset:1024
	ds_read_b128 v[154:157], v158 offset:2048
	ds_read_b128 v[158:161], v158 offset:3072
	ds_read_b128 v[162:165], v174
	ds_read_b128 v[166:169], v174 offset:1024
	ds_read_b128 v[170:173], v174 offset:2048
	ds_read_b128 v[174:177], v174 offset:3072
	s_add_u32 s52, s52, 0x4000
	s_addc_u32 s53, s53, 0
	s_mov_b32 m0, s56
	v_lshl_add_u64 v[186:187], s[52:53], 0, v[134:135]
	ds_read_b128 v[178:181], v149 offset:32768
	ds_read_b128 v[196:199], v149 offset:33792
	ds_read_b128 v[200:203], v149 offset:34816
	ds_read_b128 v[204:207], v149 offset:35840
	ds_read_b128 v[208:211], v149 offset:36864
	ds_read_b128 v[226:229], v149 offset:37888
	ds_read_b128 v[230:233], v149 offset:38912
	ds_read_b128 v[234:237], v149 offset:39936
	global_load_lds_dwordx4 v[186:187], off
	v_lshl_add_u64 v[186:187], s[52:53], 0, v[132:133]
	s_mov_b32 m0, s57
	s_nop 0
	global_load_lds_dwordx4 v[186:187], off
	s_waitcnt vmcnt(8)
	s_waitcnt lgkmcnt(0)
	s_barrier
	s_setprio 1
	s_waitcnt lgkmcnt(0)
	v_mfma_f32_16x16x32_bf16 v[126:129], v[140:143], v[178:181], v[126:129]
	v_mfma_f32_16x16x32_bf16 v[122:125], v[154:157], v[178:181], v[122:125]
	v_mfma_f32_16x16x32_bf16 v[118:121], v[140:143], v[200:203], v[118:121]
	v_mfma_f32_16x16x32_bf16 v[110:113], v[154:157], v[200:203], v[110:113]
	v_mfma_f32_16x16x32_bf16 v[94:97], v[140:143], v[208:211], v[94:97]
	v_mfma_f32_16x16x32_bf16 v[90:93], v[154:157], v[208:211], v[90:93]
	v_mfma_f32_16x16x32_bf16 v[86:89], v[140:143], v[230:233], v[86:89]
	v_mfma_f32_16x16x32_bf16 v[78:81], v[154:157], v[230:233], v[78:81]
	v_mfma_f32_16x16x32_bf16 v[126:129], v[150:153], v[196:199], v[126:129]
	v_mfma_f32_16x16x32_bf16 v[122:125], v[158:161], v[196:199], v[122:125]
	v_mfma_f32_16x16x32_bf16 v[118:121], v[150:153], v[204:207], v[118:121]
	v_mfma_f32_16x16x32_bf16 v[110:113], v[158:161], v[204:207], v[110:113]
	v_mfma_f32_16x16x32_bf16 v[94:97], v[150:153], v[226:229], v[94:97]
	v_mfma_f32_16x16x32_bf16 v[90:93], v[158:161], v[226:229], v[90:93]
	v_mfma_f32_16x16x32_bf16 v[86:89], v[150:153], v[234:237], v[86:89]
	v_mfma_f32_16x16x32_bf16 v[78:81], v[158:161], v[234:237], v[78:81]
	v_mfma_f32_16x16x32_bf16 v[114:117], v[162:165], v[178:181], v[114:117]
	v_mfma_f32_16x16x32_bf16 v[106:109], v[170:173], v[178:181], v[106:109]
	v_mfma_f32_16x16x32_bf16 v[102:105], v[162:165], v[200:203], v[102:105]
	v_mfma_f32_16x16x32_bf16 v[98:101], v[170:173], v[200:203], v[98:101]
	v_mfma_f32_16x16x32_bf16 v[82:85], v[162:165], v[208:211], v[82:85]
	v_mfma_f32_16x16x32_bf16 v[74:77], v[170:173], v[208:211], v[74:77]
	v_mfma_f32_16x16x32_bf16 v[70:73], v[162:165], v[230:233], v[70:73]
	v_mfma_f32_16x16x32_bf16 v[66:69], v[170:173], v[230:233], v[66:69]
	v_mfma_f32_16x16x32_bf16 v[114:117], v[166:169], v[196:199], v[114:117]
	v_mfma_f32_16x16x32_bf16 v[106:109], v[174:177], v[196:199], v[106:109]
	v_mfma_f32_16x16x32_bf16 v[102:105], v[166:169], v[204:207], v[102:105]
	v_mfma_f32_16x16x32_bf16 v[98:101], v[174:177], v[204:207], v[98:101]
	v_mfma_f32_16x16x32_bf16 v[82:85], v[166:169], v[226:229], v[82:85]
	v_mfma_f32_16x16x32_bf16 v[74:77], v[174:177], v[226:229], v[74:77]
	v_mfma_f32_16x16x32_bf16 v[70:73], v[166:169], v[234:237], v[70:73]
	v_mfma_f32_16x16x32_bf16 v[66:69], v[174:177], v[234:237], v[66:69]
	s_setprio 0
	s_barrier
; #define PG8_STAGE(bufoff, gbase, voff) do { _Pragma("unroll") for (int _i = 0; _i < 2; ++_i) \
;         __builtin_amdgcn_global_load_lds((const unsigned*)((const char*)(gbase) + (voff)[_i]), (LAS unsigned*)(lds + (bufoff) + ldsw + _i * 8192), 16, 0, 0); } while (0)
; #define PG8_LDA(dst, b, h) do { _Pragma("unroll") for (int m = 0; m < 4; ++m) _Pragma("unroll") for (int k = 0; k < 2; ++k) dst[m][k] = *(const LAS bf16x8*)(lds + PG8_SA(b, h) + aoff + m * 2048 + k * 1024); } while (0)
; #define PG8_MMA(ai, bj, At, Bt) do { __builtin_amdgcn_s_setprio(1); _Pragma("unroll") for (int m = 0; m < 4; ++m) _Pragma("unroll") for (int n = 0; n < 2; ++n) _Pragma("unroll") for (int k = 0; k < 2; ++k) \
;         acc[ai][bj][m][n] = __builtin_amdgcn_mfma_f32_16x16x32_bf16(Bt[n][k], At[m][k], acc[ai][bj][m][n], 0, 0, 0); __builtin_amdgcn_s_setprio(0); } while (0)
; #define PG8_WAIT_V(n) asm volatile("s_waitcnt vmcnt(" #n ")" ::: "memory")
; #define PG8_WAIT_L(n) asm volatile("s_waitcnt lgkmcnt(" #n ")" ::: "memory")
; #define PG8_BAR __builtin_amdgcn_s_barrier()
; #define PG8_SCHED __builtin_amdgcn_sched_barrier(0)
; template <class Epi>
; DI void gemm_phase(LAS unsigned char* lds, const Gemm g, const Epi& E, const int tid) {
;     ...
;             PG8_WAIT_V(8); PG8_WAIT_L(0); PG8_BAR; PG8_MMA(0, 0, At, B0); PG8_MMA(0, 1, At, B1); PG8_BAR; PG8_SCHED;
;             PG8_LDA(At, 1, 1); PG8_STAGE(PG8_SB(1, 0), b3, voffB); PG8_STAGE(PG8_SB(1, 1), b3 + hstepB, voffB); PG8_STAGE(PG8_SA(1, 0), a3, voffA);
;             PG8_WAIT_V(8); PG8_WAIT_L(0); PG8_BAR; PG8_MMA(1, 0, At, B0); PG8_MMA(1, 1, At, B1); PG8_BAR; PG8_SCHED;
;         }
;         if (wr == 0) PG8_BAR;
	s_add_i32 s12, s12, s13
	v_lshl_add_u64 v[144:145], v[144:145], 0, s[8:9]
	s_mov_b32 m0, s12
	ds_read_b128 v[178:181], v149 offset:49152
	ds_read_b128 v[196:199], v149 offset:50176
	ds_read_b128 v[200:203], v149 offset:51200
	ds_read_b128 v[204:207], v149 offset:52224
	ds_read_b128 v[208:211], v149 offset:53248
	ds_read_b128 v[226:229], v149 offset:54272
	ds_read_b128 v[230:233], v149 offset:55296
	ds_read_b128 v[234:237], v149 offset:56320
	global_load_lds_dwordx4 v[144:145], off
	s_add_i32 m0, s12, 0x2000
	s_add_u32 s50, s50, 0x100080
	v_lshl_add_u64 v[144:145], v[182:183], 0, s[8:9]
	s_addc_u32 s51, s51, 0
	s_add_i32 s12, s68, s13
	global_load_lds_dwordx4 v[144:145], off
	v_lshl_add_u64 v[144:145], s[50:51], 0, v[0:1]
	s_mov_b32 m0, s12
	s_nop 0
	global_load_lds_dwordx4 v[144:145], off
	v_lshl_add_u64 v[144:145], s[50:51], 0, v[130:131]
	s_add_i32 m0, s12, 0x2000
	s_nop 0
	global_load_lds_dwordx4 v[144:145], off
	v_lshl_add_u64 v[144:145], s[48:49], 0, v[134:135]
	s_mov_b32 m0, s58
	s_nop 0
	global_load_lds_dwordx4 v[144:145], off
	v_lshl_add_u64 v[144:145], s[48:49], 0, v[132:133]
	s_mov_b32 m0, s59
	s_nop 0
	global_load_lds_dwordx4 v[144:145], off
	s_waitcnt vmcnt(8)
	s_waitcnt lgkmcnt(0)
	s_barrier
	s_setprio 1
	s_waitcnt lgkmcnt(0)
	v_mfma_f32_16x16x32_bf16 v[62:65], v[140:143], v[178:181], v[62:65]
	v_mfma_f32_16x16x32_bf16 v[58:61], v[154:157], v[178:181], v[58:61]
	v_mfma_f32_16x16x32_bf16 v[54:57], v[140:143], v[200:203], v[54:57]
	v_mfma_f32_16x16x32_bf16 v[46:49], v[154:157], v[200:203], v[46:49]
	v_mfma_f32_16x16x32_bf16 v[34:37], v[140:143], v[208:211], v[34:37]
	v_mfma_f32_16x16x32_bf16 v[26:29], v[154:157], v[208:211], v[26:29]
	v_mfma_f32_16x16x32_bf16 v[22:25], v[140:143], v[230:233], v[22:25]
	v_mfma_f32_16x16x32_bf16 v[14:17], v[154:157], v[230:233], v[14:17]
	v_mfma_f32_16x16x32_bf16 v[62:65], v[150:153], v[196:199], v[62:65]
	v_mfma_f32_16x16x32_bf16 v[58:61], v[158:161], v[196:199], v[58:61]
	v_mfma_f32_16x16x32_bf16 v[54:57], v[150:153], v[204:207], v[54:57]
	v_mfma_f32_16x16x32_bf16 v[46:49], v[158:161], v[204:207], v[46:49]
	v_mfma_f32_16x16x32_bf16 v[34:37], v[150:153], v[226:229], v[34:37]
	v_mfma_f32_16x16x32_bf16 v[26:29], v[158:161], v[226:229], v[26:29]
	v_mfma_f32_16x16x32_bf16 v[22:25], v[150:153], v[234:237], v[22:25]
	v_mfma_f32_16x16x32_bf16 v[14:17], v[158:161], v[234:237], v[14:17]
	v_mfma_f32_16x16x32_bf16 v[50:53], v[162:165], v[178:181], v[50:53]
	v_mfma_f32_16x16x32_bf16 v[42:45], v[170:173], v[178:181], v[42:45]
	v_mfma_f32_16x16x32_bf16 v[38:41], v[162:165], v[200:203], v[38:41]
	v_mfma_f32_16x16x32_bf16 v[30:33], v[170:173], v[200:203], v[30:33]
	v_mfma_f32_16x16x32_bf16 v[18:21], v[162:165], v[208:211], v[18:21]
	v_mfma_f32_16x16x32_bf16 v[10:13], v[170:173], v[208:211], v[10:13]
	v_mfma_f32_16x16x32_bf16 v[6:9], v[162:165], v[230:233], v[6:9]
	v_mfma_f32_16x16x32_bf16 v[2:5], v[170:173], v[230:233], v[2:5]
	v_mfma_f32_16x16x32_bf16 v[50:53], v[166:169], v[196:199], v[50:53]
	v_mfma_f32_16x16x32_bf16 v[42:45], v[174:177], v[196:199], v[42:45]
	v_mfma_f32_16x16x32_bf16 v[38:41], v[166:169], v[204:207], v[38:41]
	v_mfma_f32_16x16x32_bf16 v[30:33], v[174:177], v[204:207], v[30:33]
	v_mfma_f32_16x16x32_bf16 v[18:21], v[166:169], v[226:229], v[18:21]
	v_mfma_f32_16x16x32_bf16 v[10:13], v[174:177], v[226:229], v[10:13]
	v_mfma_f32_16x16x32_bf16 v[6:9], v[166:169], v[234:237], v[6:9]
	v_mfma_f32_16x16x32_bf16 v[2:5], v[174:177], v[234:237], v[2:5]
	s_setprio 0
	s_barrier
	s_add_i32 s67, s67, 2
	s_add_u32 s65, s65, 0x100
	s_addc_u32 s66, s66, 0
	s_add_u32 s46, s46, 0x1000000
	s_addc_u32 s47, s47, 0
	s_cmp_gt_u32 s67, 61
	s_cbranch_scc0 .LBB0_92
	s_and_b64 vcc, exec, s[24:25]
	s_cbranch_vccz .LBB0_95
	s_barrier

; #define PG8_STAGE(bufoff, gbase, voff) do { _Pragma("unroll") for (int _i = 0; _i < 2; ++_i) \
;         __builtin_amdgcn_global_load_lds((const unsigned*)((const char*)(gbase) + (voff)[_i]), (LAS unsigned*)(lds + (bufoff) + ldsw + _i * 8192), 16, 0, 0); } while (0)
; #define PG8_LDA(dst, b, h) do { _Pragma("unroll") for (int m = 0; m < 4; ++m) _Pragma("unroll") for (int k = 0; k < 2; ++k) dst[m][k] = *(const LAS bf16x8*)(lds + PG8_SA(b, h) + aoff + m * 2048 + k * 1024); } while (0)
; #define PG8_LDB(dst, b, h) do { _Pragma("unroll") for (int n = 0; n < 2; ++n) _Pragma("unroll") for (int k = 0; k < 2; ++k) dst[n][k] = *(const LAS bf16x8*)(lds + PG8_SB(b, h) + boff + n * 2048 + k * 1024); } while (0)
; #define PG8_MMA(ai, bj, At, Bt) do { __builtin_amdgcn_s_setprio(1); _Pragma("unroll") for (int m = 0; m < 4; ++m) _Pragma("unroll") for (int n = 0; n < 2; ++n) _Pragma("unroll") for (int k = 0; k < 2; ++k) \
;         acc[ai][bj][m][n] = __builtin_amdgcn_mfma_f32_16x16x32_bf16(Bt[n][k], At[m][k], acc[ai][bj][m][n], 0, 0, 0); __builtin_amdgcn_s_setprio(0); } while (0)
; #define PG8_WAIT_V(n) asm volatile("s_waitcnt vmcnt(" #n ")" ::: "memory")
; #define PG8_WAIT_L(n) asm volatile("s_waitcnt lgkmcnt(" #n ")" ::: "memory")
; #define PG8_BAR __builtin_amdgcn_s_barrier()
; #define PG8_SCHED __builtin_amdgcn_sched_barrier(0)
; template <class Epi>
; DI void gemm_phase(LAS unsigned char* lds, const Gemm g, const Epi& E, const int tid) {
;     ...
;         for (int t = 0; t < nt; t += 2) {
;             const bool last = (t == nt - 2);
;             const char* a1 = cA + (size_t)(t + 1) * kstepA;
;             const char* a2 = last ? nA : cA + (size_t)(t + 2) * kstepA; const char* b2 = last ? nB : cB + (size_t)(t + 2) * kstep;
;             const char* a3 = a2 + kstepA; const char* b3 = b2 + kstep;
;             PG8_LDB(B0, 0, 0); PG8_LDB(B1, 0, 1); PG8_SCHED; PG8_LDA(At, 0, 0); PG8_STAGE(PG8_SA(1, 1), a1 + hstepA, voffA);
;             PG8_WAIT_V(8); PG8_WAIT_L(0); PG8_BAR; PG8_MMA(0, 0, At, B0); PG8_MMA(0, 1, At, B1); PG8_BAR; PG8_SCHED;
;             PG8_LDA(At, 0, 1); PG8_STAGE(PG8_SB(0, 0), b2, voffB); PG8_STAGE(PG8_SB(0, 1), b2 + hstepB, voffB); PG8_STAGE(PG8_SA(0, 0), a2, voffA);
;             PG8_WAIT_V(8); PG8_WAIT_L(0); PG8_BAR; PG8_MMA(1, 0, At, B0); PG8_MMA(1, 1, At, B1); PG8_BAR; PG8_SCHED;
.LBB0_115:
	s_add_u32 s12, s48, 0xfffc0080
	s_addc_u32 s50, s49, -1
	s_add_i32 s69, 0, 0x10000
	s_cmp_eq_u32 s68, 12
	s_cselect_b32 s53, s41, s50
	s_cselect_b32 s52, s64, s12
	v_add_u32_e32 v149, s69, v147
	s_cselect_b32 s51, s43, s67
	s_cselect_b32 s50, s65, s66
	s_add_i32 s12, 0, 0x14000
	ds_read_b128 v[142:145], v149
	ds_read_b128 v[150:153], v149 offset:1024
	ds_read_b128 v[154:157], v149 offset:2048
	ds_read_b128 v[158:161], v149 offset:3072
	v_add_u32_e32 v149, s12, v147
	ds_read_b128 v[162:165], v149
	ds_read_b128 v[166:169], v149 offset:1024
	ds_read_b128 v[170:173], v149 offset:2048
	ds_read_b128 v[174:177], v149 offset:3072
	v_lshl_add_u64 v[182:183], s[48:49], 0, v[138:139]
	s_add_i32 m0, s54, 0xc000
	ds_read_b128 v[178:181], v148
	ds_read_b128 v[196:199], v148 offset:1024
	ds_read_b128 v[200:203], v148 offset:2048
	ds_read_b128 v[204:207], v148 offset:3072
	ds_read_b128 v[208:211], v148 offset:4096
	ds_read_b128 v[226:229], v148 offset:5120
	ds_read_b128 v[230:233], v148 offset:6144
	ds_read_b128 v[234:237], v148 offset:7168
	global_load_lds_dwordx4 v[182:183], off
	v_lshl_add_u64 v[182:183], s[48:49], 0, v[140:141]
	s_add_i32 m0, s54, 0xe000
	s_nop 0
	global_load_lds_dwordx4 v[182:183], off
	s_waitcnt vmcnt(8)
	s_waitcnt lgkmcnt(0)
	s_barrier
	s_setprio 1
	s_waitcnt lgkmcnt(0)
	v_mfma_f32_16x16x32_bf16 v[126:129], v[142:145], v[178:181], v[126:129]
	v_mfma_f32_16x16x32_bf16 v[122:125], v[154:157], v[178:181], v[122:125]
	v_mfma_f32_16x16x32_bf16 v[110:113], v[142:145], v[200:203], v[110:113]
	v_mfma_f32_16x16x32_bf16 v[106:109], v[154:157], v[200:203], v[106:109]
	v_mfma_f32_16x16x32_bf16 v[94:97], v[142:145], v[208:211], v[94:97]
	v_mfma_f32_16x16x32_bf16 v[90:93], v[154:157], v[208:211], v[90:93]
	v_mfma_f32_16x16x32_bf16 v[78:81], v[142:145], v[230:233], v[78:81]
	v_mfma_f32_16x16x32_bf16 v[74:77], v[154:157], v[230:233], v[74:77]
	v_mfma_f32_16x16x32_bf16 v[126:129], v[150:153], v[196:199], v[126:129]
	v_mfma_f32_16x16x32_bf16 v[122:125], v[158:161], v[196:199], v[122:125]
	v_mfma_f32_16x16x32_bf16 v[110:113], v[150:153], v[204:207], v[110:113]
	v_mfma_f32_16x16x32_bf16 v[106:109], v[158:161], v[204:207], v[106:109]
	v_mfma_f32_16x16x32_bf16 v[94:97], v[150:153], v[226:229], v[94:97]
	v_mfma_f32_16x16x32_bf16 v[90:93], v[158:161], v[226:229], v[90:93]
	v_mfma_f32_16x16x32_bf16 v[78:81], v[150:153], v[234:237], v[78:81]
	v_mfma_f32_16x16x32_bf16 v[74:77], v[158:161], v[234:237], v[74:77]
	v_mfma_f32_16x16x32_bf16 v[118:121], v[162:165], v[178:181], v[118:121]
	v_mfma_f32_16x16x32_bf16 v[114:117], v[170:173], v[178:181], v[114:117]
	v_mfma_f32_16x16x32_bf16 v[102:105], v[162:165], v[200:203], v[102:105]
	v_mfma_f32_16x16x32_bf16 v[98:101], v[170:173], v[200:203], v[98:101]
	v_mfma_f32_16x16x32_bf16 v[86:89], v[162:165], v[208:211], v[86:89]
	v_mfma_f32_16x16x32_bf16 v[82:85], v[170:173], v[208:211], v[82:85]
	v_mfma_f32_16x16x32_bf16 v[70:73], v[162:165], v[230:233], v[70:73]
	v_mfma_f32_16x16x32_bf16 v[66:69], v[170:173], v[230:233], v[66:69]
	v_mfma_f32_16x16x32_bf16 v[118:121], v[166:169], v[196:199], v[118:121]
	v_mfma_f32_16x16x32_bf16 v[114:117], v[174:177], v[196:199], v[114:117]
	v_mfma_f32_16x16x32_bf16 v[102:105], v[166:169], v[204:207], v[102:105]
	v_mfma_f32_16x16x32_bf16 v[98:101], v[174:177], v[204:207], v[98:101]
	v_mfma_f32_16x16x32_bf16 v[86:89], v[166:169], v[226:229], v[86:89]
	v_mfma_f32_16x16x32_bf16 v[82:85], v[174:177], v[226:229], v[82:85]
	v_mfma_f32_16x16x32_bf16 v[70:73], v[166:169], v[234:237], v[70:73]
	v_mfma_f32_16x16x32_bf16 v[66:69], v[174:177], v[234:237], v[66:69]
	s_setprio 0
	s_barrier
	s_add_i32 s69, s69, s13
	v_lshl_add_u64 v[182:183], s[50:51], 0, v[134:135]
	s_mov_b32 m0, s69
	ds_read_b128 v[178:181], v148 offset:16384
	ds_read_b128 v[196:199], v148 offset:17408
	ds_read_b128 v[200:203], v148 offset:18432
	ds_read_b128 v[204:207], v148 offset:19456
	ds_read_b128 v[208:211], v148 offset:20480
	ds_read_b128 v[226:229], v148 offset:21504
	ds_read_b128 v[230:233], v148 offset:22528
	ds_read_b128 v[234:237], v148 offset:23552
	global_load_lds_dwordx4 v[182:183], off
	s_add_i32 m0, s69, 0x2000
	s_add_u32 s70, s50, 0x40000
	v_lshl_add_u64 v[186:187], s[50:51], 0, v[130:131]
	s_addc_u32 s71, s51, 0
	s_add_i32 s12, s12, s13
	global_load_lds_dwordx4 v[186:187], off
	v_lshl_add_u64 v[188:189], s[70:71], 0, v[134:135]
	s_mov_b32 m0, s12
	v_lshl_add_u64 v[212:213], s[52:53], 0, v[132:133]
	global_load_lds_dwordx4 v[188:189], off
	v_lshl_add_u64 v[188:189], s[70:71], 0, v[130:131]
	s_add_i32 m0, s12, 0x2000
	s_nop 0
	global_load_lds_dwordx4 v[188:189], off
	v_lshl_add_u64 v[188:189], s[52:53], 0, v[136:137]
	s_mov_b32 m0, s54
	s_nop 0
	global_load_lds_dwordx4 v[188:189], off
	s_mov_b32 m0, s55
	s_nop 0
	global_load_lds_dwordx4 v[212:213], off
	s_waitcnt vmcnt(8)
	s_waitcnt lgkmcnt(0)
	s_barrier
; #define PG8_STAGE(bufoff, gbase, voff) do { _Pragma("unroll") for (int _i = 0; _i < 2; ++_i) \
;         __builtin_amdgcn_global_load_lds((const unsigned*)((const char*)(gbase) + (voff)[_i]), (LAS unsigned*)(lds + (bufoff) + ldsw + _i * 8192), 16, 0, 0); } while (0)
; #define PG8_LDA(dst, b, h) do { _Pragma("unroll") for (int m = 0; m < 4; ++m) _Pragma("unroll") for (int k = 0; k < 2; ++k) dst[m][k] = *(const LAS bf16x8*)(lds + PG8_SA(b, h) + aoff + m * 2048 + k * 1024); } while (0)
; #define PG8_LDB(dst, b, h) do { _Pragma("unroll") for (int n = 0; n < 2; ++n) _Pragma("unroll") for (int k = 0; k < 2; ++k) dst[n][k] = *(const LAS bf16x8*)(lds + PG8_SB(b, h) + boff + n * 2048 + k * 1024); } while (0)
; #define PG8_MMA(ai, bj, At, Bt) do { __builtin_amdgcn_s_setprio(1); _Pragma("unroll") for (int m = 0; m < 4; ++m) _Pragma("unroll") for (int n = 0; n < 2; ++n) _Pragma("unroll") for (int k = 0; k < 2; ++k) \
;         acc[ai][bj][m][n] = __builtin_amdgcn_mfma_f32_16x16x32_bf16(Bt[n][k], At[m][k], acc[ai][bj][m][n], 0, 0, 0); __builtin_amdgcn_s_setprio(0); } while (0)
; #define PG8_WAIT_V(n) asm volatile("s_waitcnt vmcnt(" #n ")" ::: "memory")
; #define PG8_WAIT_L(n) asm volatile("s_waitcnt lgkmcnt(" #n ")" ::: "memory")
; #define PG8_BAR __builtin_amdgcn_s_barrier()
; #define PG8_SCHED __builtin_amdgcn_sched_barrier(0)
; template <class Epi>
; DI void gemm_phase(LAS unsigned char* lds, const Gemm g, const Epi& E, const int tid) {
;     ...
;             PG8_WAIT_V(8); PG8_WAIT_L(0); PG8_BAR; PG8_MMA(1, 0, At, B0); PG8_MMA(1, 1, At, B1); PG8_BAR; PG8_SCHED;
;             PG8_LDB(B0, 1, 0); PG8_LDB(B1, 1, 1); PG8_SCHED; PG8_LDA(At, 1, 0); PG8_STAGE(PG8_SA(0, 1), a2 + hstepA, voffA);
;             PG8_WAIT_V(8); PG8_WAIT_L(0); PG8_BAR; PG8_MMA(0, 0, At, B0); PG8_MMA(0, 1, At, B1); PG8_BAR; PG8_SCHED;
;             PG8_LDA(At, 1, 1); PG8_STAGE(PG8_SB(1, 0), b3, voffB); PG8_STAGE(PG8_SB(1, 1), b3 + hstepB, voffB); PG8_STAGE(PG8_SA(1, 0), a3, voffA);
	s_setprio 1
	s_waitcnt lgkmcnt(0)
	v_mfma_f32_16x16x32_bf16 v[62:65], v[142:145], v[178:181], v[62:65]
	v_mfma_f32_16x16x32_bf16 v[58:61], v[154:157], v[178:181], v[58:61]
	v_mfma_f32_16x16x32_bf16 v[46:49], v[142:145], v[200:203], v[46:49]
	v_mfma_f32_16x16x32_bf16 v[42:45], v[154:157], v[200:203], v[42:45]
	v_mfma_f32_16x16x32_bf16 v[30:33], v[142:145], v[208:211], v[30:33]
	v_mfma_f32_16x16x32_bf16 v[26:29], v[154:157], v[208:211], v[26:29]
	v_mfma_f32_16x16x32_bf16 v[14:17], v[142:145], v[230:233], v[14:17]
	v_mfma_f32_16x16x32_bf16 v[10:13], v[154:157], v[230:233], v[10:13]
	v_mfma_f32_16x16x32_bf16 v[62:65], v[150:153], v[196:199], v[62:65]
	v_mfma_f32_16x16x32_bf16 v[58:61], v[158:161], v[196:199], v[58:61]
	v_mfma_f32_16x16x32_bf16 v[46:49], v[150:153], v[204:207], v[46:49]
	v_mfma_f32_16x16x32_bf16 v[42:45], v[158:161], v[204:207], v[42:45]
	v_mfma_f32_16x16x32_bf16 v[30:33], v[150:153], v[226:229], v[30:33]
	v_mfma_f32_16x16x32_bf16 v[26:29], v[158:161], v[226:229], v[26:29]
	v_mfma_f32_16x16x32_bf16 v[14:17], v[150:153], v[234:237], v[14:17]
	v_mfma_f32_16x16x32_bf16 v[10:13], v[158:161], v[234:237], v[10:13]
	v_mfma_f32_16x16x32_bf16 v[54:57], v[162:165], v[178:181], v[54:57]
	v_mfma_f32_16x16x32_bf16 v[50:53], v[170:173], v[178:181], v[50:53]
	v_mfma_f32_16x16x32_bf16 v[38:41], v[162:165], v[200:203], v[38:41]
	v_mfma_f32_16x16x32_bf16 v[34:37], v[170:173], v[200:203], v[34:37]
	v_mfma_f32_16x16x32_bf16 v[22:25], v[162:165], v[208:211], v[22:25]
	v_mfma_f32_16x16x32_bf16 v[18:21], v[170:173], v[208:211], v[18:21]
	v_mfma_f32_16x16x32_bf16 v[6:9], v[162:165], v[230:233], v[6:9]
	v_mfma_f32_16x16x32_bf16 v[2:5], v[170:173], v[230:233], v[2:5]
	v_mfma_f32_16x16x32_bf16 v[54:57], v[166:169], v[196:199], v[54:57]
	v_mfma_f32_16x16x32_bf16 v[50:53], v[174:177], v[196:199], v[50:53]
	v_mfma_f32_16x16x32_bf16 v[38:41], v[166:169], v[204:207], v[38:41]
	v_mfma_f32_16x16x32_bf16 v[34:37], v[174:177], v[204:207], v[34:37]
	v_mfma_f32_16x16x32_bf16 v[22:25], v[166:169], v[226:229], v[22:25]
	v_mfma_f32_16x16x32_bf16 v[18:21], v[174:177], v[226:229], v[18:21]
	v_mfma_f32_16x16x32_bf16 v[6:9], v[166:169], v[234:237], v[6:9]
	v_mfma_f32_16x16x32_bf16 v[2:5], v[174:177], v[234:237], v[2:5]
	s_setprio 0
	s_barrier
	s_add_i32 s12, 0, 0x18000
	v_add_u32_e32 v149, s12, v147
	s_add_i32 s69, 0, 0x1c000
	ds_read_b128 v[142:145], v149
	ds_read_b128 v[150:153], v149 offset:1024
	ds_read_b128 v[154:157], v149 offset:2048
	ds_read_b128 v[158:161], v149 offset:3072
	v_add_u32_e32 v149, s69, v147
	ds_read_b128 v[162:165], v149
	ds_read_b128 v[166:169], v149 offset:1024
	ds_read_b128 v[170:173], v149 offset:2048
	ds_read_b128 v[174:177], v149 offset:3072
	s_add_u32 s52, s52, 0x40000
	s_addc_u32 s53, s53, 0
	s_mov_b32 m0, s56
	v_lshl_add_u64 v[214:215], s[52:53], 0, v[136:137]
	ds_read_b128 v[178:181], v148 offset:32768
	ds_read_b128 v[196:199], v148 offset:33792
	ds_read_b128 v[200:203], v148 offset:34816
	ds_read_b128 v[204:207], v148 offset:35840
	ds_read_b128 v[208:211], v148 offset:36864
	ds_read_b128 v[226:229], v148 offset:37888
	ds_read_b128 v[230:233], v148 offset:38912
	ds_read_b128 v[234:237], v148 offset:39936
	global_load_lds_dwordx4 v[214:215], off
	v_lshl_add_u64 v[214:215], s[52:53], 0, v[132:133]
	s_mov_b32 m0, s57
	s_nop 0
	global_load_lds_dwordx4 v[214:215], off
	s_waitcnt vmcnt(8)
	s_waitcnt lgkmcnt(0)
	s_barrier
	s_setprio 1
	s_waitcnt lgkmcnt(0)
	v_mfma_f32_16x16x32_bf16 v[126:129], v[142:145], v[178:181], v[126:129]
	v_mfma_f32_16x16x32_bf16 v[122:125], v[154:157], v[178:181], v[122:125]
	v_mfma_f32_16x16x32_bf16 v[110:113], v[142:145], v[200:203], v[110:113]
	v_mfma_f32_16x16x32_bf16 v[106:109], v[154:157], v[200:203], v[106:109]
	v_mfma_f32_16x16x32_bf16 v[94:97], v[142:145], v[208:211], v[94:97]
	v_mfma_f32_16x16x32_bf16 v[90:93], v[154:157], v[208:211], v[90:93]
	v_mfma_f32_16x16x32_bf16 v[78:81], v[142:145], v[230:233], v[78:81]
	v_mfma_f32_16x16x32_bf16 v[74:77], v[154:157], v[230:233], v[74:77]
	v_mfma_f32_16x16x32_bf16 v[126:129], v[150:153], v[196:199], v[126:129]
	v_mfma_f32_16x16x32_bf16 v[122:125], v[158:161], v[196:199], v[122:125]
	v_mfma_f32_16x16x32_bf16 v[110:113], v[150:153], v[204:207], v[110:113]
	v_mfma_f32_16x16x32_bf16 v[106:109], v[158:161], v[204:207], v[106:109]
	v_mfma_f32_16x16x32_bf16 v[94:97], v[150:153], v[226:229], v[94:97]
	v_mfma_f32_16x16x32_bf16 v[90:93], v[158:161], v[226:229], v[90:93]
	v_mfma_f32_16x16x32_bf16 v[78:81], v[150:153], v[234:237], v[78:81]
	v_mfma_f32_16x16x32_bf16 v[74:77], v[158:161], v[234:237], v[74:77]
	v_mfma_f32_16x16x32_bf16 v[118:121], v[162:165], v[178:181], v[118:121]
	v_mfma_f32_16x16x32_bf16 v[114:117], v[170:173], v[178:181], v[114:117]
	v_mfma_f32_16x16x32_bf16 v[102:105], v[162:165], v[200:203], v[102:105]
	v_mfma_f32_16x16x32_bf16 v[98:101], v[170:173], v[200:203], v[98:101]
	v_mfma_f32_16x16x32_bf16 v[86:89], v[162:165], v[208:211], v[86:89]
	v_mfma_f32_16x16x32_bf16 v[82:85], v[170:173], v[208:211], v[82:85]
	v_mfma_f32_16x16x32_bf16 v[70:73], v[162:165], v[230:233], v[70:73]
	v_mfma_f32_16x16x32_bf16 v[66:69], v[170:173], v[230:233], v[66:69]
	v_mfma_f32_16x16x32_bf16 v[118:121], v[166:169], v[196:199], v[118:121]
	v_mfma_f32_16x16x32_bf16 v[114:117], v[174:177], v[196:199], v[114:117]
	v_mfma_f32_16x16x32_bf16 v[102:105], v[166:169], v[204:207], v[102:105]
	v_mfma_f32_16x16x32_bf16 v[98:101], v[174:177], v[204:207], v[98:101]
	v_mfma_f32_16x16x32_bf16 v[86:89], v[166:169], v[226:229], v[86:89]
	v_mfma_f32_16x16x32_bf16 v[82:85], v[174:177], v[226:229], v[82:85]
	v_mfma_f32_16x16x32_bf16 v[70:73], v[166:169], v[234:237], v[70:73]
	v_mfma_f32_16x16x32_bf16 v[66:69], v[174:177], v[234:237], v[66:69]
	s_setprio 0
	s_barrier
; #define PG8_STAGE(bufoff, gbase, voff) do { _Pragma("unroll") for (int _i = 0; _i < 2; ++_i) \
;         __builtin_amdgcn_global_load_lds((const unsigned*)((const char*)(gbase) + (voff)[_i]), (LAS unsigned*)(lds + (bufoff) + ldsw + _i * 8192), 16, 0, 0); } while (0)
; #define PG8_LDA(dst, b, h) do { _Pragma("unroll") for (int m = 0; m < 4; ++m) _Pragma("unroll") for (int k = 0; k < 2; ++k) dst[m][k] = *(const LAS bf16x8*)(lds + PG8_SA(b, h) + aoff + m * 2048 + k * 1024); } while (0)
; #define PG8_MMA(ai, bj, At, Bt) do { __builtin_amdgcn_s_setprio(1); _Pragma("unroll") for (int m = 0; m < 4; ++m) _Pragma("unroll") for (int n = 0; n < 2; ++n) _Pragma("unroll") for (int k = 0; k < 2; ++k) \
;         acc[ai][bj][m][n] = __builtin_amdgcn_mfma_f32_16x16x32_bf16(Bt[n][k], At[m][k], acc[ai][bj][m][n], 0, 0, 0); __builtin_amdgcn_s_setprio(0); } while (0)
; #define PG8_WAIT_V(n) asm volatile("s_waitcnt vmcnt(" #n ")" ::: "memory")
; #define PG8_WAIT_L(n) asm volatile("s_waitcnt lgkmcnt(" #n ")" ::: "memory")
; #define PG8_BAR __builtin_amdgcn_s_barrier()
; #define PG8_SCHED __builtin_amdgcn_sched_barrier(0)
; template <class Epi>
; DI void gemm_phase(LAS unsigned char* lds, const Gemm g, const Epi& E, const int tid) {
;     ...
;             PG8_WAIT_V(8); PG8_WAIT_L(0); PG8_BAR; PG8_MMA(0, 0, At, B0); PG8_MMA(0, 1, At, B1); PG8_BAR; PG8_SCHED;
;             PG8_LDA(At, 1, 1); PG8_STAGE(PG8_SB(1, 0), b3, voffB); PG8_STAGE(PG8_SB(1, 1), b3 + hstepB, voffB); PG8_STAGE(PG8_SA(1, 0), a3, voffA);
;             PG8_WAIT_V(8); PG8_WAIT_L(0); PG8_BAR; PG8_MMA(1, 0, At, B0); PG8_MMA(1, 1, At, B1); PG8_BAR; PG8_SCHED;
;         }
;         if (wr == 0) PG8_BAR;
	s_add_i32 s12, s12, s13
	v_lshl_add_u64 v[182:183], v[182:183], 0, s[8:9]
	s_mov_b32 m0, s12
	ds_read_b128 v[178:181], v148 offset:49152
	ds_read_b128 v[196:199], v148 offset:50176
	ds_read_b128 v[200:203], v148 offset:51200
	ds_read_b128 v[204:207], v148 offset:52224
	ds_read_b128 v[208:211], v148 offset:53248
	ds_read_b128 v[226:229], v148 offset:54272
	ds_read_b128 v[230:233], v148 offset:55296
	ds_read_b128 v[234:237], v148 offset:56320
	global_load_lds_dwordx4 v[182:183], off
	s_add_i32 m0, s12, 0x2000
	s_add_u32 s50, s50, 0x40080
	v_lshl_add_u64 v[182:183], v[186:187], 0, s[8:9]
	s_addc_u32 s51, s51, 0
	s_add_i32 s12, s69, s13
	global_load_lds_dwordx4 v[182:183], off
	v_lshl_add_u64 v[182:183], s[50:51], 0, v[134:135]
	s_mov_b32 m0, s12
	s_nop 0
	global_load_lds_dwordx4 v[182:183], off
	v_lshl_add_u64 v[182:183], s[50:51], 0, v[130:131]
	s_add_i32 m0, s12, 0x2000
	s_nop 0
	global_load_lds_dwordx4 v[182:183], off
	v_lshl_add_u64 v[182:183], v[188:189], 0, s[8:9]
	s_mov_b32 m0, s58
	s_nop 0
	global_load_lds_dwordx4 v[182:183], off
	v_lshl_add_u64 v[182:183], v[212:213], 0, s[8:9]
	s_mov_b32 m0, s59
	s_nop 0
	global_load_lds_dwordx4 v[182:183], off
	s_waitcnt vmcnt(8)
	s_waitcnt lgkmcnt(0)
	s_barrier
	s_setprio 1
	s_waitcnt lgkmcnt(0)
	v_mfma_f32_16x16x32_bf16 v[62:65], v[142:145], v[178:181], v[62:65]
	v_mfma_f32_16x16x32_bf16 v[58:61], v[154:157], v[178:181], v[58:61]
	v_mfma_f32_16x16x32_bf16 v[46:49], v[142:145], v[200:203], v[46:49]
	v_mfma_f32_16x16x32_bf16 v[42:45], v[154:157], v[200:203], v[42:45]
	v_mfma_f32_16x16x32_bf16 v[30:33], v[142:145], v[208:211], v[30:33]
	v_mfma_f32_16x16x32_bf16 v[26:29], v[154:157], v[208:211], v[26:29]
	v_mfma_f32_16x16x32_bf16 v[14:17], v[142:145], v[230:233], v[14:17]
	v_mfma_f32_16x16x32_bf16 v[10:13], v[154:157], v[230:233], v[10:13]
	v_mfma_f32_16x16x32_bf16 v[62:65], v[150:153], v[196:199], v[62:65]
	v_mfma_f32_16x16x32_bf16 v[58:61], v[158:161], v[196:199], v[58:61]
	v_mfma_f32_16x16x32_bf16 v[46:49], v[150:153], v[204:207], v[46:49]
	v_mfma_f32_16x16x32_bf16 v[42:45], v[158:161], v[204:207], v[42:45]
	v_mfma_f32_16x16x32_bf16 v[30:33], v[150:153], v[226:229], v[30:33]
	v_mfma_f32_16x16x32_bf16 v[26:29], v[158:161], v[226:229], v[26:29]
	v_mfma_f32_16x16x32_bf16 v[14:17], v[150:153], v[234:237], v[14:17]
	v_mfma_f32_16x16x32_bf16 v[10:13], v[158:161], v[234:237], v[10:13]
	v_mfma_f32_16x16x32_bf16 v[54:57], v[162:165], v[178:181], v[54:57]
	v_mfma_f32_16x16x32_bf16 v[50:53], v[170:173], v[178:181], v[50:53]
	v_mfma_f32_16x16x32_bf16 v[38:41], v[162:165], v[200:203], v[38:41]
	v_mfma_f32_16x16x32_bf16 v[34:37], v[170:173], v[200:203], v[34:37]
	v_mfma_f32_16x16x32_bf16 v[22:25], v[162:165], v[208:211], v[22:25]
	v_mfma_f32_16x16x32_bf16 v[18:21], v[170:173], v[208:211], v[18:21]
	v_mfma_f32_16x16x32_bf16 v[6:9], v[162:165], v[230:233], v[6:9]
	v_mfma_f32_16x16x32_bf16 v[2:5], v[170:173], v[230:233], v[2:5]
	v_mfma_f32_16x16x32_bf16 v[54:57], v[166:169], v[196:199], v[54:57]
	v_mfma_f32_16x16x32_bf16 v[50:53], v[174:177], v[196:199], v[50:53]
	v_mfma_f32_16x16x32_bf16 v[38:41], v[166:169], v[204:207], v[38:41]
	v_mfma_f32_16x16x32_bf16 v[34:37], v[174:177], v[204:207], v[34:37]
	v_mfma_f32_16x16x32_bf16 v[22:25], v[166:169], v[226:229], v[22:25]
	v_mfma_f32_16x16x32_bf16 v[18:21], v[174:177], v[226:229], v[18:21]
	v_mfma_f32_16x16x32_bf16 v[6:9], v[166:169], v[234:237], v[6:9]
	v_mfma_f32_16x16x32_bf16 v[2:5], v[174:177], v[234:237], v[2:5]
	s_setprio 0
	s_barrier
	s_add_i32 s68, s68, 2
	s_add_u32 s48, s48, 0x100
	s_addc_u32 s49, s49, 0
	s_add_u32 s66, s66, 0x100
	s_addc_u32 s67, s67, 0
	s_cmp_gt_u32 s68, 13
	s_cbranch_scc0 .LBB0_115
	s_and_b64 vcc, exec, s[34:35]
	s_cbranch_vccz .LBB0_118
	s_barrier

; #define PG8_STAGE(bufoff, gbase, voff) do { _Pragma("unroll") for (int _i = 0; _i < 2; ++_i) \
;         __builtin_amdgcn_global_load_lds((const unsigned*)((const char*)(gbase) + (voff)[_i]), (LAS unsigned*)(lds + (bufoff) + ldsw + _i * 8192), 16, 0, 0); } while (0)
; #define PG8_LDA(dst, b, h) do { _Pragma("unroll") for (int m = 0; m < 4; ++m) _Pragma("unroll") for (int k = 0; k < 2; ++k) dst[m][k] = *(const LAS bf16x8*)(lds + PG8_SA(b, h) + aoff + m * 2048 + k * 1024); } while (0)
; #define PG8_LDB(dst, b, h) do { _Pragma("unroll") for (int n = 0; n < 2; ++n) _Pragma("unroll") for (int k = 0; k < 2; ++k) dst[n][k] = *(const LAS bf16x8*)(lds + PG8_SB(b, h) + boff + n * 2048 + k * 1024); } while (0)
; #define PG8_MMA(ai, bj, At, Bt) do { __builtin_amdgcn_s_setprio(1); _Pragma("unroll") for (int m = 0; m < 4; ++m) _Pragma("unroll") for (int n = 0; n < 2; ++n) _Pragma("unroll") for (int k = 0; k < 2; ++k) \
;         acc[ai][bj][m][n] = __builtin_amdgcn_mfma_f32_16x16x32_bf16(Bt[n][k], At[m][k], acc[ai][bj][m][n], 0, 0, 0); __builtin_amdgcn_s_setprio(0); } while (0)
; #define PG8_WAIT_V(n) asm volatile("s_waitcnt vmcnt(" #n ")" ::: "memory")
; #define PG8_WAIT_L(n) asm volatile("s_waitcnt lgkmcnt(" #n ")" ::: "memory")
; #define PG8_BAR __builtin_amdgcn_s_barrier()
; #define PG8_SCHED __builtin_amdgcn_sched_barrier(0)
; template <class Epi>
; DI void gemm_phase(LAS unsigned char* lds, const Gemm g, const Epi& E, const int tid) {
;     ...
;         for (int t = 0; t < nt; t += 2) {
;             const bool last = (t == nt - 2);
;             const char* a1 = cA + (size_t)(t + 1) * kstepA;
;             const char* a2 = last ? nA : cA + (size_t)(t + 2) * kstepA; const char* b2 = last ? nB : cB + (size_t)(t + 2) * kstep;
;             const char* a3 = a2 + kstepA; const char* b3 = b2 + kstep;
;             PG8_LDB(B0, 0, 0); PG8_LDB(B1, 0, 1); PG8_SCHED; PG8_LDA(At, 0, 0); PG8_STAGE(PG8_SA(1, 1), a1 + hstepA, voffA);
;             PG8_WAIT_V(8); PG8_WAIT_L(0); PG8_BAR; PG8_MMA(0, 0, At, B0); PG8_MMA(0, 1, At, B1); PG8_BAR; PG8_SCHED;
;             PG8_LDA(At, 0, 1); PG8_STAGE(PG8_SB(0, 0), b2, voffB); PG8_STAGE(PG8_SB(0, 1), b2 + hstepB, voffB); PG8_STAGE(PG8_SA(0, 0), a2, voffA);
;             PG8_WAIT_V(8); PG8_WAIT_L(0); PG8_BAR; PG8_MMA(1, 0, At, B0); PG8_MMA(1, 1, At, B1); PG8_BAR; PG8_SCHED;
.LBB0_150:
	s_add_u32 s12, s48, 0xfffc0080
	s_addc_u32 s50, s49, -1
	s_add_i32 s69, 0, 0x10000
	s_cmp_eq_u32 s68, 12
	s_cselect_b32 s53, s41, s50
	s_cselect_b32 s52, s64, s12
	v_add_u32_e32 v140, s69, v143
	s_cselect_b32 s51, s43, s67
	s_cselect_b32 s50, s65, s66
	s_add_i32 s12, 0, 0x14000
	ds_read_b128 v[136:139], v140
	ds_read_b128 v[146:149], v140 offset:1024
	ds_read_b128 v[150:153], v140 offset:2048
	ds_read_b128 v[154:157], v140 offset:3072
	v_add_u32_e32 v140, s12, v143
	ds_read_b128 v[158:161], v140
	ds_read_b128 v[162:165], v140 offset:1024
	ds_read_b128 v[166:169], v140 offset:2048
	ds_read_b128 v[170:173], v140 offset:3072
	v_lshl_add_u64 v[140:141], s[48:49], 0, v[132:133]
	s_add_i32 m0, s55, 0xc000
	ds_read_b128 v[174:177], v145
	ds_read_b128 v[178:181], v145 offset:1024
	ds_read_b128 v[186:189], v145 offset:2048
	ds_read_b128 v[196:199], v145 offset:3072
	ds_read_b128 v[200:203], v145 offset:4096
	ds_read_b128 v[204:207], v145 offset:5120
	ds_read_b128 v[208:211], v145 offset:6144
	ds_read_b128 v[212:215], v145 offset:7168
	global_load_lds_dwordx4 v[140:141], off
	v_lshl_add_u64 v[140:141], s[48:49], 0, v[134:135]
	s_add_i32 m0, s55, 0xe000
	s_nop 0
	global_load_lds_dwordx4 v[140:141], off
	s_waitcnt vmcnt(8)
	s_waitcnt lgkmcnt(0)
	s_barrier
	s_setprio 1
	s_waitcnt lgkmcnt(0)
	v_mfma_f32_16x16x32_bf16 v[126:129], v[136:139], v[174:177], v[126:129]
	v_mfma_f32_16x16x32_bf16 v[122:125], v[150:153], v[174:177], v[122:125]
	v_mfma_f32_16x16x32_bf16 v[118:121], v[136:139], v[186:189], v[118:121]
	v_mfma_f32_16x16x32_bf16 v[110:113], v[150:153], v[186:189], v[110:113]
	v_mfma_f32_16x16x32_bf16 v[94:97], v[136:139], v[200:203], v[94:97]
	v_mfma_f32_16x16x32_bf16 v[90:93], v[150:153], v[200:203], v[90:93]
	v_mfma_f32_16x16x32_bf16 v[86:89], v[136:139], v[208:211], v[86:89]
	v_mfma_f32_16x16x32_bf16 v[78:81], v[150:153], v[208:211], v[78:81]
	v_mfma_f32_16x16x32_bf16 v[126:129], v[146:149], v[178:181], v[126:129]
	v_mfma_f32_16x16x32_bf16 v[122:125], v[154:157], v[178:181], v[122:125]
	v_mfma_f32_16x16x32_bf16 v[118:121], v[146:149], v[196:199], v[118:121]
	v_mfma_f32_16x16x32_bf16 v[110:113], v[154:157], v[196:199], v[110:113]
	v_mfma_f32_16x16x32_bf16 v[94:97], v[146:149], v[204:207], v[94:97]
	v_mfma_f32_16x16x32_bf16 v[90:93], v[154:157], v[204:207], v[90:93]
	v_mfma_f32_16x16x32_bf16 v[86:89], v[146:149], v[212:215], v[86:89]
	v_mfma_f32_16x16x32_bf16 v[78:81], v[154:157], v[212:215], v[78:81]
	v_mfma_f32_16x16x32_bf16 v[114:117], v[158:161], v[174:177], v[114:117]
	v_mfma_f32_16x16x32_bf16 v[106:109], v[166:169], v[174:177], v[106:109]
	v_mfma_f32_16x16x32_bf16 v[102:105], v[158:161], v[186:189], v[102:105]
	v_mfma_f32_16x16x32_bf16 v[98:101], v[166:169], v[186:189], v[98:101]
	v_mfma_f32_16x16x32_bf16 v[82:85], v[158:161], v[200:203], v[82:85]
	v_mfma_f32_16x16x32_bf16 v[74:77], v[166:169], v[200:203], v[74:77]
	v_mfma_f32_16x16x32_bf16 v[70:73], v[158:161], v[208:211], v[70:73]
	v_mfma_f32_16x16x32_bf16 v[66:69], v[166:169], v[208:211], v[66:69]
	v_mfma_f32_16x16x32_bf16 v[114:117], v[162:165], v[178:181], v[114:117]
	v_mfma_f32_16x16x32_bf16 v[106:109], v[170:173], v[178:181], v[106:109]
	v_mfma_f32_16x16x32_bf16 v[102:105], v[162:165], v[196:199], v[102:105]
	v_mfma_f32_16x16x32_bf16 v[98:101], v[170:173], v[196:199], v[98:101]
	v_mfma_f32_16x16x32_bf16 v[82:85], v[162:165], v[204:207], v[82:85]
	v_mfma_f32_16x16x32_bf16 v[74:77], v[170:173], v[204:207], v[74:77]
	v_mfma_f32_16x16x32_bf16 v[70:73], v[162:165], v[212:215], v[70:73]
	v_mfma_f32_16x16x32_bf16 v[66:69], v[170:173], v[212:215], v[66:69]
	s_setprio 0
	s_barrier
	s_add_i32 s69, s69, s54
	v_lshl_add_u64 v[140:141], s[50:51], 0, v[0:1]
	s_mov_b32 m0, s69
	ds_read_b128 v[174:177], v145 offset:16384
	ds_read_b128 v[178:181], v145 offset:17408
	ds_read_b128 v[186:189], v145 offset:18432
	ds_read_b128 v[196:199], v145 offset:19456
	ds_read_b128 v[200:203], v145 offset:20480
	ds_read_b128 v[204:207], v145 offset:21504
	ds_read_b128 v[208:211], v145 offset:22528
	ds_read_b128 v[212:215], v145 offset:23552
	global_load_lds_dwordx4 v[140:141], off
	s_add_i32 m0, s69, 0x2000
	s_add_u32 s70, s50, 0x40000
	v_lshl_add_u64 v[182:183], s[50:51], 0, v[130:131]
	s_addc_u32 s71, s51, 0
	s_add_i32 s12, s12, s54
	global_load_lds_dwordx4 v[182:183], off
	v_lshl_add_u64 v[192:193], s[70:71], 0, v[0:1]
	s_mov_b32 m0, s12
	v_lshl_add_u64 v[216:217], s[52:53], 0, v[130:131]
	global_load_lds_dwordx4 v[192:193], off
	v_lshl_add_u64 v[192:193], s[70:71], 0, v[130:131]
	s_add_i32 m0, s12, 0x2000
	s_nop 0
	global_load_lds_dwordx4 v[192:193], off
	v_lshl_add_u64 v[192:193], s[52:53], 0, v[0:1]
	s_mov_b32 m0, s55
	s_nop 0
	global_load_lds_dwordx4 v[192:193], off
	s_mov_b32 m0, s56
	s_nop 0
	global_load_lds_dwordx4 v[216:217], off
	s_waitcnt vmcnt(8)
	s_waitcnt lgkmcnt(0)
	s_barrier
; #define PG8_STAGE(bufoff, gbase, voff) do { _Pragma("unroll") for (int _i = 0; _i < 2; ++_i) \
;         __builtin_amdgcn_global_load_lds((const unsigned*)((const char*)(gbase) + (voff)[_i]), (LAS unsigned*)(lds + (bufoff) + ldsw + _i * 8192), 16, 0, 0); } while (0)
; #define PG8_LDA(dst, b, h) do { _Pragma("unroll") for (int m = 0; m < 4; ++m) _Pragma("unroll") for (int k = 0; k < 2; ++k) dst[m][k] = *(const LAS bf16x8*)(lds + PG8_SA(b, h) + aoff + m * 2048 + k * 1024); } while (0)
; #define PG8_LDB(dst, b, h) do { _Pragma("unroll") for (int n = 0; n < 2; ++n) _Pragma("unroll") for (int k = 0; k < 2; ++k) dst[n][k] = *(const LAS bf16x8*)(lds + PG8_SB(b, h) + boff + n * 2048 + k * 1024); } while (0)
; #define PG8_MMA(ai, bj, At, Bt) do { __builtin_amdgcn_s_setprio(1); _Pragma("unroll") for (int m = 0; m < 4; ++m) _Pragma("unroll") for (int n = 0; n < 2; ++n) _Pragma("unroll") for (int k = 0; k < 2; ++k) \
;         acc[ai][bj][m][n] = __builtin_amdgcn_mfma_f32_16x16x32_bf16(Bt[n][k], At[m][k], acc[ai][bj][m][n], 0, 0, 0); __builtin_amdgcn_s_setprio(0); } while (0)
; #define PG8_WAIT_V(n) asm volatile("s_waitcnt vmcnt(" #n ")" ::: "memory")
; #define PG8_WAIT_L(n) asm volatile("s_waitcnt lgkmcnt(" #n ")" ::: "memory")
; #define PG8_BAR __builtin_amdgcn_s_barrier()
; #define PG8_SCHED __builtin_amdgcn_sched_barrier(0)
; template <class Epi>
; DI void gemm_phase(LAS unsigned char* lds, const Gemm g, const Epi& E, const int tid) {
;     ...
;             PG8_WAIT_V(8); PG8_WAIT_L(0); PG8_BAR; PG8_MMA(1, 0, At, B0); PG8_MMA(1, 1, At, B1); PG8_BAR; PG8_SCHED;
;             PG8_LDB(B0, 1, 0); PG8_LDB(B1, 1, 1); PG8_SCHED; PG8_LDA(At, 1, 0); PG8_STAGE(PG8_SA(0, 1), a2 + hstepA, voffA);
;             PG8_WAIT_V(8); PG8_WAIT_L(0); PG8_BAR; PG8_MMA(0, 0, At, B0); PG8_MMA(0, 1, At, B1); PG8_BAR; PG8_SCHED;
;             PG8_LDA(At, 1, 1); PG8_STAGE(PG8_SB(1, 0), b3, voffB); PG8_STAGE(PG8_SB(1, 1), b3 + hstepB, voffB); PG8_STAGE(PG8_SA(1, 0), a3, voffA);
	s_setprio 1
	s_waitcnt lgkmcnt(0)
	v_mfma_f32_16x16x32_bf16 v[62:65], v[136:139], v[174:177], v[62:65]
	v_mfma_f32_16x16x32_bf16 v[58:61], v[150:153], v[174:177], v[58:61]
	v_mfma_f32_16x16x32_bf16 v[54:57], v[136:139], v[186:189], v[54:57]
	v_mfma_f32_16x16x32_bf16 v[46:49], v[150:153], v[186:189], v[46:49]
	v_mfma_f32_16x16x32_bf16 v[34:37], v[136:139], v[200:203], v[34:37]
	v_mfma_f32_16x16x32_bf16 v[26:29], v[150:153], v[200:203], v[26:29]
	v_mfma_f32_16x16x32_bf16 v[22:25], v[136:139], v[208:211], v[22:25]
	v_mfma_f32_16x16x32_bf16 v[14:17], v[150:153], v[208:211], v[14:17]
	v_mfma_f32_16x16x32_bf16 v[62:65], v[146:149], v[178:181], v[62:65]
	v_mfma_f32_16x16x32_bf16 v[58:61], v[154:157], v[178:181], v[58:61]
	v_mfma_f32_16x16x32_bf16 v[54:57], v[146:149], v[196:199], v[54:57]
	v_mfma_f32_16x16x32_bf16 v[46:49], v[154:157], v[196:199], v[46:49]
	v_mfma_f32_16x16x32_bf16 v[34:37], v[146:149], v[204:207], v[34:37]
	v_mfma_f32_16x16x32_bf16 v[26:29], v[154:157], v[204:207], v[26:29]
	v_mfma_f32_16x16x32_bf16 v[22:25], v[146:149], v[212:215], v[22:25]
	v_mfma_f32_16x16x32_bf16 v[14:17], v[154:157], v[212:215], v[14:17]
	v_mfma_f32_16x16x32_bf16 v[50:53], v[158:161], v[174:177], v[50:53]
	v_mfma_f32_16x16x32_bf16 v[42:45], v[166:169], v[174:177], v[42:45]
	v_mfma_f32_16x16x32_bf16 v[38:41], v[158:161], v[186:189], v[38:41]
	v_mfma_f32_16x16x32_bf16 v[30:33], v[166:169], v[186:189], v[30:33]
	v_mfma_f32_16x16x32_bf16 v[18:21], v[158:161], v[200:203], v[18:21]
	v_mfma_f32_16x16x32_bf16 v[10:13], v[166:169], v[200:203], v[10:13]
	v_mfma_f32_16x16x32_bf16 v[6:9], v[158:161], v[208:211], v[6:9]
	v_mfma_f32_16x16x32_bf16 v[2:5], v[166:169], v[208:211], v[2:5]
	v_mfma_f32_16x16x32_bf16 v[50:53], v[162:165], v[178:181], v[50:53]
	v_mfma_f32_16x16x32_bf16 v[42:45], v[170:173], v[178:181], v[42:45]
	v_mfma_f32_16x16x32_bf16 v[38:41], v[162:165], v[196:199], v[38:41]
	v_mfma_f32_16x16x32_bf16 v[30:33], v[170:173], v[196:199], v[30:33]
	v_mfma_f32_16x16x32_bf16 v[18:21], v[162:165], v[204:207], v[18:21]
	v_mfma_f32_16x16x32_bf16 v[10:13], v[170:173], v[204:207], v[10:13]
	v_mfma_f32_16x16x32_bf16 v[6:9], v[162:165], v[212:215], v[6:9]
	v_mfma_f32_16x16x32_bf16 v[2:5], v[170:173], v[212:215], v[2:5]
	s_setprio 0
	s_barrier
	s_add_i32 s12, 0, 0x18000
	s_add_i32 s69, 0, 0x1c000
	v_add_u32_e32 v154, s12, v143
	v_add_u32_e32 v170, s69, v143
	ds_read_b128 v[136:139], v154
	ds_read_b128 v[146:149], v154 offset:1024
	ds_read_b128 v[150:153], v154 offset:2048
	ds_read_b128 v[154:157], v154 offset:3072
	ds_read_b128 v[158:161], v170
	ds_read_b128 v[162:165], v170 offset:1024
	ds_read_b128 v[166:169], v170 offset:2048
	ds_read_b128 v[170:173], v170 offset:3072
	s_add_u32 s52, s52, 0x40000
	s_addc_u32 s53, s53, 0
	s_mov_b32 m0, s57
	v_lshl_add_u64 v[228:229], s[52:53], 0, v[0:1]
	ds_read_b128 v[174:177], v145 offset:32768
	ds_read_b128 v[178:181], v145 offset:33792
	ds_read_b128 v[186:189], v145 offset:34816
	ds_read_b128 v[196:199], v145 offset:35840
	ds_read_b128 v[200:203], v145 offset:36864
	ds_read_b128 v[204:207], v145 offset:37888
	ds_read_b128 v[208:211], v145 offset:38912
	ds_read_b128 v[212:215], v145 offset:39936
	global_load_lds_dwordx4 v[228:229], off
	v_lshl_add_u64 v[228:229], s[52:53], 0, v[130:131]
	s_mov_b32 m0, s58
	s_nop 0
	global_load_lds_dwordx4 v[228:229], off
	s_waitcnt vmcnt(8)
	s_waitcnt lgkmcnt(0)
	s_barrier
	s_setprio 1
	s_waitcnt lgkmcnt(0)
	v_mfma_f32_16x16x32_bf16 v[126:129], v[136:139], v[174:177], v[126:129]
	v_mfma_f32_16x16x32_bf16 v[122:125], v[150:153], v[174:177], v[122:125]
	v_mfma_f32_16x16x32_bf16 v[118:121], v[136:139], v[186:189], v[118:121]
	v_mfma_f32_16x16x32_bf16 v[110:113], v[150:153], v[186:189], v[110:113]
	v_mfma_f32_16x16x32_bf16 v[94:97], v[136:139], v[200:203], v[94:97]
	v_mfma_f32_16x16x32_bf16 v[90:93], v[150:153], v[200:203], v[90:93]
	v_mfma_f32_16x16x32_bf16 v[86:89], v[136:139], v[208:211], v[86:89]
	v_mfma_f32_16x16x32_bf16 v[78:81], v[150:153], v[208:211], v[78:81]
	v_mfma_f32_16x16x32_bf16 v[126:129], v[146:149], v[178:181], v[126:129]
	v_mfma_f32_16x16x32_bf16 v[122:125], v[154:157], v[178:181], v[122:125]
	v_mfma_f32_16x16x32_bf16 v[118:121], v[146:149], v[196:199], v[118:121]
	v_mfma_f32_16x16x32_bf16 v[110:113], v[154:157], v[196:199], v[110:113]
	v_mfma_f32_16x16x32_bf16 v[94:97], v[146:149], v[204:207], v[94:97]
	v_mfma_f32_16x16x32_bf16 v[90:93], v[154:157], v[204:207], v[90:93]
	v_mfma_f32_16x16x32_bf16 v[86:89], v[146:149], v[212:215], v[86:89]
	v_mfma_f32_16x16x32_bf16 v[78:81], v[154:157], v[212:215], v[78:81]
	v_mfma_f32_16x16x32_bf16 v[114:117], v[158:161], v[174:177], v[114:117]
	v_mfma_f32_16x16x32_bf16 v[106:109], v[166:169], v[174:177], v[106:109]
	v_mfma_f32_16x16x32_bf16 v[102:105], v[158:161], v[186:189], v[102:105]
	v_mfma_f32_16x16x32_bf16 v[98:101], v[166:169], v[186:189], v[98:101]
	v_mfma_f32_16x16x32_bf16 v[82:85], v[158:161], v[200:203], v[82:85]
	v_mfma_f32_16x16x32_bf16 v[74:77], v[166:169], v[200:203], v[74:77]
	v_mfma_f32_16x16x32_bf16 v[70:73], v[158:161], v[208:211], v[70:73]
	v_mfma_f32_16x16x32_bf16 v[66:69], v[166:169], v[208:211], v[66:69]
	v_mfma_f32_16x16x32_bf16 v[114:117], v[162:165], v[178:181], v[114:117]
	v_mfma_f32_16x16x32_bf16 v[106:109], v[170:173], v[178:181], v[106:109]
	v_mfma_f32_16x16x32_bf16 v[102:105], v[162:165], v[196:199], v[102:105]
	v_mfma_f32_16x16x32_bf16 v[98:101], v[170:173], v[196:199], v[98:101]
	v_mfma_f32_16x16x32_bf16 v[82:85], v[162:165], v[204:207], v[82:85]
	v_mfma_f32_16x16x32_bf16 v[74:77], v[170:173], v[204:207], v[74:77]
	v_mfma_f32_16x16x32_bf16 v[70:73], v[162:165], v[212:215], v[70:73]
	v_mfma_f32_16x16x32_bf16 v[66:69], v[170:173], v[212:215], v[66:69]
	s_setprio 0
	s_barrier
; #define PG8_STAGE(bufoff, gbase, voff) do { _Pragma("unroll") for (int _i = 0; _i < 2; ++_i) \
;         __builtin_amdgcn_global_load_lds((const unsigned*)((const char*)(gbase) + (voff)[_i]), (LAS unsigned*)(lds + (bufoff) + ldsw + _i * 8192), 16, 0, 0); } while (0)
; #define PG8_LDA(dst, b, h) do { _Pragma("unroll") for (int m = 0; m < 4; ++m) _Pragma("unroll") for (int k = 0; k < 2; ++k) dst[m][k] = *(const LAS bf16x8*)(lds + PG8_SA(b, h) + aoff + m * 2048 + k * 1024); } while (0)
; #define PG8_MMA(ai, bj, At, Bt) do { __builtin_amdgcn_s_setprio(1); _Pragma("unroll") for (int m = 0; m < 4; ++m) _Pragma("unroll") for (int n = 0; n < 2; ++n) _Pragma("unroll") for (int k = 0; k < 2; ++k) \
;         acc[ai][bj][m][n] = __builtin_amdgcn_mfma_f32_16x16x32_bf16(Bt[n][k], At[m][k], acc[ai][bj][m][n], 0, 0, 0); __builtin_amdgcn_s_setprio(0); } while (0)
; #define PG8_WAIT_V(n) asm volatile("s_waitcnt vmcnt(" #n ")" ::: "memory")
; #define PG8_WAIT_L(n) asm volatile("s_waitcnt lgkmcnt(" #n ")" ::: "memory")
; #define PG8_BAR __builtin_amdgcn_s_barrier()
; #define PG8_SCHED __builtin_amdgcn_sched_barrier(0)
; template <class Epi>
; DI void gemm_phase(LAS unsigned char* lds, const Gemm g, const Epi& E, const int tid) {
;     ...
;             PG8_WAIT_V(8); PG8_WAIT_L(0); PG8_BAR; PG8_MMA(0, 0, At, B0); PG8_MMA(0, 1, At, B1); PG8_BAR; PG8_SCHED;
;             PG8_LDA(At, 1, 1); PG8_STAGE(PG8_SB(1, 0), b3, voffB); PG8_STAGE(PG8_SB(1, 1), b3 + hstepB, voffB); PG8_STAGE(PG8_SA(1, 0), a3, voffA);
;             PG8_WAIT_V(8); PG8_WAIT_L(0); PG8_BAR; PG8_MMA(1, 0, At, B0); PG8_MMA(1, 1, At, B1); PG8_BAR; PG8_SCHED;
;         }
;         if (wr == 0) PG8_BAR;
	s_add_i32 s12, s12, s54
	v_lshl_add_u64 v[140:141], v[140:141], 0, s[8:9]
	s_mov_b32 m0, s12
	ds_read_b128 v[174:177], v145 offset:49152
	ds_read_b128 v[178:181], v145 offset:50176
	ds_read_b128 v[186:189], v145 offset:51200
	ds_read_b128 v[196:199], v145 offset:52224
	ds_read_b128 v[200:203], v145 offset:53248
	ds_read_b128 v[204:207], v145 offset:54272
	ds_read_b128 v[208:211], v145 offset:55296
	ds_read_b128 v[212:215], v145 offset:56320
	global_load_lds_dwordx4 v[140:141], off
	s_add_i32 m0, s12, 0x2000
	s_add_u32 s50, s50, 0x40080
	v_lshl_add_u64 v[140:141], v[182:183], 0, s[8:9]
	s_addc_u32 s51, s51, 0
	s_add_i32 s12, s69, s54
	global_load_lds_dwordx4 v[140:141], off
	v_lshl_add_u64 v[140:141], s[50:51], 0, v[0:1]
	s_mov_b32 m0, s12
	s_nop 0
	global_load_lds_dwordx4 v[140:141], off
	v_lshl_add_u64 v[140:141], s[50:51], 0, v[130:131]
	s_add_i32 m0, s12, 0x2000
	s_nop 0
	global_load_lds_dwordx4 v[140:141], off
	v_lshl_add_u64 v[140:141], v[192:193], 0, s[8:9]
	s_mov_b32 m0, s59
	s_nop 0
	global_load_lds_dwordx4 v[140:141], off
	v_lshl_add_u64 v[140:141], v[216:217], 0, s[8:9]
	s_mov_b32 m0, s60
	s_nop 0
	global_load_lds_dwordx4 v[140:141], off
	s_waitcnt vmcnt(8)
	s_waitcnt lgkmcnt(0)
	s_barrier
	s_setprio 1
	s_waitcnt lgkmcnt(0)
	v_mfma_f32_16x16x32_bf16 v[62:65], v[136:139], v[174:177], v[62:65]
	v_mfma_f32_16x16x32_bf16 v[58:61], v[150:153], v[174:177], v[58:61]
	v_mfma_f32_16x16x32_bf16 v[54:57], v[136:139], v[186:189], v[54:57]
	v_mfma_f32_16x16x32_bf16 v[46:49], v[150:153], v[186:189], v[46:49]
	v_mfma_f32_16x16x32_bf16 v[34:37], v[136:139], v[200:203], v[34:37]
	v_mfma_f32_16x16x32_bf16 v[26:29], v[150:153], v[200:203], v[26:29]
	v_mfma_f32_16x16x32_bf16 v[22:25], v[136:139], v[208:211], v[22:25]
	v_mfma_f32_16x16x32_bf16 v[14:17], v[150:153], v[208:211], v[14:17]
	v_mfma_f32_16x16x32_bf16 v[62:65], v[146:149], v[178:181], v[62:65]
	v_mfma_f32_16x16x32_bf16 v[58:61], v[154:157], v[178:181], v[58:61]
	v_mfma_f32_16x16x32_bf16 v[54:57], v[146:149], v[196:199], v[54:57]
	v_mfma_f32_16x16x32_bf16 v[46:49], v[154:157], v[196:199], v[46:49]
	v_mfma_f32_16x16x32_bf16 v[34:37], v[146:149], v[204:207], v[34:37]
	v_mfma_f32_16x16x32_bf16 v[26:29], v[154:157], v[204:207], v[26:29]
	v_mfma_f32_16x16x32_bf16 v[22:25], v[146:149], v[212:215], v[22:25]
	v_mfma_f32_16x16x32_bf16 v[14:17], v[154:157], v[212:215], v[14:17]
	v_mfma_f32_16x16x32_bf16 v[50:53], v[158:161], v[174:177], v[50:53]
	v_mfma_f32_16x16x32_bf16 v[42:45], v[166:169], v[174:177], v[42:45]
	v_mfma_f32_16x16x32_bf16 v[38:41], v[158:161], v[186:189], v[38:41]
	v_mfma_f32_16x16x32_bf16 v[30:33], v[166:169], v[186:189], v[30:33]
	v_mfma_f32_16x16x32_bf16 v[18:21], v[158:161], v[200:203], v[18:21]
	v_mfma_f32_16x16x32_bf16 v[10:13], v[166:169], v[200:203], v[10:13]
	v_mfma_f32_16x16x32_bf16 v[6:9], v[158:161], v[208:211], v[6:9]
	v_mfma_f32_16x16x32_bf16 v[2:5], v[166:169], v[208:211], v[2:5]
	v_mfma_f32_16x16x32_bf16 v[50:53], v[162:165], v[178:181], v[50:53]
	v_mfma_f32_16x16x32_bf16 v[42:45], v[170:173], v[178:181], v[42:45]
	v_mfma_f32_16x16x32_bf16 v[38:41], v[162:165], v[196:199], v[38:41]
	v_mfma_f32_16x16x32_bf16 v[30:33], v[170:173], v[196:199], v[30:33]
	v_mfma_f32_16x16x32_bf16 v[18:21], v[162:165], v[204:207], v[18:21]
	v_mfma_f32_16x16x32_bf16 v[10:13], v[170:173], v[204:207], v[10:13]
	v_mfma_f32_16x16x32_bf16 v[6:9], v[162:165], v[212:215], v[6:9]
	v_mfma_f32_16x16x32_bf16 v[2:5], v[170:173], v[212:215], v[2:5]
	s_setprio 0
	s_barrier
	s_add_i32 s68, s68, 2
	s_add_u32 s48, s48, 0x100
	s_addc_u32 s49, s49, 0
	s_add_u32 s66, s66, 0x100
	s_addc_u32 s67, s67, 0
	s_cmp_gt_u32 s68, 13
	s_cbranch_scc0 .LBB0_150
	s_and_b64 vcc, exec, s[34:35]
	s_cbranch_vccz .LBB0_153
	s_barrier

; #define PG8_STAGE(bufoff, gbase, voff) do { _Pragma("unroll") for (int _i = 0; _i < 2; ++_i) \
;         __builtin_amdgcn_global_load_lds((const unsigned*)((const char*)(gbase) + (voff)[_i]), (LAS unsigned*)(lds + (bufoff) + ldsw + _i * 8192), 16, 0, 0); } while (0)
; #define PG8_LDA(dst, b, h) do { _Pragma("unroll") for (int m = 0; m < 4; ++m) _Pragma("unroll") for (int k = 0; k < 2; ++k) dst[m][k] = *(const LAS bf16x8*)(lds + PG8_SA(b, h) + aoff + m * 2048 + k * 1024); } while (0)
; #define PG8_LDB(dst, b, h) do { _Pragma("unroll") for (int n = 0; n < 2; ++n) _Pragma("unroll") for (int k = 0; k < 2; ++k) dst[n][k] = *(const LAS bf16x8*)(lds + PG8_SB(b, h) + boff + n * 2048 + k * 1024); } while (0)
; #define PG8_MMA(ai, bj, At, Bt) do { __builtin_amdgcn_s_setprio(1); _Pragma("unroll") for (int m = 0; m < 4; ++m) _Pragma("unroll") for (int n = 0; n < 2; ++n) _Pragma("unroll") for (int k = 0; k < 2; ++k) \
;         acc[ai][bj][m][n] = __builtin_amdgcn_mfma_f32_16x16x32_bf16(Bt[n][k], At[m][k], acc[ai][bj][m][n], 0, 0, 0); __builtin_amdgcn_s_setprio(0); } while (0)
; #define PG8_WAIT_V(n) asm volatile("s_waitcnt vmcnt(" #n ")" ::: "memory")
; #define PG8_WAIT_L(n) asm volatile("s_waitcnt lgkmcnt(" #n ")" ::: "memory")
; #define PG8_BAR __builtin_amdgcn_s_barrier()
; #define PG8_SCHED __builtin_amdgcn_sched_barrier(0)
; template <class Epi>
; DI void gemm_phase(LAS unsigned char* lds, const Gemm g, const Epi& E, const int tid) {
;     ...
;         for (int t = 0; t < nt; t += 2) {
;             const bool last = (t == nt - 2);
;             const char* a1 = cA + (size_t)(t + 1) * kstepA;
;             const char* a2 = last ? nA : cA + (size_t)(t + 2) * kstepA; const char* b2 = last ? nB : cB + (size_t)(t + 2) * kstep;
;             const char* a3 = a2 + kstepA; const char* b3 = b2 + kstep;
;             PG8_LDB(B0, 0, 0); PG8_LDB(B1, 0, 1); PG8_SCHED; PG8_LDA(At, 0, 0); PG8_STAGE(PG8_SA(1, 1), a1 + hstepA, voffA);
;             PG8_WAIT_V(8); PG8_WAIT_L(0); PG8_BAR; PG8_MMA(0, 0, At, B0); PG8_MMA(0, 1, At, B1); PG8_BAR; PG8_SCHED;
;             PG8_LDA(At, 0, 1); PG8_STAGE(PG8_SB(0, 0), b2, voffB); PG8_STAGE(PG8_SB(0, 1), b2 + hstepB, voffB); PG8_STAGE(PG8_SA(0, 0), a2, voffA);
;             PG8_WAIT_V(8); PG8_WAIT_L(0); PG8_BAR; PG8_MMA(1, 0, At, B0); PG8_MMA(1, 1, At, B1); PG8_BAR; PG8_SCHED;
.LBB0_172:
	s_add_u32 s12, s44, 0xfffc0080
	s_addc_u32 s46, s45, -1
	s_add_i32 s67, 0, 0x10000
	s_cmp_eq_u32 s66, 12
	s_cselect_b32 s49, s25, s46
	s_cselect_b32 s48, s62, s12
	s_cselect_b32 s47, s35, s65
	s_cselect_b32 s46, s63, s64
	s_add_i32 s12, 0, 0x14000
	v_add_u32_e32 v148, s67, v173
	v_add_u32_e32 v164, s12, v173
	ds_read_b128 v[136:139], v148
	ds_read_b128 v[140:143], v148 offset:1024
	ds_read_b128 v[144:147], v148 offset:2048
	ds_read_b128 v[148:151], v148 offset:3072
	ds_read_b128 v[152:155], v164
	ds_read_b128 v[156:159], v164 offset:1024
	ds_read_b128 v[160:163], v164 offset:2048
	ds_read_b128 v[164:167], v164 offset:3072
	v_lshl_add_u64 v[192:193], s[44:45], 0, v[132:133]
	s_add_i32 m0, s53, 0xc000
	ds_read_b128 v[168:171], v175
	ds_read_b128 v[176:179], v175 offset:1024
	ds_read_b128 v[180:183], v175 offset:2048
	ds_read_b128 v[186:189], v175 offset:3072
	ds_read_b128 v[196:199], v175 offset:4096
	ds_read_b128 v[200:203], v175 offset:5120
	ds_read_b128 v[204:207], v175 offset:6144
	ds_read_b128 v[208:211], v175 offset:7168
	global_load_lds_dwordx4 v[192:193], off
	v_lshl_add_u64 v[192:193], s[44:45], 0, v[134:135]
	s_add_i32 m0, s53, 0xe000
	s_nop 0
	global_load_lds_dwordx4 v[192:193], off
	s_waitcnt vmcnt(8)
	s_waitcnt lgkmcnt(0)
	s_barrier
	s_setprio 1
	s_waitcnt lgkmcnt(0)
	v_mfma_f32_16x16x32_bf16 v[126:129], v[136:139], v[168:171], v[126:129]
	v_mfma_f32_16x16x32_bf16 v[122:125], v[144:147], v[168:171], v[122:125]
	v_mfma_f32_16x16x32_bf16 v[110:113], v[136:139], v[180:183], v[110:113]
	v_mfma_f32_16x16x32_bf16 v[106:109], v[144:147], v[180:183], v[106:109]
	v_mfma_f32_16x16x32_bf16 v[94:97], v[136:139], v[196:199], v[94:97]
	v_mfma_f32_16x16x32_bf16 v[90:93], v[144:147], v[196:199], v[90:93]
	v_mfma_f32_16x16x32_bf16 v[78:81], v[136:139], v[204:207], v[78:81]
	v_mfma_f32_16x16x32_bf16 v[74:77], v[144:147], v[204:207], v[74:77]
	v_mfma_f32_16x16x32_bf16 v[126:129], v[140:143], v[176:179], v[126:129]
	v_mfma_f32_16x16x32_bf16 v[122:125], v[148:151], v[176:179], v[122:125]
	v_mfma_f32_16x16x32_bf16 v[110:113], v[140:143], v[186:189], v[110:113]
	v_mfma_f32_16x16x32_bf16 v[106:109], v[148:151], v[186:189], v[106:109]
	v_mfma_f32_16x16x32_bf16 v[94:97], v[140:143], v[200:203], v[94:97]
	v_mfma_f32_16x16x32_bf16 v[90:93], v[148:151], v[200:203], v[90:93]
	v_mfma_f32_16x16x32_bf16 v[78:81], v[140:143], v[208:211], v[78:81]
	v_mfma_f32_16x16x32_bf16 v[74:77], v[148:151], v[208:211], v[74:77]
	v_mfma_f32_16x16x32_bf16 v[118:121], v[152:155], v[168:171], v[118:121]
	v_mfma_f32_16x16x32_bf16 v[114:117], v[160:163], v[168:171], v[114:117]
	v_mfma_f32_16x16x32_bf16 v[102:105], v[152:155], v[180:183], v[102:105]
	v_mfma_f32_16x16x32_bf16 v[98:101], v[160:163], v[180:183], v[98:101]
	v_mfma_f32_16x16x32_bf16 v[86:89], v[152:155], v[196:199], v[86:89]
	v_mfma_f32_16x16x32_bf16 v[82:85], v[160:163], v[196:199], v[82:85]
	v_mfma_f32_16x16x32_bf16 v[70:73], v[152:155], v[204:207], v[70:73]
	v_mfma_f32_16x16x32_bf16 v[66:69], v[160:163], v[204:207], v[66:69]
	v_mfma_f32_16x16x32_bf16 v[118:121], v[156:159], v[176:179], v[118:121]
	v_mfma_f32_16x16x32_bf16 v[114:117], v[164:167], v[176:179], v[114:117]
	v_mfma_f32_16x16x32_bf16 v[102:105], v[156:159], v[186:189], v[102:105]
	v_mfma_f32_16x16x32_bf16 v[98:101], v[164:167], v[186:189], v[98:101]
	v_mfma_f32_16x16x32_bf16 v[86:89], v[156:159], v[200:203], v[86:89]
	v_mfma_f32_16x16x32_bf16 v[82:85], v[164:167], v[200:203], v[82:85]
	v_mfma_f32_16x16x32_bf16 v[70:73], v[156:159], v[208:211], v[70:73]
	v_mfma_f32_16x16x32_bf16 v[66:69], v[164:167], v[208:211], v[66:69]
	s_setprio 0
	s_barrier
	s_add_i32 s67, s67, s52
	v_lshl_add_u64 v[192:193], s[46:47], 0, v[0:1]
	s_mov_b32 m0, s67
	ds_read_b128 v[168:171], v175 offset:16384
	ds_read_b128 v[176:179], v175 offset:17408
	ds_read_b128 v[180:183], v175 offset:18432
	ds_read_b128 v[186:189], v175 offset:19456
	ds_read_b128 v[196:199], v175 offset:20480
	ds_read_b128 v[200:203], v175 offset:21504
	ds_read_b128 v[204:207], v175 offset:22528
	ds_read_b128 v[208:211], v175 offset:23552
	global_load_lds_dwordx4 v[192:193], off
	s_add_i32 m0, s67, 0x2000
	s_add_u32 s68, s46, 0x40000
	v_lshl_add_u64 v[212:213], s[46:47], 0, v[130:131]
	s_addc_u32 s69, s47, 0
	s_add_i32 s12, s12, s52
	global_load_lds_dwordx4 v[212:213], off
	v_lshl_add_u64 v[214:215], s[68:69], 0, v[0:1]
	s_mov_b32 m0, s12
	v_lshl_add_u64 v[216:217], s[48:49], 0, v[130:131]
	global_load_lds_dwordx4 v[214:215], off
	v_lshl_add_u64 v[214:215], s[68:69], 0, v[130:131]
	s_add_i32 m0, s12, 0x2000
	s_nop 0
	global_load_lds_dwordx4 v[214:215], off
	v_lshl_add_u64 v[214:215], s[48:49], 0, v[0:1]
	s_mov_b32 m0, s53
	s_nop 0
	global_load_lds_dwordx4 v[214:215], off
	s_mov_b32 m0, s54
	s_nop 0
	global_load_lds_dwordx4 v[216:217], off
	s_waitcnt vmcnt(8)
	s_waitcnt lgkmcnt(0)
	s_barrier
; #define PG8_STAGE(bufoff, gbase, voff) do { _Pragma("unroll") for (int _i = 0; _i < 2; ++_i) \
;         __builtin_amdgcn_global_load_lds((const unsigned*)((const char*)(gbase) + (voff)[_i]), (LAS unsigned*)(lds + (bufoff) + ldsw + _i * 8192), 16, 0, 0); } while (0)
; #define PG8_LDA(dst, b, h) do { _Pragma("unroll") for (int m = 0; m < 4; ++m) _Pragma("unroll") for (int k = 0; k < 2; ++k) dst[m][k] = *(const LAS bf16x8*)(lds + PG8_SA(b, h) + aoff + m * 2048 + k * 1024); } while (0)
; #define PG8_LDB(dst, b, h) do { _Pragma("unroll") for (int n = 0; n < 2; ++n) _Pragma("unroll") for (int k = 0; k < 2; ++k) dst[n][k] = *(const LAS bf16x8*)(lds + PG8_SB(b, h) + boff + n * 2048 + k * 1024); } while (0)
; #define PG8_MMA(ai, bj, At, Bt) do { __builtin_amdgcn_s_setprio(1); _Pragma("unroll") for (int m = 0; m < 4; ++m) _Pragma("unroll") for (int n = 0; n < 2; ++n) _Pragma("unroll") for (int k = 0; k < 2; ++k) \
;         acc[ai][bj][m][n] = __builtin_amdgcn_mfma_f32_16x16x32_bf16(Bt[n][k], At[m][k], acc[ai][bj][m][n], 0, 0, 0); __builtin_amdgcn_s_setprio(0); } while (0)
; #define PG8_WAIT_V(n) asm volatile("s_waitcnt vmcnt(" #n ")" ::: "memory")
; #define PG8_WAIT_L(n) asm volatile("s_waitcnt lgkmcnt(" #n ")" ::: "memory")
; #define PG8_BAR __builtin_amdgcn_s_barrier()
; #define PG8_SCHED __builtin_amdgcn_sched_barrier(0)
; template <class Epi>
; DI void gemm_phase(LAS unsigned char* lds, const Gemm g, const Epi& E, const int tid) {
;     ...
;             PG8_WAIT_V(8); PG8_WAIT_L(0); PG8_BAR; PG8_MMA(1, 0, At, B0); PG8_MMA(1, 1, At, B1); PG8_BAR; PG8_SCHED;
;             PG8_LDB(B0, 1, 0); PG8_LDB(B1, 1, 1); PG8_SCHED; PG8_LDA(At, 1, 0); PG8_STAGE(PG8_SA(0, 1), a2 + hstepA, voffA);
;             PG8_WAIT_V(8); PG8_WAIT_L(0); PG8_BAR; PG8_MMA(0, 0, At, B0); PG8_MMA(0, 1, At, B1); PG8_BAR; PG8_SCHED;
;             PG8_LDA(At, 1, 1); PG8_STAGE(PG8_SB(1, 0), b3, voffB); PG8_STAGE(PG8_SB(1, 1), b3 + hstepB, voffB); PG8_STAGE(PG8_SA(1, 0), a3, voffA);
	s_setprio 1
	s_waitcnt lgkmcnt(0)
	v_mfma_f32_16x16x32_bf16 v[62:65], v[136:139], v[168:171], v[62:65]
	v_mfma_f32_16x16x32_bf16 v[58:61], v[144:147], v[168:171], v[58:61]
	v_mfma_f32_16x16x32_bf16 v[46:49], v[136:139], v[180:183], v[46:49]
	v_mfma_f32_16x16x32_bf16 v[42:45], v[144:147], v[180:183], v[42:45]
	v_mfma_f32_16x16x32_bf16 v[30:33], v[136:139], v[196:199], v[30:33]
	v_mfma_f32_16x16x32_bf16 v[26:29], v[144:147], v[196:199], v[26:29]
	v_mfma_f32_16x16x32_bf16 v[14:17], v[136:139], v[204:207], v[14:17]
	v_mfma_f32_16x16x32_bf16 v[10:13], v[144:147], v[204:207], v[10:13]
	v_mfma_f32_16x16x32_bf16 v[62:65], v[140:143], v[176:179], v[62:65]
	v_mfma_f32_16x16x32_bf16 v[58:61], v[148:151], v[176:179], v[58:61]
	v_mfma_f32_16x16x32_bf16 v[46:49], v[140:143], v[186:189], v[46:49]
	v_mfma_f32_16x16x32_bf16 v[42:45], v[148:151], v[186:189], v[42:45]
	v_mfma_f32_16x16x32_bf16 v[30:33], v[140:143], v[200:203], v[30:33]
	v_mfma_f32_16x16x32_bf16 v[26:29], v[148:151], v[200:203], v[26:29]
	v_mfma_f32_16x16x32_bf16 v[14:17], v[140:143], v[208:211], v[14:17]
	v_mfma_f32_16x16x32_bf16 v[10:13], v[148:151], v[208:211], v[10:13]
	v_mfma_f32_16x16x32_bf16 v[54:57], v[152:155], v[168:171], v[54:57]
	v_mfma_f32_16x16x32_bf16 v[50:53], v[160:163], v[168:171], v[50:53]
	v_mfma_f32_16x16x32_bf16 v[38:41], v[152:155], v[180:183], v[38:41]
	v_mfma_f32_16x16x32_bf16 v[34:37], v[160:163], v[180:183], v[34:37]
	v_mfma_f32_16x16x32_bf16 v[22:25], v[152:155], v[196:199], v[22:25]
	v_mfma_f32_16x16x32_bf16 v[18:21], v[160:163], v[196:199], v[18:21]
	v_mfma_f32_16x16x32_bf16 v[6:9], v[152:155], v[204:207], v[6:9]
	v_mfma_f32_16x16x32_bf16 v[2:5], v[160:163], v[204:207], v[2:5]
	v_mfma_f32_16x16x32_bf16 v[54:57], v[156:159], v[176:179], v[54:57]
	v_mfma_f32_16x16x32_bf16 v[50:53], v[164:167], v[176:179], v[50:53]
	v_mfma_f32_16x16x32_bf16 v[38:41], v[156:159], v[186:189], v[38:41]
	v_mfma_f32_16x16x32_bf16 v[34:37], v[164:167], v[186:189], v[34:37]
	v_mfma_f32_16x16x32_bf16 v[22:25], v[156:159], v[200:203], v[22:25]
	v_mfma_f32_16x16x32_bf16 v[18:21], v[164:167], v[200:203], v[18:21]
	v_mfma_f32_16x16x32_bf16 v[6:9], v[156:159], v[208:211], v[6:9]
	v_mfma_f32_16x16x32_bf16 v[2:5], v[164:167], v[208:211], v[2:5]
	s_setprio 0
	s_barrier
	s_add_i32 s12, 0, 0x18000
	s_add_i32 s67, 0, 0x1c000
	v_add_u32_e32 v148, s12, v173
	v_add_u32_e32 v164, s67, v173
	ds_read_b128 v[136:139], v148
	ds_read_b128 v[140:143], v148 offset:1024
	ds_read_b128 v[144:147], v148 offset:2048
	ds_read_b128 v[148:151], v148 offset:3072
	ds_read_b128 v[152:155], v164
	ds_read_b128 v[156:159], v164 offset:1024
	ds_read_b128 v[160:163], v164 offset:2048
	ds_read_b128 v[164:167], v164 offset:3072
	s_add_u32 s48, s48, 0x40000
	s_addc_u32 s49, s49, 0
	s_mov_b32 m0, s55
	v_lshl_add_u64 v[228:229], s[48:49], 0, v[0:1]
	ds_read_b128 v[168:171], v175 offset:32768
	ds_read_b128 v[176:179], v175 offset:33792
	ds_read_b128 v[180:183], v175 offset:34816
	ds_read_b128 v[186:189], v175 offset:35840
	ds_read_b128 v[196:199], v175 offset:36864
	ds_read_b128 v[200:203], v175 offset:37888
	ds_read_b128 v[204:207], v175 offset:38912
	ds_read_b128 v[208:211], v175 offset:39936
	global_load_lds_dwordx4 v[228:229], off
	v_lshl_add_u64 v[228:229], s[48:49], 0, v[130:131]
	s_mov_b32 m0, s56
	s_nop 0
	global_load_lds_dwordx4 v[228:229], off
	s_waitcnt vmcnt(8)
	s_waitcnt lgkmcnt(0)
	s_barrier
	s_setprio 1
	s_waitcnt lgkmcnt(0)
	v_mfma_f32_16x16x32_bf16 v[126:129], v[136:139], v[168:171], v[126:129]
	v_mfma_f32_16x16x32_bf16 v[122:125], v[144:147], v[168:171], v[122:125]
	v_mfma_f32_16x16x32_bf16 v[110:113], v[136:139], v[180:183], v[110:113]
	v_mfma_f32_16x16x32_bf16 v[106:109], v[144:147], v[180:183], v[106:109]
	v_mfma_f32_16x16x32_bf16 v[94:97], v[136:139], v[196:199], v[94:97]
	v_mfma_f32_16x16x32_bf16 v[90:93], v[144:147], v[196:199], v[90:93]
	v_mfma_f32_16x16x32_bf16 v[78:81], v[136:139], v[204:207], v[78:81]
	v_mfma_f32_16x16x32_bf16 v[74:77], v[144:147], v[204:207], v[74:77]
	v_mfma_f32_16x16x32_bf16 v[126:129], v[140:143], v[176:179], v[126:129]
	v_mfma_f32_16x16x32_bf16 v[122:125], v[148:151], v[176:179], v[122:125]
	v_mfma_f32_16x16x32_bf16 v[110:113], v[140:143], v[186:189], v[110:113]
	v_mfma_f32_16x16x32_bf16 v[106:109], v[148:151], v[186:189], v[106:109]
	v_mfma_f32_16x16x32_bf16 v[94:97], v[140:143], v[200:203], v[94:97]
	v_mfma_f32_16x16x32_bf16 v[90:93], v[148:151], v[200:203], v[90:93]
	v_mfma_f32_16x16x32_bf16 v[78:81], v[140:143], v[208:211], v[78:81]
	v_mfma_f32_16x16x32_bf16 v[74:77], v[148:151], v[208:211], v[74:77]
	v_mfma_f32_16x16x32_bf16 v[118:121], v[152:155], v[168:171], v[118:121]
	v_mfma_f32_16x16x32_bf16 v[114:117], v[160:163], v[168:171], v[114:117]
	v_mfma_f32_16x16x32_bf16 v[102:105], v[152:155], v[180:183], v[102:105]
	v_mfma_f32_16x16x32_bf16 v[98:101], v[160:163], v[180:183], v[98:101]
	v_mfma_f32_16x16x32_bf16 v[86:89], v[152:155], v[196:199], v[86:89]
	v_mfma_f32_16x16x32_bf16 v[82:85], v[160:163], v[196:199], v[82:85]
	v_mfma_f32_16x16x32_bf16 v[70:73], v[152:155], v[204:207], v[70:73]
	v_mfma_f32_16x16x32_bf16 v[66:69], v[160:163], v[204:207], v[66:69]
	v_mfma_f32_16x16x32_bf16 v[118:121], v[156:159], v[176:179], v[118:121]
	v_mfma_f32_16x16x32_bf16 v[114:117], v[164:167], v[176:179], v[114:117]
	v_mfma_f32_16x16x32_bf16 v[102:105], v[156:159], v[186:189], v[102:105]
	v_mfma_f32_16x16x32_bf16 v[98:101], v[164:167], v[186:189], v[98:101]
	v_mfma_f32_16x16x32_bf16 v[86:89], v[156:159], v[200:203], v[86:89]
	v_mfma_f32_16x16x32_bf16 v[82:85], v[164:167], v[200:203], v[82:85]
	v_mfma_f32_16x16x32_bf16 v[70:73], v[156:159], v[208:211], v[70:73]
	v_mfma_f32_16x16x32_bf16 v[66:69], v[164:167], v[208:211], v[66:69]
	s_setprio 0
	s_barrier
; #define PG8_STAGE(bufoff, gbase, voff) do { _Pragma("unroll") for (int _i = 0; _i < 2; ++_i) \
;         __builtin_amdgcn_global_load_lds((const unsigned*)((const char*)(gbase) + (voff)[_i]), (LAS unsigned*)(lds + (bufoff) + ldsw + _i * 8192), 16, 0, 0); } while (0)
; #define PG8_LDA(dst, b, h) do { _Pragma("unroll") for (int m = 0; m < 4; ++m) _Pragma("unroll") for (int k = 0; k < 2; ++k) dst[m][k] = *(const LAS bf16x8*)(lds + PG8_SA(b, h) + aoff + m * 2048 + k * 1024); } while (0)
; #define PG8_MMA(ai, bj, At, Bt) do { __builtin_amdgcn_s_setprio(1); _Pragma("unroll") for (int m = 0; m < 4; ++m) _Pragma("unroll") for (int n = 0; n < 2; ++n) _Pragma("unroll") for (int k = 0; k < 2; ++k) \
;         acc[ai][bj][m][n] = __builtin_amdgcn_mfma_f32_16x16x32_bf16(Bt[n][k], At[m][k], acc[ai][bj][m][n], 0, 0, 0); __builtin_amdgcn_s_setprio(0); } while (0)
; #define PG8_WAIT_V(n) asm volatile("s_waitcnt vmcnt(" #n ")" ::: "memory")
; #define PG8_WAIT_L(n) asm volatile("s_waitcnt lgkmcnt(" #n ")" ::: "memory")
; #define PG8_BAR __builtin_amdgcn_s_barrier()
; #define PG8_SCHED __builtin_amdgcn_sched_barrier(0)
; template <class Epi>
; DI void gemm_phase(LAS unsigned char* lds, const Gemm g, const Epi& E, const int tid) {
;     ...
;             PG8_WAIT_V(8); PG8_WAIT_L(0); PG8_BAR; PG8_MMA(0, 0, At, B0); PG8_MMA(0, 1, At, B1); PG8_BAR; PG8_SCHED;
;             PG8_LDA(At, 1, 1); PG8_STAGE(PG8_SB(1, 0), b3, voffB); PG8_STAGE(PG8_SB(1, 1), b3 + hstepB, voffB); PG8_STAGE(PG8_SA(1, 0), a3, voffA);
;             PG8_WAIT_V(8); PG8_WAIT_L(0); PG8_BAR; PG8_MMA(1, 0, At, B0); PG8_MMA(1, 1, At, B1); PG8_BAR; PG8_SCHED;
;         }
;         if (wr == 0) PG8_BAR;
	s_add_i32 s12, s12, s52
	v_lshl_add_u64 v[192:193], v[192:193], 0, s[8:9]
	s_mov_b32 m0, s12
	ds_read_b128 v[168:171], v175 offset:49152
	ds_read_b128 v[176:179], v175 offset:50176
	ds_read_b128 v[180:183], v175 offset:51200
	ds_read_b128 v[186:189], v175 offset:52224
	ds_read_b128 v[196:199], v175 offset:53248
	ds_read_b128 v[200:203], v175 offset:54272
	ds_read_b128 v[204:207], v175 offset:55296
	ds_read_b128 v[208:211], v175 offset:56320
	global_load_lds_dwordx4 v[192:193], off
	s_add_i32 m0, s12, 0x2000
	s_add_u32 s46, s46, 0x40080
	v_lshl_add_u64 v[192:193], v[212:213], 0, s[8:9]
	s_addc_u32 s47, s47, 0
	s_add_i32 s12, s67, s52
	global_load_lds_dwordx4 v[192:193], off
	v_lshl_add_u64 v[192:193], s[46:47], 0, v[0:1]
	s_mov_b32 m0, s12
	s_nop 0
	global_load_lds_dwordx4 v[192:193], off
	v_lshl_add_u64 v[192:193], s[46:47], 0, v[130:131]
	s_add_i32 m0, s12, 0x2000
	s_nop 0
	global_load_lds_dwordx4 v[192:193], off
	v_lshl_add_u64 v[192:193], v[214:215], 0, s[8:9]
	s_mov_b32 m0, s57
	s_nop 0
	global_load_lds_dwordx4 v[192:193], off
	v_lshl_add_u64 v[192:193], v[216:217], 0, s[8:9]
	s_mov_b32 m0, s58
	s_nop 0
	global_load_lds_dwordx4 v[192:193], off
	s_waitcnt vmcnt(8)
	s_waitcnt lgkmcnt(0)
	s_barrier
	s_setprio 1
	s_waitcnt lgkmcnt(0)
	v_mfma_f32_16x16x32_bf16 v[62:65], v[136:139], v[168:171], v[62:65]
	v_mfma_f32_16x16x32_bf16 v[58:61], v[144:147], v[168:171], v[58:61]
	v_mfma_f32_16x16x32_bf16 v[46:49], v[136:139], v[180:183], v[46:49]
	v_mfma_f32_16x16x32_bf16 v[42:45], v[144:147], v[180:183], v[42:45]
	v_mfma_f32_16x16x32_bf16 v[30:33], v[136:139], v[196:199], v[30:33]
	v_mfma_f32_16x16x32_bf16 v[26:29], v[144:147], v[196:199], v[26:29]
	v_mfma_f32_16x16x32_bf16 v[14:17], v[136:139], v[204:207], v[14:17]
	v_mfma_f32_16x16x32_bf16 v[10:13], v[144:147], v[204:207], v[10:13]
	v_mfma_f32_16x16x32_bf16 v[62:65], v[140:143], v[176:179], v[62:65]
	v_mfma_f32_16x16x32_bf16 v[58:61], v[148:151], v[176:179], v[58:61]
	v_mfma_f32_16x16x32_bf16 v[46:49], v[140:143], v[186:189], v[46:49]
	v_mfma_f32_16x16x32_bf16 v[42:45], v[148:151], v[186:189], v[42:45]
	v_mfma_f32_16x16x32_bf16 v[30:33], v[140:143], v[200:203], v[30:33]
	v_mfma_f32_16x16x32_bf16 v[26:29], v[148:151], v[200:203], v[26:29]
	v_mfma_f32_16x16x32_bf16 v[14:17], v[140:143], v[208:211], v[14:17]
	v_mfma_f32_16x16x32_bf16 v[10:13], v[148:151], v[208:211], v[10:13]
	v_mfma_f32_16x16x32_bf16 v[54:57], v[152:155], v[168:171], v[54:57]
	v_mfma_f32_16x16x32_bf16 v[50:53], v[160:163], v[168:171], v[50:53]
	v_mfma_f32_16x16x32_bf16 v[38:41], v[152:155], v[180:183], v[38:41]
	v_mfma_f32_16x16x32_bf16 v[34:37], v[160:163], v[180:183], v[34:37]
	v_mfma_f32_16x16x32_bf16 v[22:25], v[152:155], v[196:199], v[22:25]
	v_mfma_f32_16x16x32_bf16 v[18:21], v[160:163], v[196:199], v[18:21]
	v_mfma_f32_16x16x32_bf16 v[6:9], v[152:155], v[204:207], v[6:9]
	v_mfma_f32_16x16x32_bf16 v[2:5], v[160:163], v[204:207], v[2:5]
	v_mfma_f32_16x16x32_bf16 v[54:57], v[156:159], v[176:179], v[54:57]
	v_mfma_f32_16x16x32_bf16 v[50:53], v[164:167], v[176:179], v[50:53]
	v_mfma_f32_16x16x32_bf16 v[38:41], v[156:159], v[186:189], v[38:41]
	v_mfma_f32_16x16x32_bf16 v[34:37], v[164:167], v[186:189], v[34:37]
	v_mfma_f32_16x16x32_bf16 v[22:25], v[156:159], v[200:203], v[22:25]
	v_mfma_f32_16x16x32_bf16 v[18:21], v[164:167], v[200:203], v[18:21]
	v_mfma_f32_16x16x32_bf16 v[6:9], v[156:159], v[208:211], v[6:9]
	v_mfma_f32_16x16x32_bf16 v[2:5], v[164:167], v[208:211], v[2:5]
	s_setprio 0
	s_barrier
	s_add_i32 s66, s66, 2
	s_add_u32 s44, s44, 0x100
	s_addc_u32 s45, s45, 0
	s_add_u32 s64, s64, 0x100
	s_addc_u32 s65, s65, 0
	s_cmp_gt_u32 s66, 13
	s_cbranch_scc0 .LBB0_172
	s_and_b64 vcc, exec, s[14:15]
	s_cbranch_vccz .LBB0_175
	s_barrier

; #define PG8_STAGE(bufoff, gbase, voff) do { _Pragma("unroll") for (int _i = 0; _i < 2; ++_i) \
;         __builtin_amdgcn_global_load_lds((const unsigned*)((const char*)(gbase) + (voff)[_i]), (LAS unsigned*)(lds + (bufoff) + ldsw + _i * 8192), 16, 0, 0); } while (0)
; #define PG8_LDA(dst, b, h) do { _Pragma("unroll") for (int m = 0; m < 4; ++m) _Pragma("unroll") for (int k = 0; k < 2; ++k) dst[m][k] = *(const LAS bf16x8*)(lds + PG8_SA(b, h) + aoff + m * 2048 + k * 1024); } while (0)
; #define PG8_LDB(dst, b, h) do { _Pragma("unroll") for (int n = 0; n < 2; ++n) _Pragma("unroll") for (int k = 0; k < 2; ++k) dst[n][k] = *(const LAS bf16x8*)(lds + PG8_SB(b, h) + boff + n * 2048 + k * 1024); } while (0)
; #define PG8_MMA(ai, bj, At, Bt) do { __builtin_amdgcn_s_setprio(1); _Pragma("unroll") for (int m = 0; m < 4; ++m) _Pragma("unroll") for (int n = 0; n < 2; ++n) _Pragma("unroll") for (int k = 0; k < 2; ++k) \
;         acc[ai][bj][m][n] = __builtin_amdgcn_mfma_f32_16x16x32_bf16(Bt[n][k], At[m][k], acc[ai][bj][m][n], 0, 0, 0); __builtin_amdgcn_s_setprio(0); } while (0)
; #define PG8_WAIT_V(n) asm volatile("s_waitcnt vmcnt(" #n ")" ::: "memory")
; #define PG8_WAIT_L(n) asm volatile("s_waitcnt lgkmcnt(" #n ")" ::: "memory")
; #define PG8_BAR __builtin_amdgcn_s_barrier()
; #define PG8_SCHED __builtin_amdgcn_sched_barrier(0)
; template <class Epi>
; DI void gemm_phase(LAS unsigned char* lds, const Gemm g, const Epi& E, const int tid) {
;     ...
;         for (int t = 0; t < nt; t += 2) {
;             const bool last = (t == nt - 2);
;             const char* a1 = cA + (size_t)(t + 1) * kstepA;
;             const char* a2 = last ? nA : cA + (size_t)(t + 2) * kstepA; const char* b2 = last ? nB : cB + (size_t)(t + 2) * kstep;
;             const char* a3 = a2 + kstepA; const char* b3 = b2 + kstep;
;             PG8_LDB(B0, 0, 0); PG8_LDB(B1, 0, 1); PG8_SCHED; PG8_LDA(At, 0, 0); PG8_STAGE(PG8_SA(1, 1), a1 + hstepA, voffA);
;             PG8_WAIT_V(8); PG8_WAIT_L(0); PG8_BAR; PG8_MMA(0, 0, At, B0); PG8_MMA(0, 1, At, B1); PG8_BAR; PG8_SCHED;
;             PG8_LDA(At, 0, 1); PG8_STAGE(PG8_SB(0, 0), b2, voffB); PG8_STAGE(PG8_SB(0, 1), b2 + hstepB, voffB); PG8_STAGE(PG8_SA(0, 0), a2, voffA);
;             PG8_WAIT_V(8); PG8_WAIT_L(0); PG8_BAR; PG8_MMA(1, 0, At, B0); PG8_MMA(1, 1, At, B1); PG8_BAR; PG8_SCHED;
.LBB0_195:
	s_add_u32 s12, s46, 0xfff80080
	s_addc_u32 s48, s47, -1
	s_add_i32 s66, 0, 0x10000
	s_cmp_eq_u32 s65, 4
	s_cselect_b32 s51, s35, s48
	s_cselect_b32 s50, s62, s12
	s_cselect_b32 s49, s25, s64
	s_cselect_b32 s48, s41, s63
	s_add_i32 s12, 0, 0x14000
	v_add_u32_e32 v156, s66, v141
	v_add_u32_e32 v172, s12, v141
	ds_read_b128 v[144:147], v156
	ds_read_b128 v[148:151], v156 offset:1024
	ds_read_b128 v[152:155], v156 offset:2048
	ds_read_b128 v[156:159], v156 offset:3072
	ds_read_b128 v[160:163], v172
	ds_read_b128 v[164:167], v172 offset:1024
	ds_read_b128 v[168:171], v172 offset:2048
	ds_read_b128 v[172:175], v172 offset:3072
	v_lshl_add_u64 v[192:193], s[46:47], 0, v[136:137]
	s_add_i32 m0, s52, 0xc000
	ds_read_b128 v[176:179], v143
	ds_read_b128 v[180:183], v143 offset:1024
	ds_read_b128 v[186:189], v143 offset:2048
	ds_read_b128 v[196:199], v143 offset:3072
	ds_read_b128 v[200:203], v143 offset:4096
	ds_read_b128 v[204:207], v143 offset:5120
	ds_read_b128 v[208:211], v143 offset:6144
	ds_read_b128 v[212:215], v143 offset:7168
	global_load_lds_dwordx4 v[192:193], off
	v_lshl_add_u64 v[192:193], s[46:47], 0, v[138:139]
	s_add_i32 m0, s52, 0xe000
	s_nop 0
	global_load_lds_dwordx4 v[192:193], off
	s_waitcnt vmcnt(8)
	s_waitcnt lgkmcnt(0)
	s_barrier
	s_setprio 1
	s_waitcnt lgkmcnt(0)
	v_mfma_f32_16x16x32_bf16 v[126:129], v[144:147], v[176:179], v[126:129]
	v_mfma_f32_16x16x32_bf16 v[122:125], v[152:155], v[176:179], v[122:125]
	v_mfma_f32_16x16x32_bf16 v[118:121], v[144:147], v[186:189], v[118:121]
	v_mfma_f32_16x16x32_bf16 v[114:117], v[152:155], v[186:189], v[114:117]
	v_mfma_f32_16x16x32_bf16 v[102:105], v[144:147], v[200:203], v[102:105]
	v_mfma_f32_16x16x32_bf16 v[98:101], v[152:155], v[200:203], v[98:101]
	v_mfma_f32_16x16x32_bf16 v[86:89], v[144:147], v[208:211], v[86:89]
	v_mfma_f32_16x16x32_bf16 v[82:85], v[152:155], v[208:211], v[82:85]
	v_mfma_f32_16x16x32_bf16 v[126:129], v[148:151], v[180:183], v[126:129]
	v_mfma_f32_16x16x32_bf16 v[122:125], v[156:159], v[180:183], v[122:125]
	v_mfma_f32_16x16x32_bf16 v[118:121], v[148:151], v[196:199], v[118:121]
	v_mfma_f32_16x16x32_bf16 v[114:117], v[156:159], v[196:199], v[114:117]
	v_mfma_f32_16x16x32_bf16 v[102:105], v[148:151], v[204:207], v[102:105]
	v_mfma_f32_16x16x32_bf16 v[98:101], v[156:159], v[204:207], v[98:101]
	v_mfma_f32_16x16x32_bf16 v[86:89], v[148:151], v[212:215], v[86:89]
	v_mfma_f32_16x16x32_bf16 v[82:85], v[156:159], v[212:215], v[82:85]
	v_mfma_f32_16x16x32_bf16 v[110:113], v[160:163], v[176:179], v[110:113]
	v_mfma_f32_16x16x32_bf16 v[106:109], v[168:171], v[176:179], v[106:109]
	v_mfma_f32_16x16x32_bf16 v[94:97], v[160:163], v[186:189], v[94:97]
	v_mfma_f32_16x16x32_bf16 v[90:93], v[168:171], v[186:189], v[90:93]
	v_mfma_f32_16x16x32_bf16 v[78:81], v[160:163], v[200:203], v[78:81]
	v_mfma_f32_16x16x32_bf16 v[74:77], v[168:171], v[200:203], v[74:77]
	v_mfma_f32_16x16x32_bf16 v[70:73], v[160:163], v[208:211], v[70:73]
	v_mfma_f32_16x16x32_bf16 v[66:69], v[168:171], v[208:211], v[66:69]
	v_mfma_f32_16x16x32_bf16 v[110:113], v[164:167], v[180:183], v[110:113]
	v_mfma_f32_16x16x32_bf16 v[106:109], v[172:175], v[180:183], v[106:109]
	v_mfma_f32_16x16x32_bf16 v[94:97], v[164:167], v[196:199], v[94:97]
	v_mfma_f32_16x16x32_bf16 v[90:93], v[172:175], v[196:199], v[90:93]
	v_mfma_f32_16x16x32_bf16 v[78:81], v[164:167], v[204:207], v[78:81]
	v_mfma_f32_16x16x32_bf16 v[74:77], v[172:175], v[204:207], v[74:77]
	v_mfma_f32_16x16x32_bf16 v[70:73], v[164:167], v[212:215], v[70:73]
	v_mfma_f32_16x16x32_bf16 v[66:69], v[172:175], v[212:215], v[66:69]
	s_setprio 0
	s_barrier
	s_add_i32 s66, s66, s4
	v_lshl_add_u64 v[192:193], s[48:49], 0, v[0:1]
	s_mov_b32 m0, s66
	ds_read_b128 v[176:179], v143 offset:16384
	ds_read_b128 v[180:183], v143 offset:17408
	ds_read_b128 v[186:189], v143 offset:18432
	ds_read_b128 v[196:199], v143 offset:19456
	ds_read_b128 v[200:203], v143 offset:20480
	ds_read_b128 v[204:207], v143 offset:21504
	ds_read_b128 v[208:211], v143 offset:22528
	ds_read_b128 v[212:215], v143 offset:23552
	global_load_lds_dwordx4 v[192:193], off
	s_add_i32 m0, s66, 0x2000
	s_add_u32 s66, s48, 0x20000
	v_lshl_add_u64 v[216:217], s[48:49], 0, v[130:131]
	s_addc_u32 s67, s49, 0
	s_add_i32 s12, s12, s4
	global_load_lds_dwordx4 v[216:217], off
	v_lshl_add_u64 v[228:229], s[66:67], 0, v[0:1]
	s_mov_b32 m0, s12
	v_lshl_add_u64 v[230:231], s[50:51], 0, v[132:133]
	global_load_lds_dwordx4 v[228:229], off
	v_lshl_add_u64 v[228:229], s[66:67], 0, v[130:131]
	s_add_i32 m0, s12, 0x2000
	s_nop 0
	global_load_lds_dwordx4 v[228:229], off
	v_lshl_add_u64 v[228:229], s[50:51], 0, v[134:135]
	s_mov_b32 m0, s52
	s_nop 0
	global_load_lds_dwordx4 v[228:229], off
	s_mov_b32 m0, s53
	s_nop 0
	global_load_lds_dwordx4 v[230:231], off
	s_waitcnt vmcnt(8)
	s_waitcnt lgkmcnt(0)
	s_barrier
; #define PG8_STAGE(bufoff, gbase, voff) do { _Pragma("unroll") for (int _i = 0; _i < 2; ++_i) \
;         __builtin_amdgcn_global_load_lds((const unsigned*)((const char*)(gbase) + (voff)[_i]), (LAS unsigned*)(lds + (bufoff) + ldsw + _i * 8192), 16, 0, 0); } while (0)
; #define PG8_LDA(dst, b, h) do { _Pragma("unroll") for (int m = 0; m < 4; ++m) _Pragma("unroll") for (int k = 0; k < 2; ++k) dst[m][k] = *(const LAS bf16x8*)(lds + PG8_SA(b, h) + aoff + m * 2048 + k * 1024); } while (0)
; #define PG8_LDB(dst, b, h) do { _Pragma("unroll") for (int n = 0; n < 2; ++n) _Pragma("unroll") for (int k = 0; k < 2; ++k) dst[n][k] = *(const LAS bf16x8*)(lds + PG8_SB(b, h) + boff + n * 2048 + k * 1024); } while (0)
; #define PG8_MMA(ai, bj, At, Bt) do { __builtin_amdgcn_s_setprio(1); _Pragma("unroll") for (int m = 0; m < 4; ++m) _Pragma("unroll") for (int n = 0; n < 2; ++n) _Pragma("unroll") for (int k = 0; k < 2; ++k) \
;         acc[ai][bj][m][n] = __builtin_amdgcn_mfma_f32_16x16x32_bf16(Bt[n][k], At[m][k], acc[ai][bj][m][n], 0, 0, 0); __builtin_amdgcn_s_setprio(0); } while (0)
; #define PG8_WAIT_V(n) asm volatile("s_waitcnt vmcnt(" #n ")" ::: "memory")
; #define PG8_WAIT_L(n) asm volatile("s_waitcnt lgkmcnt(" #n ")" ::: "memory")
; #define PG8_BAR __builtin_amdgcn_s_barrier()
; #define PG8_SCHED __builtin_amdgcn_sched_barrier(0)
; template <class Epi>
; DI void gemm_phase(LAS unsigned char* lds, const Gemm g, const Epi& E, const int tid) {
;     ...
;             PG8_WAIT_V(8); PG8_WAIT_L(0); PG8_BAR; PG8_MMA(1, 0, At, B0); PG8_MMA(1, 1, At, B1); PG8_BAR; PG8_SCHED;
;             PG8_LDB(B0, 1, 0); PG8_LDB(B1, 1, 1); PG8_SCHED; PG8_LDA(At, 1, 0); PG8_STAGE(PG8_SA(0, 1), a2 + hstepA, voffA);
;             PG8_WAIT_V(8); PG8_WAIT_L(0); PG8_BAR; PG8_MMA(0, 0, At, B0); PG8_MMA(0, 1, At, B1); PG8_BAR; PG8_SCHED;
;             PG8_LDA(At, 1, 1); PG8_STAGE(PG8_SB(1, 0), b3, voffB); PG8_STAGE(PG8_SB(1, 1), b3 + hstepB, voffB); PG8_STAGE(PG8_SA(1, 0), a3, voffA);
	s_setprio 1
	s_waitcnt lgkmcnt(0)
	v_mfma_f32_16x16x32_bf16 v[62:65], v[144:147], v[176:179], v[62:65]
	v_mfma_f32_16x16x32_bf16 v[58:61], v[152:155], v[176:179], v[58:61]
	v_mfma_f32_16x16x32_bf16 v[54:57], v[144:147], v[186:189], v[54:57]
	v_mfma_f32_16x16x32_bf16 v[50:53], v[152:155], v[186:189], v[50:53]
	v_mfma_f32_16x16x32_bf16 v[38:41], v[144:147], v[200:203], v[38:41]
	v_mfma_f32_16x16x32_bf16 v[34:37], v[152:155], v[200:203], v[34:37]
	v_mfma_f32_16x16x32_bf16 v[22:25], v[144:147], v[208:211], v[22:25]
	v_mfma_f32_16x16x32_bf16 v[18:21], v[152:155], v[208:211], v[18:21]
	v_mfma_f32_16x16x32_bf16 v[62:65], v[148:151], v[180:183], v[62:65]
	v_mfma_f32_16x16x32_bf16 v[58:61], v[156:159], v[180:183], v[58:61]
	v_mfma_f32_16x16x32_bf16 v[54:57], v[148:151], v[196:199], v[54:57]
	v_mfma_f32_16x16x32_bf16 v[50:53], v[156:159], v[196:199], v[50:53]
	v_mfma_f32_16x16x32_bf16 v[38:41], v[148:151], v[204:207], v[38:41]
	v_mfma_f32_16x16x32_bf16 v[34:37], v[156:159], v[204:207], v[34:37]
	v_mfma_f32_16x16x32_bf16 v[22:25], v[148:151], v[212:215], v[22:25]
	v_mfma_f32_16x16x32_bf16 v[18:21], v[156:159], v[212:215], v[18:21]
	v_mfma_f32_16x16x32_bf16 v[46:49], v[160:163], v[176:179], v[46:49]
	v_mfma_f32_16x16x32_bf16 v[42:45], v[168:171], v[176:179], v[42:45]
	v_mfma_f32_16x16x32_bf16 v[30:33], v[160:163], v[186:189], v[30:33]
	v_mfma_f32_16x16x32_bf16 v[26:29], v[168:171], v[186:189], v[26:29]
	v_mfma_f32_16x16x32_bf16 v[14:17], v[160:163], v[200:203], v[14:17]
	v_mfma_f32_16x16x32_bf16 v[10:13], v[168:171], v[200:203], v[10:13]
	v_mfma_f32_16x16x32_bf16 v[6:9], v[160:163], v[208:211], v[6:9]
	v_mfma_f32_16x16x32_bf16 v[2:5], v[168:171], v[208:211], v[2:5]
	v_mfma_f32_16x16x32_bf16 v[46:49], v[164:167], v[180:183], v[46:49]
	v_mfma_f32_16x16x32_bf16 v[42:45], v[172:175], v[180:183], v[42:45]
	v_mfma_f32_16x16x32_bf16 v[30:33], v[164:167], v[196:199], v[30:33]
	v_mfma_f32_16x16x32_bf16 v[26:29], v[172:175], v[196:199], v[26:29]
	v_mfma_f32_16x16x32_bf16 v[14:17], v[164:167], v[204:207], v[14:17]
	v_mfma_f32_16x16x32_bf16 v[10:13], v[172:175], v[204:207], v[10:13]
	v_mfma_f32_16x16x32_bf16 v[6:9], v[164:167], v[212:215], v[6:9]
	v_mfma_f32_16x16x32_bf16 v[2:5], v[172:175], v[212:215], v[2:5]
	s_setprio 0
	s_barrier
	s_add_i32 s12, 0, 0x18000
	s_add_i32 s66, 0, 0x1c000
	v_add_u32_e32 v156, s12, v141
	v_add_u32_e32 v172, s66, v141
	ds_read_b128 v[144:147], v156
	ds_read_b128 v[148:151], v156 offset:1024
	ds_read_b128 v[152:155], v156 offset:2048
	ds_read_b128 v[156:159], v156 offset:3072
	ds_read_b128 v[160:163], v172
	ds_read_b128 v[164:167], v172 offset:1024
	ds_read_b128 v[168:171], v172 offset:2048
	ds_read_b128 v[172:175], v172 offset:3072
	s_add_u32 s50, s50, 0x80000
	s_addc_u32 s51, s51, 0
	s_mov_b32 m0, s54
	v_lshl_add_u64 v[232:233], s[50:51], 0, v[134:135]
	ds_read_b128 v[176:179], v143 offset:32768
	ds_read_b128 v[180:183], v143 offset:33792
	ds_read_b128 v[186:189], v143 offset:34816
	ds_read_b128 v[196:199], v143 offset:35840
	ds_read_b128 v[200:203], v143 offset:36864
	ds_read_b128 v[204:207], v143 offset:37888
	ds_read_b128 v[208:211], v143 offset:38912
	ds_read_b128 v[212:215], v143 offset:39936
	global_load_lds_dwordx4 v[232:233], off
	v_lshl_add_u64 v[232:233], s[50:51], 0, v[132:133]
	s_mov_b32 m0, s55
	s_nop 0
	global_load_lds_dwordx4 v[232:233], off
	s_waitcnt vmcnt(8)
	s_waitcnt lgkmcnt(0)
	s_barrier
	s_setprio 1
	s_waitcnt lgkmcnt(0)
	v_mfma_f32_16x16x32_bf16 v[126:129], v[144:147], v[176:179], v[126:129]
	v_mfma_f32_16x16x32_bf16 v[122:125], v[152:155], v[176:179], v[122:125]
	v_mfma_f32_16x16x32_bf16 v[118:121], v[144:147], v[186:189], v[118:121]
	v_mfma_f32_16x16x32_bf16 v[114:117], v[152:155], v[186:189], v[114:117]
	v_mfma_f32_16x16x32_bf16 v[102:105], v[144:147], v[200:203], v[102:105]
	v_mfma_f32_16x16x32_bf16 v[98:101], v[152:155], v[200:203], v[98:101]
	v_mfma_f32_16x16x32_bf16 v[86:89], v[144:147], v[208:211], v[86:89]
	v_mfma_f32_16x16x32_bf16 v[82:85], v[152:155], v[208:211], v[82:85]
	v_mfma_f32_16x16x32_bf16 v[126:129], v[148:151], v[180:183], v[126:129]
	v_mfma_f32_16x16x32_bf16 v[122:125], v[156:159], v[180:183], v[122:125]
	v_mfma_f32_16x16x32_bf16 v[118:121], v[148:151], v[196:199], v[118:121]
	v_mfma_f32_16x16x32_bf16 v[114:117], v[156:159], v[196:199], v[114:117]
	v_mfma_f32_16x16x32_bf16 v[102:105], v[148:151], v[204:207], v[102:105]
	v_mfma_f32_16x16x32_bf16 v[98:101], v[156:159], v[204:207], v[98:101]
	v_mfma_f32_16x16x32_bf16 v[86:89], v[148:151], v[212:215], v[86:89]
	v_mfma_f32_16x16x32_bf16 v[82:85], v[156:159], v[212:215], v[82:85]
	v_mfma_f32_16x16x32_bf16 v[110:113], v[160:163], v[176:179], v[110:113]
	v_mfma_f32_16x16x32_bf16 v[106:109], v[168:171], v[176:179], v[106:109]
	v_mfma_f32_16x16x32_bf16 v[94:97], v[160:163], v[186:189], v[94:97]
	v_mfma_f32_16x16x32_bf16 v[90:93], v[168:171], v[186:189], v[90:93]
	v_mfma_f32_16x16x32_bf16 v[78:81], v[160:163], v[200:203], v[78:81]
	v_mfma_f32_16x16x32_bf16 v[74:77], v[168:171], v[200:203], v[74:77]
	v_mfma_f32_16x16x32_bf16 v[70:73], v[160:163], v[208:211], v[70:73]
	v_mfma_f32_16x16x32_bf16 v[66:69], v[168:171], v[208:211], v[66:69]
	v_mfma_f32_16x16x32_bf16 v[110:113], v[164:167], v[180:183], v[110:113]
	v_mfma_f32_16x16x32_bf16 v[106:109], v[172:175], v[180:183], v[106:109]
	v_mfma_f32_16x16x32_bf16 v[94:97], v[164:167], v[196:199], v[94:97]
	v_mfma_f32_16x16x32_bf16 v[90:93], v[172:175], v[196:199], v[90:93]
	v_mfma_f32_16x16x32_bf16 v[78:81], v[164:167], v[204:207], v[78:81]
	v_mfma_f32_16x16x32_bf16 v[74:77], v[172:175], v[204:207], v[74:77]
	v_mfma_f32_16x16x32_bf16 v[70:73], v[164:167], v[212:215], v[70:73]
	v_mfma_f32_16x16x32_bf16 v[66:69], v[172:175], v[212:215], v[66:69]
	s_setprio 0
	s_barrier
; #define PG8_STAGE(bufoff, gbase, voff) do { _Pragma("unroll") for (int _i = 0; _i < 2; ++_i) \
;         __builtin_amdgcn_global_load_lds((const unsigned*)((const char*)(gbase) + (voff)[_i]), (LAS unsigned*)(lds + (bufoff) + ldsw + _i * 8192), 16, 0, 0); } while (0)
; #define PG8_LDA(dst, b, h) do { _Pragma("unroll") for (int m = 0; m < 4; ++m) _Pragma("unroll") for (int k = 0; k < 2; ++k) dst[m][k] = *(const LAS bf16x8*)(lds + PG8_SA(b, h) + aoff + m * 2048 + k * 1024); } while (0)
; #define PG8_MMA(ai, bj, At, Bt) do { __builtin_amdgcn_s_setprio(1); _Pragma("unroll") for (int m = 0; m < 4; ++m) _Pragma("unroll") for (int n = 0; n < 2; ++n) _Pragma("unroll") for (int k = 0; k < 2; ++k) \
;         acc[ai][bj][m][n] = __builtin_amdgcn_mfma_f32_16x16x32_bf16(Bt[n][k], At[m][k], acc[ai][bj][m][n], 0, 0, 0); __builtin_amdgcn_s_setprio(0); } while (0)
; #define PG8_WAIT_V(n) asm volatile("s_waitcnt vmcnt(" #n ")" ::: "memory")
; #define PG8_WAIT_L(n) asm volatile("s_waitcnt lgkmcnt(" #n ")" ::: "memory")
; #define PG8_BAR __builtin_amdgcn_s_barrier()
; #define PG8_SCHED __builtin_amdgcn_sched_barrier(0)
; template <class Epi>
; DI void gemm_phase(LAS unsigned char* lds, const Gemm g, const Epi& E, const int tid) {
;     ...
;             PG8_WAIT_V(8); PG8_WAIT_L(0); PG8_BAR; PG8_MMA(0, 0, At, B0); PG8_MMA(0, 1, At, B1); PG8_BAR; PG8_SCHED;
;             PG8_LDA(At, 1, 1); PG8_STAGE(PG8_SB(1, 0), b3, voffB); PG8_STAGE(PG8_SB(1, 1), b3 + hstepB, voffB); PG8_STAGE(PG8_SA(1, 0), a3, voffA);
;             PG8_WAIT_V(8); PG8_WAIT_L(0); PG8_BAR; PG8_MMA(1, 0, At, B0); PG8_MMA(1, 1, At, B1); PG8_BAR; PG8_SCHED;
;         }
;         if (wr == 0) PG8_BAR;
	s_add_i32 s12, s12, s4
	v_lshl_add_u64 v[192:193], v[192:193], 0, s[8:9]
	s_mov_b32 m0, s12
	ds_read_b128 v[176:179], v143 offset:49152
	ds_read_b128 v[180:183], v143 offset:50176
	ds_read_b128 v[186:189], v143 offset:51200
	ds_read_b128 v[196:199], v143 offset:52224
	ds_read_b128 v[200:203], v143 offset:53248
	ds_read_b128 v[204:207], v143 offset:54272
	ds_read_b128 v[208:211], v143 offset:55296
	ds_read_b128 v[212:215], v143 offset:56320
	global_load_lds_dwordx4 v[192:193], off
	s_add_i32 m0, s12, 0x2000
	s_add_u32 s48, s48, 0x20080
	v_lshl_add_u64 v[192:193], v[216:217], 0, s[8:9]
	s_addc_u32 s49, s49, 0
	s_add_i32 s12, s66, s4
	global_load_lds_dwordx4 v[192:193], off
	v_lshl_add_u64 v[192:193], s[48:49], 0, v[0:1]
	s_mov_b32 m0, s12
	s_nop 0
	global_load_lds_dwordx4 v[192:193], off
	v_lshl_add_u64 v[192:193], s[48:49], 0, v[130:131]
	s_add_i32 m0, s12, 0x2000
	s_nop 0
	global_load_lds_dwordx4 v[192:193], off
	v_lshl_add_u64 v[192:193], v[228:229], 0, s[8:9]
	s_mov_b32 m0, s56
	s_nop 0
	global_load_lds_dwordx4 v[192:193], off
	v_lshl_add_u64 v[192:193], v[230:231], 0, s[8:9]
	s_mov_b32 m0, s57
	s_nop 0
	global_load_lds_dwordx4 v[192:193], off
	s_waitcnt vmcnt(8)
	s_waitcnt lgkmcnt(0)
	s_barrier
	s_setprio 1
	s_waitcnt lgkmcnt(0)
	v_mfma_f32_16x16x32_bf16 v[62:65], v[144:147], v[176:179], v[62:65]
	v_mfma_f32_16x16x32_bf16 v[58:61], v[152:155], v[176:179], v[58:61]
	v_mfma_f32_16x16x32_bf16 v[54:57], v[144:147], v[186:189], v[54:57]
	v_mfma_f32_16x16x32_bf16 v[50:53], v[152:155], v[186:189], v[50:53]
	v_mfma_f32_16x16x32_bf16 v[38:41], v[144:147], v[200:203], v[38:41]
	v_mfma_f32_16x16x32_bf16 v[34:37], v[152:155], v[200:203], v[34:37]
	v_mfma_f32_16x16x32_bf16 v[22:25], v[144:147], v[208:211], v[22:25]
	v_mfma_f32_16x16x32_bf16 v[18:21], v[152:155], v[208:211], v[18:21]
	v_mfma_f32_16x16x32_bf16 v[62:65], v[148:151], v[180:183], v[62:65]
	v_mfma_f32_16x16x32_bf16 v[58:61], v[156:159], v[180:183], v[58:61]
	v_mfma_f32_16x16x32_bf16 v[54:57], v[148:151], v[196:199], v[54:57]
	v_mfma_f32_16x16x32_bf16 v[50:53], v[156:159], v[196:199], v[50:53]
	v_mfma_f32_16x16x32_bf16 v[38:41], v[148:151], v[204:207], v[38:41]
	v_mfma_f32_16x16x32_bf16 v[34:37], v[156:159], v[204:207], v[34:37]
	v_mfma_f32_16x16x32_bf16 v[22:25], v[148:151], v[212:215], v[22:25]
	v_mfma_f32_16x16x32_bf16 v[18:21], v[156:159], v[212:215], v[18:21]
	v_mfma_f32_16x16x32_bf16 v[46:49], v[160:163], v[176:179], v[46:49]
	v_mfma_f32_16x16x32_bf16 v[42:45], v[168:171], v[176:179], v[42:45]
	v_mfma_f32_16x16x32_bf16 v[30:33], v[160:163], v[186:189], v[30:33]
	v_mfma_f32_16x16x32_bf16 v[26:29], v[168:171], v[186:189], v[26:29]
	v_mfma_f32_16x16x32_bf16 v[14:17], v[160:163], v[200:203], v[14:17]
	v_mfma_f32_16x16x32_bf16 v[10:13], v[168:171], v[200:203], v[10:13]
	v_mfma_f32_16x16x32_bf16 v[6:9], v[160:163], v[208:211], v[6:9]
	v_mfma_f32_16x16x32_bf16 v[2:5], v[168:171], v[208:211], v[2:5]
	v_mfma_f32_16x16x32_bf16 v[46:49], v[164:167], v[180:183], v[46:49]
	v_mfma_f32_16x16x32_bf16 v[42:45], v[172:175], v[180:183], v[42:45]
	v_mfma_f32_16x16x32_bf16 v[30:33], v[164:167], v[196:199], v[30:33]
	v_mfma_f32_16x16x32_bf16 v[26:29], v[172:175], v[196:199], v[26:29]
	v_mfma_f32_16x16x32_bf16 v[14:17], v[164:167], v[204:207], v[14:17]
	v_mfma_f32_16x16x32_bf16 v[10:13], v[172:175], v[204:207], v[10:13]
	v_mfma_f32_16x16x32_bf16 v[6:9], v[164:167], v[212:215], v[6:9]
	v_mfma_f32_16x16x32_bf16 v[2:5], v[172:175], v[212:215], v[2:5]
	s_setprio 0
	s_barrier
	s_add_i32 s65, s65, 2
	s_add_u32 s46, s46, 0x100
	s_addc_u32 s47, s47, 0
	s_add_u32 s63, s63, 0x100
	s_addc_u32 s64, s64, 0
	s_cmp_gt_u32 s65, 5
	s_cbranch_scc0 .LBB0_195
	s_and_b64 vcc, exec, s[14:15]
	s_cbranch_vccz .LBB0_198
	s_barrier

;     ...
;     const float c0 = (DECAY ? cum[q0 + r] * LOG2E : 0.f) - m0;
;     const int ntiles = (qt + 1) * 4;
;     u32x4 pk_[NKL], pv_[2]; float pc_ = 0.f;
;     ...
;         unsigned char* st = smem + (j & 1) * STAGE;
;         bf16_t* Ks = (bf16_t*)st; bf16_t* Vs = (bf16_t*)(st + 64 * KLD * 2); float* cks = (float*)(st + 64 * KLD * 2 + 128 * VLD * 2);
;         if (amode != 5 || j == 0) {
; #pragma unroll
;         for (int i = 0; i < NKL; ++i) { const int c = tid + i * NTHR, row = c / NKC, cc = c % NKC; *(u32x4*)(Ks + row * KLD + cc * 8) = pk_[i]; }
; #pragma unroll
;         for (int i = 0; i < 2; ++i) { const int c = tid + i * NTHR, row = c >> 3, cc = c & 7; u32x2 lo, hi; lo[0] = pv_[i][0]; lo[1] = pv_[i][1]; hi[0] = pv_[i][2]; hi[1] = pv_[i][3];
;             *(u32x2*)(Vs + row * VLD + cc * 8) = lo; *(u32x2*)(Vs + row * VLD + cc * 8 + 4) = hi; }
;         if (DECAY && tid < 64) cks[tid] = pc_;
;         }
;         __syncthreads();
.LBB0_249:
	s_bitcmp1_b32 s60, 0
	s_cselect_b32 s0, 0x8900, 0
	s_add_i32 s41, s0, 0
	v_add3_u32 v0, s41, v207, v209
	s_waitcnt vmcnt(0)
	ds_write_b128 v0, v[214:217]
	v_add3_u32 v0, s41, v208, v210
	ds_write_b128 v0, v[222:225]
	v_lshl_add_u32 v0, v203, 1, s41
	s_movk_i32 s0, 0x4400
	v_add3_u32 v2, v0, v206, s0
	v_add3_u32 v0, v0, v205, s0
	ds_write2_b64 v2, v[244:245], v[246:247] offset1:1
	ds_write2_b64 v0, v[240:241], v[242:243] offset1:1
	s_and_saveexec_b64 s[0:1], vcc
	v_lshl_add_u32 v0, v196, 2, s41
	v_mul_f32_e32 v2, 0x3fb8aa3b, v201
	ds_write_b32 v0, v2 offset:34816
	s_or_b64 exec, exec, s[0:1]
	v_mov_b32_e32 v80, v182
	v_mov_b32_e32 v81, v182
	v_mov_b32_e32 v82, v182
	v_mov_b32_e32 v83, v182
	v_mov_b32_e32 v84, v182
	v_mov_b32_e32 v85, v182
	v_mov_b32_e32 v86, v182
	v_mov_b32_e32 v87, v182
	v_mov_b32_e32 v88, v182
	v_mov_b32_e32 v89, v182
	v_mov_b32_e32 v90, v182
	v_mov_b32_e32 v91, v182
	v_mov_b32_e32 v92, v182
	v_mov_b32_e32 v93, v182
	v_mov_b32_e32 v94, v182
	v_mov_b32_e32 v95, v182
	v_cmp_le_i32_e64 s[0:1], s40, v204
	s_add_i32 s98, s40, 63
	v_cmp_le_i32_e64 s[98:99], s98, v200
	s_waitcnt lgkmcnt(0)
	s_barrier
	v_add_u32_e32 v0, s40, v213
	v_mad_i64_i32 v[2:3], s[34:35], v0, s3, v[168:169]
	v_add_u32_e32 v0, s40, v212
	v_mad_i64_i32 v[4:5], s[34:35], v0, s3, v[170:171]
	global_load_dwordx4 v[214:217], v[2:3], off
	global_load_dwordx4 v[222:225], v[4:5], off
	s_add_i32 s4, s40, 64
	v_lshl_add_u64 v[2:3], s[4:5], 1, v[162:163]
	v_lshl_add_u64 v[4:5], v[2:3], 0, v[164:165]
	v_lshl_add_u64 v[2:3], v[2:3], 0, v[166:167]
	global_load_dwordx4 v[244:247], v[4:5], off
	global_load_dwordx4 v[240:243], v[2:3], off
	s_and_saveexec_b64 s[34:35], vcc
	s_cbranch_execz .Lfox_nocum
	v_add_u32_e32 v2, s40, v211
	v_ashrrev_i32_e32 v3, 31, v2
	v_lshl_add_u64 v[2:3], v[2:3], 2, s[24:25]
	global_load_dword v201, v[2:3], off

;     ...
;         if (active) {
; #pragma unroll
;             for (int kb = 0; kb < 2; ++kb) {
;                 constexpr int NB = KS / 4;
;                 const bf16_t* kp = Ks + (32 * kb + r) * KLD + 8 * h2;
;                 bf16x8 kf[2][4];
; #pragma unroll
;                 for (int e = 0; e < 4; ++e) kf[0][e] = *(const bf16x8*)(kp + 16 * e);
;                 f32x16 acc; for (int i = 0; i < 16; ++i) acc[i] = 0.f;
; #pragma unroll
;                 for (int bb = 0; bb < NB; ++bb) {
;                     if (bb + 1 < NB) {
; #pragma unroll
;                         for (int e = 0; e < 4; ++e) kf[(bb + 1) & 1][e] = *(const bf16x8*)(kp + 16 * (4 * (bb + 1) + e)); }
;                     __builtin_amdgcn_sched_barrier(0);
; #pragma unroll
;                     for (int e = 0; e < 4; ++e) acc = MFMA32(kf[bb & 1][e], qf[4 * bb + e], acc);
;                     __builtin_amdgcn_sched_barrier(0);
;                 }
;                 sacc[kb] = acc;
;             }
;         }
;         if (j + 1 < ntiles && amode != 5) ATT_ISSUE_K(j + 1);
;         if (active) {
;             const bool masked = (k0 + 63 > q0); const int qpos = q0 + r;
; #pragma unroll
;             for (int kb = 0; kb < 2; ++kb) {
;                 bf16x8 vfa[2][2], vfb[2][2];
; #pragma unroll
;                 for (int d = 0; d < 2; ++d) { vfa[d][0] = ld_perm(Vs + (32 * d + r) * VLD + 32 * kb + 4 * h2); vfa[d][1] = ld_perm(Vs + (32 * d + r) * VLD + 32 * kb + 16 + 4 * h2); }
;                 f32x4 c4[2];
;                 if (DECAY) {
; #pragma unroll
;                     for (int g = 0; g < 2; ++g) c4[g] = *(const f32x4*)(cks + 32 * kb + 8 * g + 4 * h2); }
;                 __builtin_amdgcn_sched_barrier(0);
;                 if (DECAY) {
; #pragma unroll
;                     for (int g = 0; g < 2; ++g)
; #pragma unroll
;                         for (int e = 0; e < 4; ++e) sacc[kb][4 * g + e] -= c4[g][e];
; #pragma unroll
;                     for (int g = 0; g < 2; ++g) c4[g] = *(const f32x4*)(cks + 32 * kb + 8 * (g + 2) + 4 * h2);
; #pragma unroll
;                     for (int g = 0; g < 2; ++g)
; #pragma unroll
;                         for (int e = 0; e < 4; ++e) sacc[kb][4 * (g + 2) + e] -= c4[g][e];
;                 }
;                 if (masked) {
; #pragma unroll
;                     for (int i = 0; i < 16; ++i) { if (k0 + 32 * kb + crow(i, h2) > qpos) sacc[kb][i] = -INFINITY; } }
.Lfox_fast:
	v_add3_u32 v0, s41, v198, v202
	ds_read_b128 v[2:5], v0
	ds_read_b128 v[6:9], v0 offset:32
	ds_read_b128 v[10:13], v0 offset:64
	ds_read_b128 v[148:151], v0 offset:96
	ds_read_b128 v[152:155], v0 offset:128
	ds_read_b128 v[156:159], v0 offset:160
	ds_read_b128 v[172:175], v0 offset:192
	ds_read_b128 v[144:147], v0 offset:224
	s_waitcnt lgkmcnt(7)
	v_mfma_f32_32x32x16_bf16 v[80:95], v[2:5], v[140:143], v[80:95]
	v_mov_b32_e32 v96, v182
	v_mov_b32_e32 v97, v182
	s_waitcnt lgkmcnt(6)
	v_mfma_f32_32x32x16_bf16 v[80:95], v[6:9], v[136:139], v[80:95]
	v_mov_b32_e32 v98, v182
	v_mov_b32_e32 v99, v182
	s_waitcnt lgkmcnt(5)
	v_mfma_f32_32x32x16_bf16 v[80:95], v[10:13], v[132:135], v[80:95]
	v_mov_b32_e32 v100, v182
	v_mov_b32_e32 v101, v182
	s_waitcnt lgkmcnt(4)
	v_mfma_f32_32x32x16_bf16 v[80:95], v[148:151], v[128:131], v[80:95]
	v_mov_b32_e32 v102, v182
	v_mov_b32_e32 v103, v182
	s_waitcnt lgkmcnt(3)
	v_mfma_f32_32x32x16_bf16 v[80:95], v[152:155], v[124:127], v[80:95]
	v_mov_b32_e32 v104, v182
	v_mov_b32_e32 v105, v182
	s_waitcnt lgkmcnt(2)
	v_mfma_f32_32x32x16_bf16 v[80:95], v[156:159], v[120:123], v[80:95]
	v_mov_b32_e32 v106, v182
	v_mov_b32_e32 v107, v182
	s_waitcnt lgkmcnt(1)
	v_mfma_f32_32x32x16_bf16 v[80:95], v[172:175], v[116:119], v[80:95]
	v_mov_b32_e32 v108, v182
	v_mov_b32_e32 v109, v182
	s_waitcnt lgkmcnt(0)
	v_mfma_f32_32x32x16_bf16 v[80:95], v[144:147], v[112:115], v[80:95]
	v_mov_b32_e32 v110, v182
	v_mov_b32_e32 v111, v182
	ds_read_b128 v[2:5], v0 offset:8704
	ds_read_b128 v[6:9], v0 offset:8736
	ds_read_b128 v[10:13], v0 offset:8768
	ds_read_b128 v[144:147], v0 offset:8800
	ds_read_b128 v[148:151], v0 offset:8832
	ds_read_b128 v[152:155], v0 offset:8864
	ds_read_b128 v[156:159], v0 offset:8896
	ds_read_b128 v[172:175], v0 offset:8928
	v_add_u32_e32 v232, s41, v198
	ds_read_b128 v[176:179], v232 offset:34816
	ds_read_b128 v[186:189], v232 offset:34848
	ds_read_b128 v[236:239], v232 offset:34880
	ds_read_b128 v[232:235], v232 offset:34912
	s_waitcnt lgkmcnt(11)
	v_mfma_f32_32x32x16_bf16 v[96:111], v[2:5], v[140:143], v[96:111]
	s_waitcnt lgkmcnt(10)
	v_mfma_f32_32x32x16_bf16 v[96:111], v[6:9], v[136:139], v[96:111]
	s_waitcnt lgkmcnt(0)
	v_sub_f32_e32 v192, v80, v176
	v_exp_f32_e32 v80, v192
	v_mfma_f32_32x32x16_bf16 v[96:111], v[10:13], v[132:135], v[96:111]
	v_sub_f32_e32 v193, v81, v177
	v_exp_f32_e32 v81, v193
	v_sub_f32_e32 v192, v82, v178
	v_exp_f32_e32 v82, v192
	v_sub_f32_e32 v193, v83, v179
	v_exp_f32_e32 v83, v193
	v_mfma_f32_32x32x16_bf16 v[96:111], v[144:147], v[128:131], v[96:111]
	v_sub_f32_e32 v192, v84, v186
	v_exp_f32_e32 v84, v192
	v_sub_f32_e32 v193, v85, v187
	v_exp_f32_e32 v85, v193
	v_sub_f32_e32 v192, v86, v188
	v_exp_f32_e32 v86, v192
	v_mfma_f32_32x32x16_bf16 v[96:111], v[148:151], v[124:127], v[96:111]
	v_sub_f32_e32 v193, v87, v189
	v_exp_f32_e32 v87, v193
	v_sub_f32_e32 v192, v88, v236
	v_exp_f32_e32 v88, v192
	v_sub_f32_e32 v193, v89, v237
	v_exp_f32_e32 v89, v193
	v_mfma_f32_32x32x16_bf16 v[96:111], v[152:155], v[120:123], v[96:111]
	v_sub_f32_e32 v192, v90, v238
	v_exp_f32_e32 v90, v192
	v_sub_f32_e32 v193, v91, v239
	v_exp_f32_e32 v91, v193
	v_sub_f32_e32 v192, v92, v232
	v_exp_f32_e32 v92, v192
	v_mfma_f32_32x32x16_bf16 v[96:111], v[156:159], v[116:119], v[96:111]
	v_sub_f32_e32 v193, v93, v233
	v_exp_f32_e32 v93, v193
	v_sub_f32_e32 v192, v94, v234
	v_exp_f32_e32 v94, v192
	v_sub_f32_e32 v193, v95, v235
	v_exp_f32_e32 v95, v193
	v_mfma_f32_32x32x16_bf16 v[96:111], v[172:175], v[112:115], v[96:111]
	v_cvt_pk_bf16_f32 v148, v80, v81
	v_cvt_pk_bf16_f32 v149, v82, v83
	v_cvt_pk_bf16_f32 v150, v84, v85
	v_cvt_pk_bf16_f32 v151, v86, v87
	v_cvt_pk_bf16_f32 v152, v88, v89
	v_cvt_pk_bf16_f32 v153, v90, v91
	v_cvt_pk_bf16_f32 v154, v92, v93
	v_cvt_pk_bf16_f32 v155, v94, v95
	v_add_u32_e32 v232, s41, v198
	ds_read_b128 v[156:159], v232 offset:34944
	ds_read_b128 v[172:175], v232 offset:34976
	ds_read_b128 v[176:179], v232 offset:35008
	ds_read_b128 v[186:189], v232 offset:35040
	v_lshlrev_b32_e32 v0, 1, v197
	v_add3_u32 v14, s41, v199, v0
	v_add_u32_e32 v15, 0x4000, v14
	v_add_u32_e32 v0, 0x5000, v14
	ds_read2_b64 v[2:5], v15 offset0:128 offset1:130
	ds_read2_b64 v[6:9], v15 offset0:132 offset1:134
	ds_read2_b64 v[10:13], v0 offset0:160 offset1:162
	ds_read2_b64 v[144:147], v0 offset0:164 offset1:166
	v_add_u32_e32 v236, 0x6000, v14
	v_add_u32_e32 v237, 0x7000, v14
	s_waitcnt lgkmcnt(3)
;     ...
;         if (active) {
;             const bool masked = (k0 + 63 > q0); const int qpos = q0 + r;
; #pragma unroll
;             for (int kb = 0; kb < 2; ++kb) {
;                 bf16x8 vfa[2][2], vfb[2][2];
; #pragma unroll
;                 for (int d = 0; d < 2; ++d) { vfa[d][0] = ld_perm(Vs + (32 * d + r) * VLD + 32 * kb + 4 * h2); vfa[d][1] = ld_perm(Vs + (32 * d + r) * VLD + 32 * kb + 16 + 4 * h2); }
;                 f32x4 c4[2];
;                 if (DECAY) {
; #pragma unroll
;                     for (int g = 0; g < 2; ++g) c4[g] = *(const f32x4*)(cks + 32 * kb + 8 * g + 4 * h2); }
;                 __builtin_amdgcn_sched_barrier(0);
;                 if (DECAY) {
; #pragma unroll
;                     for (int g = 0; g < 2; ++g)
; #pragma unroll
;                         for (int e = 0; e < 4; ++e) sacc[kb][4 * g + e] -= c4[g][e];
; #pragma unroll
;                     for (int g = 0; g < 2; ++g) c4[g] = *(const f32x4*)(cks + 32 * kb + 8 * (g + 2) + 4 * h2);
; #pragma unroll
;                     for (int g = 0; g < 2; ++g)
; #pragma unroll
;                         for (int e = 0; e < 4; ++e) sacc[kb][4 * (g + 2) + e] -= c4[g][e];
;                 }
;                 if (masked) {
; #pragma unroll
;                     for (int i = 0; i < 16; ++i) { if (k0 + 32 * kb + crow(i, h2) > qpos) sacc[kb][i] = -INFINITY; } }
;                 float rs = 0.f;
; #pragma unroll
;                 for (int i = 0; i < 16; ++i) { const float pz = __builtin_amdgcn_exp2f(sacc[kb][i] + c0); sacc[kb][i] = pz; rs += pz; }
;                 l_run += rs;
;                 const bf16x8 pf0 = pack8(sacc[kb], 0), pf1 = pack8(sacc[kb], 1);
;                 __builtin_amdgcn_sched_barrier(0);
; #pragma unroll
;                 for (int d = 0; d < 2; ++d) { oacc[d] = MFMA32(vfa[d][0], pf0, oacc[d]); oacc[d] = MFMA32(vfa[d][1], pf1, oacc[d]); }
; #pragma unroll
;                 for (int d = 0; d < 2; ++d) { vfb[d][0] = ld_perm(Vs + (32 * (d + 2) + r) * VLD + 32 * kb + 4 * h2); vfb[d][1] = ld_perm(Vs + (32 * (d + 2) + r) * VLD + 32 * kb + 16 + 4 * h2); }
;                 if (kb == 1 && j + 1 < ntiles && amode != 5) ATT_ISSUE_V(j + 1);
;                 __builtin_amdgcn_sched_barrier(0);
; #pragma unroll
;                 for (int d = 0; d < 2; ++d) { oacc[d + 2] = MFMA32(vfb[d][0], pf0, oacc[d + 2]); oacc[d + 2] = MFMA32(vfb[d][1], pf1, oacc[d + 2]); }
;             }
	v_mfma_f32_32x32x16_bf16 v[64:79], v[2:5], v[148:151], v[64:79]
	v_sub_f32_e32 v192, v96, v156
	v_exp_f32_e32 v96, v192
	v_sub_f32_e32 v193, v97, v157
	v_exp_f32_e32 v97, v193
	s_waitcnt lgkmcnt(1)
	v_mfma_f32_32x32x16_bf16 v[48:63], v[10:13], v[148:151], v[48:63]
	v_sub_f32_e32 v192, v98, v158
	v_exp_f32_e32 v98, v192
	v_sub_f32_e32 v193, v99, v159
	v_exp_f32_e32 v99, v193
	v_mfma_f32_32x32x16_bf16 v[64:79], v[6:9], v[152:155], v[64:79]
	ds_read2_b64 v[2:5], v237 offset0:228 offset1:230
	ds_read2_b64 v[6:9], v237 offset0:224 offset1:226
	v_sub_f32_e32 v192, v100, v172
	v_exp_f32_e32 v100, v192
	v_sub_f32_e32 v193, v101, v173
	v_exp_f32_e32 v101, v193
	s_waitcnt lgkmcnt(2)
	v_mfma_f32_32x32x16_bf16 v[48:63], v[144:147], v[152:155], v[48:63]
	ds_read2_b64 v[10:13], v236 offset0:192 offset1:194
	ds_read2_b64 v[144:147], v236 offset0:196 offset1:198
	v_sub_f32_e32 v192, v102, v174
	v_exp_f32_e32 v102, v192
	v_sub_f32_e32 v193, v103, v175
	v_exp_f32_e32 v103, v193
	s_waitcnt lgkmcnt(1)
	v_mfma_f32_32x32x16_bf16 v[32:47], v[10:13], v[148:151], v[32:47]
	v_sub_f32_e32 v192, v104, v176
	v_exp_f32_e32 v104, v192
	v_sub_f32_e32 v193, v105, v177
	v_exp_f32_e32 v105, v193
	v_mfma_f32_32x32x16_bf16 v[16:31], v[6:9], v[148:151], v[16:31]
	v_sub_f32_e32 v192, v106, v178
	v_exp_f32_e32 v106, v192
	v_sub_f32_e32 v193, v107, v179
	v_exp_f32_e32 v107, v193
	s_waitcnt lgkmcnt(0)
	v_mfma_f32_32x32x16_bf16 v[32:47], v[144:147], v[152:155], v[32:47]
	ds_read2_b64 v[6:9], v15 offset0:136 offset1:138
	ds_read2_b64 v[10:13], v15 offset0:140 offset1:142
	ds_read2_b64 v[144:147], v0 offset0:168 offset1:170
	ds_read2_b64 v[232:235], v0 offset0:172 offset1:174
	v_sub_f32_e32 v192, v108, v186
	v_exp_f32_e32 v108, v192
	v_sub_f32_e32 v193, v109, v187
	v_exp_f32_e32 v109, v193
	v_mfma_f32_32x32x16_bf16 v[16:31], v[2:5], v[152:155], v[16:31]
	v_sub_f32_e32 v192, v110, v188
	v_exp_f32_e32 v110, v192
	v_sub_f32_e32 v193, v111, v189
	v_exp_f32_e32 v111, v193
	v_cvt_pk_bf16_f32 v2, v96, v97
	v_cvt_pk_bf16_f32 v3, v98, v99
	v_cvt_pk_bf16_f32 v4, v100, v101
	v_cvt_pk_bf16_f32 v5, v102, v103
	v_cvt_pk_bf16_f32 v148, v104, v105
	v_cvt_pk_bf16_f32 v149, v106, v107
	v_cvt_pk_bf16_f32 v150, v108, v109
	v_cvt_pk_bf16_f32 v151, v110, v111
	s_waitcnt lgkmcnt(3)
	v_mfma_f32_32x32x16_bf16 v[64:79], v[6:9], v[2:5], v[64:79]
	v_add_f32_e32 v192, 0, v80
	v_add_f32_e32 v193, 0, v96
	v_add_f32_e32 v192, v81, v192
	v_add_f32_e32 v193, v97, v193
	s_waitcnt lgkmcnt(1)
	v_mfma_f32_32x32x16_bf16 v[48:63], v[144:147], v[2:5], v[48:63]
	v_add_f32_e32 v192, v82, v192
	v_add_f32_e32 v193, v98, v193
	v_add_f32_e32 v192, v83, v192
	v_add_f32_e32 v193, v99, v193
	v_mfma_f32_32x32x16_bf16 v[64:79], v[10:13], v[148:151], v[64:79]
	ds_read2_b64 v[6:9], v236 offset0:200 offset1:202
	ds_read2_b64 v[10:13], v236 offset0:204 offset1:206
	ds_read2_b64 v[144:147], v237 offset0:232 offset1:234
	ds_read2_b64 v[152:155], v237 offset0:236 offset1:238
	v_add_f32_e32 v192, v84, v192
	v_add_f32_e32 v193, v100, v193
	v_add_f32_e32 v192, v85, v192
	v_add_f32_e32 v193, v101, v193
	s_waitcnt lgkmcnt(4)
	v_mfma_f32_32x32x16_bf16 v[48:63], v[232:235], v[148:151], v[48:63]
	v_add_f32_e32 v192, v86, v192
	v_add_f32_e32 v193, v102, v193
	v_add_f32_e32 v192, v87, v192
	v_add_f32_e32 v193, v103, v193
	s_waitcnt lgkmcnt(3)
	v_mfma_f32_32x32x16_bf16 v[32:47], v[6:9], v[2:5], v[32:47]
	v_add_f32_e32 v192, v88, v192
	v_add_f32_e32 v193, v104, v193
	v_add_f32_e32 v192, v89, v192
	v_add_f32_e32 v193, v105, v193
	s_waitcnt lgkmcnt(1)
	v_mfma_f32_32x32x16_bf16 v[16:31], v[144:147], v[2:5], v[16:31]
	v_add_f32_e32 v192, v90, v192
	v_add_f32_e32 v193, v106, v193
	v_add_f32_e32 v192, v91, v192
	v_add_f32_e32 v193, v107, v193
	v_mfma_f32_32x32x16_bf16 v[32:47], v[10:13], v[148:151], v[32:47]
	v_add_f32_e32 v192, v92, v192
	v_add_f32_e32 v193, v108, v193
	v_add_f32_e32 v192, v93, v192
	v_add_f32_e32 v193, v109, v193
	s_waitcnt lgkmcnt(0)
	v_mfma_f32_32x32x16_bf16 v[16:31], v[152:155], v[148:151], v[16:31]
	v_add_f32_e32 v192, v94, v192
	v_add_f32_e32 v193, v110, v193
	v_add_f32_e32 v192, v95, v192
	v_add_f32_e32 v193, v111, v193
	v_add_f32_e32 v192, v183, v192
	v_add_f32_e32 v183, v192, v193
	s_branch .LBB0_257

; #define PG8_STAGE(bufoff, gbase, voff) do { _Pragma("unroll") for (int _i = 0; _i < 2; ++_i) \
;         __builtin_amdgcn_global_load_lds((const unsigned*)((const char*)(gbase) + (voff)[_i]), (LAS unsigned*)(lds + (bufoff) + ldsw + _i * 8192), 16, 0, 0); } while (0)
; #define PG8_LDA(dst, b, h) do { _Pragma("unroll") for (int m = 0; m < 4; ++m) _Pragma("unroll") for (int k = 0; k < 2; ++k) dst[m][k] = *(const LAS bf16x8*)(lds + PG8_SA(b, h) + aoff + m * 2048 + k * 1024); } while (0)
; #define PG8_LDB(dst, b, h) do { _Pragma("unroll") for (int n = 0; n < 2; ++n) _Pragma("unroll") for (int k = 0; k < 2; ++k) dst[n][k] = *(const LAS bf16x8*)(lds + PG8_SB(b, h) + boff + n * 2048 + k * 1024); } while (0)
; #define PG8_WAIT_V(n) asm volatile("s_waitcnt vmcnt(" #n ")" ::: "memory")
; #define PG8_WAIT_L(n) asm volatile("s_waitcnt lgkmcnt(" #n ")" ::: "memory")
; #define PG8_BAR __builtin_amdgcn_s_barrier()
; #define PG8_SCHED __builtin_amdgcn_sched_barrier(0)
; template <class Epi>
; DI void gemm_phase(LAS unsigned char* lds, const Gemm g, const Epi& E, const int tid) {
;     ...
;         const bool has_next = S.next(ui + 1, nxt);
;         const char* nA = has_next ? (const char*)g.A + (size_t)nxt.z * g.zA * 2 + (size_t)nxt.pm * 2 * hstepA + (nxt.pn >= g.pn_split ? (size_t)g.a_off2 * 2 : (size_t)0) : cA;
;         const char* nB = has_next ? (const char*)g.Bt + (size_t)nxt.z * g.zB * 2 + (size_t)nxt.pn * 2 * hstepB : cB;
; #pragma clang loop unroll(disable)
;         for (int t = 0; t < nt; t += 2) {
;             const bool last = (t == nt - 2);
;             const char* a1 = cA + (size_t)(t + 1) * kstepA;
;             const char* a2 = last ? nA : cA + (size_t)(t + 2) * kstepA; const char* b2 = last ? nB : cB + (size_t)(t + 2) * kstep;
;             const char* a3 = a2 + kstepA; const char* b3 = b2 + kstep;
;             PG8_LDB(B0, 0, 0); PG8_LDB(B1, 0, 1); PG8_SCHED; PG8_LDA(At, 0, 0); PG8_STAGE(PG8_SA(1, 1), a1 + hstepA, voffA);
;             PG8_WAIT_V(8); PG8_WAIT_L(0); PG8_BAR; PG8_MMA(0, 0, At, B0); PG8_MMA(0, 1, At, B1); PG8_BAR; PG8_SCHED;
;             PG8_LDA(At, 0, 1); PG8_STAGE(PG8_SB(0, 0), b2, voffB); PG8_STAGE(PG8_SB(0, 1), b2 + hstepB, voffB); PG8_STAGE(PG8_SA(0, 0), a2, voffA);
;             PG8_WAIT_V(8); PG8_WAIT_L(0); PG8_BAR; PG8_MMA(1, 0, At, B0); PG8_MMA(1, 1, At, B1); PG8_BAR; PG8_SCHED;
.LBB0_360:
	s_add_u32 s12, s46, s50
	s_addc_u32 s51, s47, 0
	s_add_u32 s54, s12, 0x100
	s_addc_u32 s55, s51, 0
	s_and_b64 s[52:53], s[48:49], exec
	s_cselect_b32 s53, s41, s55
	s_cselect_b32 s52, s40, s54
	s_add_u32 s50, s44, s50
	s_addc_u32 s54, s45, 0
	s_add_u32 s50, s50, 0x100
	s_addc_u32 s54, s54, 0
	s_add_i32 s81, 0, 0x10000
	s_and_b64 s[48:49], s[48:49], exec
	s_cselect_b32 s55, s35, s54
	s_cselect_b32 s54, s70, s50
	s_add_i32 s49, 0, 0x14000
	s_add_u32 s58, s12, 0x18080
	s_addc_u32 s59, s51, 0
	s_add_i32 s80, s81, s4
	s_add_i32 m0, s60, 0xc000
	s_add_i32 s12, s60, 0xe000
	s_add_i32 s75, s80, 0x2000
	s_add_u32 s56, s54, 0x10000
	v_add_u32_e32 v152, s81, v137
	v_add_u32_e32 v168, s49, v137
	s_addc_u32 s57, s55, 0
	s_add_i32 s79, s49, s4
	ds_read_b128 v[140:143], v152
	ds_read_b128 v[144:147], v152 offset:1024
	ds_read_b128 v[148:151], v152 offset:2048
	ds_read_b128 v[152:155], v152 offset:3072
	ds_read_b128 v[156:159], v168
	ds_read_b128 v[160:163], v168 offset:1024
	ds_read_b128 v[164:167], v168 offset:2048
	ds_read_b128 v[168:171], v168 offset:3072
	s_add_i32 s78, s79, 0x2000
	s_add_i32 s74, 0, 0x18000
	s_add_i32 s73, 0, 0x1c000
	s_add_u32 s50, s52, 0x18000
	s_addc_u32 s51, s53, 0
	s_add_i32 s72, s74, s4
	s_add_i32 s71, s72, 0x2000
	s_add_u32 s48, s54, 0x10080
	s_addc_u32 s49, s55, 0
	s_add_i32 s82, s73, s4
	s_add_i32 s81, s82, 0x2000
	v_lshl_add_u64 v[186:187], s[58:59], 0, v[134:135]
	ds_read_b128 v[172:175], v139
	ds_read_b128 v[176:179], v139 offset:1024
	ds_read_b128 v[180:183], v139 offset:2048
	ds_read_b128 v[196:199], v139 offset:3072
	ds_read_b128 v[200:203], v139 offset:4096
	ds_read_b128 v[204:207], v139 offset:5120
	ds_read_b128 v[208:211], v139 offset:6144
	ds_read_b128 v[228:231], v139 offset:7168
	global_load_lds_dwordx4 v[186:187], off
	v_lshl_add_u64 v[186:187], s[58:59], 0, v[132:133]
	s_mov_b32 m0, s12
	s_nop 0
	global_load_lds_dwordx4 v[186:187], off
	s_waitcnt vmcnt(8)
	s_waitcnt lgkmcnt(0)
	s_barrier
	s_setprio 1
	s_waitcnt lgkmcnt(0)
	v_mfma_f32_16x16x32_bf16 v[126:129], v[140:143], v[172:175], v[126:129]
	v_mfma_f32_16x16x32_bf16 v[122:125], v[148:151], v[172:175], v[122:125]
	v_mfma_f32_16x16x32_bf16 v[118:121], v[140:143], v[180:183], v[118:121]
	v_mfma_f32_16x16x32_bf16 v[114:117], v[148:151], v[180:183], v[114:117]
	v_mfma_f32_16x16x32_bf16 v[102:105], v[140:143], v[200:203], v[102:105]
	v_mfma_f32_16x16x32_bf16 v[98:101], v[148:151], v[200:203], v[98:101]
	v_mfma_f32_16x16x32_bf16 v[86:89], v[140:143], v[208:211], v[86:89]
	v_mfma_f32_16x16x32_bf16 v[82:85], v[148:151], v[208:211], v[82:85]
	v_mfma_f32_16x16x32_bf16 v[126:129], v[144:147], v[176:179], v[126:129]
	v_mfma_f32_16x16x32_bf16 v[122:125], v[152:155], v[176:179], v[122:125]
	v_mfma_f32_16x16x32_bf16 v[118:121], v[144:147], v[196:199], v[118:121]
	v_mfma_f32_16x16x32_bf16 v[114:117], v[152:155], v[196:199], v[114:117]
	v_mfma_f32_16x16x32_bf16 v[102:105], v[144:147], v[204:207], v[102:105]
	v_mfma_f32_16x16x32_bf16 v[98:101], v[152:155], v[204:207], v[98:101]
	v_mfma_f32_16x16x32_bf16 v[86:89], v[144:147], v[228:231], v[86:89]
	v_mfma_f32_16x16x32_bf16 v[82:85], v[152:155], v[228:231], v[82:85]
	v_mfma_f32_16x16x32_bf16 v[110:113], v[156:159], v[172:175], v[110:113]
	v_mfma_f32_16x16x32_bf16 v[106:109], v[164:167], v[172:175], v[106:109]
	v_mfma_f32_16x16x32_bf16 v[94:97], v[156:159], v[180:183], v[94:97]
	v_mfma_f32_16x16x32_bf16 v[90:93], v[164:167], v[180:183], v[90:93]
	v_mfma_f32_16x16x32_bf16 v[78:81], v[156:159], v[200:203], v[78:81]
	v_mfma_f32_16x16x32_bf16 v[74:77], v[164:167], v[200:203], v[74:77]
	v_mfma_f32_16x16x32_bf16 v[70:73], v[156:159], v[208:211], v[70:73]
	v_mfma_f32_16x16x32_bf16 v[66:69], v[164:167], v[208:211], v[66:69]
	v_mfma_f32_16x16x32_bf16 v[110:113], v[160:163], v[176:179], v[110:113]
	v_mfma_f32_16x16x32_bf16 v[106:109], v[168:171], v[176:179], v[106:109]
	v_mfma_f32_16x16x32_bf16 v[94:97], v[160:163], v[196:199], v[94:97]
	v_mfma_f32_16x16x32_bf16 v[90:93], v[168:171], v[196:199], v[90:93]
	v_mfma_f32_16x16x32_bf16 v[78:81], v[160:163], v[204:207], v[78:81]
	v_mfma_f32_16x16x32_bf16 v[74:77], v[168:171], v[204:207], v[74:77]
	v_mfma_f32_16x16x32_bf16 v[70:73], v[160:163], v[228:231], v[70:73]
	v_mfma_f32_16x16x32_bf16 v[66:69], v[168:171], v[228:231], v[66:69]
	s_setprio 0
	s_barrier
	s_mov_b32 m0, s80
	v_lshl_add_u64 v[186:187], s[54:55], 0, v[0:1]
	ds_read_b128 v[172:175], v139 offset:16384
	ds_read_b128 v[176:179], v139 offset:17408
	ds_read_b128 v[180:183], v139 offset:18432
	ds_read_b128 v[196:199], v139 offset:19456
	ds_read_b128 v[200:203], v139 offset:20480
	ds_read_b128 v[204:207], v139 offset:21504
	ds_read_b128 v[208:211], v139 offset:22528
	ds_read_b128 v[228:231], v139 offset:23552
	global_load_lds_dwordx4 v[186:187], off
	v_lshl_add_u64 v[188:189], s[54:55], 0, v[130:131]
	s_mov_b32 m0, s75
	v_lshl_add_u64 v[212:213], s[56:57], 0, v[0:1]
	global_load_lds_dwordx4 v[188:189], off
	s_mov_b32 m0, s79
	v_lshl_add_u64 v[214:215], s[52:53], 0, v[132:133]
	global_load_lds_dwordx4 v[212:213], off
	v_lshl_add_u64 v[212:213], s[56:57], 0, v[130:131]
	s_mov_b32 m0, s78
	s_nop 0
	global_load_lds_dwordx4 v[212:213], off
	v_lshl_add_u64 v[212:213], s[52:53], 0, v[134:135]
	s_mov_b32 m0, s60
	s_nop 0
	global_load_lds_dwordx4 v[212:213], off
	s_mov_b32 m0, s61
	s_nop 0
	global_load_lds_dwordx4 v[214:215], off
	s_waitcnt vmcnt(8)
	s_waitcnt lgkmcnt(0)
	s_barrier
; #define PG8_STAGE(bufoff, gbase, voff) do { _Pragma("unroll") for (int _i = 0; _i < 2; ++_i) \
;         __builtin_amdgcn_global_load_lds((const unsigned*)((const char*)(gbase) + (voff)[_i]), (LAS unsigned*)(lds + (bufoff) + ldsw + _i * 8192), 16, 0, 0); } while (0)
; #define PG8_LDA(dst, b, h) do { _Pragma("unroll") for (int m = 0; m < 4; ++m) _Pragma("unroll") for (int k = 0; k < 2; ++k) dst[m][k] = *(const LAS bf16x8*)(lds + PG8_SA(b, h) + aoff + m * 2048 + k * 1024); } while (0)
; #define PG8_LDB(dst, b, h) do { _Pragma("unroll") for (int n = 0; n < 2; ++n) _Pragma("unroll") for (int k = 0; k < 2; ++k) dst[n][k] = *(const LAS bf16x8*)(lds + PG8_SB(b, h) + boff + n * 2048 + k * 1024); } while (0)
; #define PG8_MMA(ai, bj, At, Bt) do { __builtin_amdgcn_s_setprio(1); _Pragma("unroll") for (int m = 0; m < 4; ++m) _Pragma("unroll") for (int n = 0; n < 2; ++n) _Pragma("unroll") for (int k = 0; k < 2; ++k) \
;         acc[ai][bj][m][n] = __builtin_amdgcn_mfma_f32_16x16x32_bf16(Bt[n][k], At[m][k], acc[ai][bj][m][n], 0, 0, 0); __builtin_amdgcn_s_setprio(0); } while (0)
; #define PG8_WAIT_V(n) asm volatile("s_waitcnt vmcnt(" #n ")" ::: "memory")
; #define PG8_WAIT_L(n) asm volatile("s_waitcnt lgkmcnt(" #n ")" ::: "memory")
; #define PG8_BAR __builtin_amdgcn_s_barrier()
; #define PG8_SCHED __builtin_amdgcn_sched_barrier(0)
; template <class Epi>
; DI void gemm_phase(LAS unsigned char* lds, const Gemm g, const Epi& E, const int tid) {
;     ...
;             PG8_WAIT_V(8); PG8_WAIT_L(0); PG8_BAR; PG8_MMA(1, 0, At, B0); PG8_MMA(1, 1, At, B1); PG8_BAR; PG8_SCHED;
;             PG8_LDB(B0, 1, 0); PG8_LDB(B1, 1, 1); PG8_SCHED; PG8_LDA(At, 1, 0); PG8_STAGE(PG8_SA(0, 1), a2 + hstepA, voffA);
;             PG8_WAIT_V(8); PG8_WAIT_L(0); PG8_BAR; PG8_MMA(0, 0, At, B0); PG8_MMA(0, 1, At, B1); PG8_BAR; PG8_SCHED;
;             PG8_LDA(At, 1, 1); PG8_STAGE(PG8_SB(1, 0), b3, voffB); PG8_STAGE(PG8_SB(1, 1), b3 + hstepB, voffB); PG8_STAGE(PG8_SA(1, 0), a3, voffA);
	s_setprio 1
	s_waitcnt lgkmcnt(0)
	v_mfma_f32_16x16x32_bf16 v[62:65], v[140:143], v[172:175], v[62:65]
	v_mfma_f32_16x16x32_bf16 v[58:61], v[148:151], v[172:175], v[58:61]
	v_mfma_f32_16x16x32_bf16 v[54:57], v[140:143], v[180:183], v[54:57]
	v_mfma_f32_16x16x32_bf16 v[50:53], v[148:151], v[180:183], v[50:53]
	v_mfma_f32_16x16x32_bf16 v[38:41], v[140:143], v[200:203], v[38:41]
	v_mfma_f32_16x16x32_bf16 v[34:37], v[148:151], v[200:203], v[34:37]
	v_mfma_f32_16x16x32_bf16 v[22:25], v[140:143], v[208:211], v[22:25]
	v_mfma_f32_16x16x32_bf16 v[18:21], v[148:151], v[208:211], v[18:21]
	v_mfma_f32_16x16x32_bf16 v[62:65], v[144:147], v[176:179], v[62:65]
	v_mfma_f32_16x16x32_bf16 v[58:61], v[152:155], v[176:179], v[58:61]
	v_mfma_f32_16x16x32_bf16 v[54:57], v[144:147], v[196:199], v[54:57]
	v_mfma_f32_16x16x32_bf16 v[50:53], v[152:155], v[196:199], v[50:53]
	v_mfma_f32_16x16x32_bf16 v[38:41], v[144:147], v[204:207], v[38:41]
	v_mfma_f32_16x16x32_bf16 v[34:37], v[152:155], v[204:207], v[34:37]
	v_mfma_f32_16x16x32_bf16 v[22:25], v[144:147], v[228:231], v[22:25]
	v_mfma_f32_16x16x32_bf16 v[18:21], v[152:155], v[228:231], v[18:21]
	v_mfma_f32_16x16x32_bf16 v[46:49], v[156:159], v[172:175], v[46:49]
	v_mfma_f32_16x16x32_bf16 v[42:45], v[164:167], v[172:175], v[42:45]
	v_mfma_f32_16x16x32_bf16 v[30:33], v[156:159], v[180:183], v[30:33]
	v_mfma_f32_16x16x32_bf16 v[26:29], v[164:167], v[180:183], v[26:29]
	v_mfma_f32_16x16x32_bf16 v[14:17], v[156:159], v[200:203], v[14:17]
	v_mfma_f32_16x16x32_bf16 v[10:13], v[164:167], v[200:203], v[10:13]
	v_mfma_f32_16x16x32_bf16 v[6:9], v[156:159], v[208:211], v[6:9]
	v_mfma_f32_16x16x32_bf16 v[2:5], v[164:167], v[208:211], v[2:5]
	v_mfma_f32_16x16x32_bf16 v[46:49], v[160:163], v[176:179], v[46:49]
	v_mfma_f32_16x16x32_bf16 v[42:45], v[168:171], v[176:179], v[42:45]
	v_mfma_f32_16x16x32_bf16 v[30:33], v[160:163], v[196:199], v[30:33]
	v_mfma_f32_16x16x32_bf16 v[26:29], v[168:171], v[196:199], v[26:29]
	v_mfma_f32_16x16x32_bf16 v[14:17], v[160:163], v[204:207], v[14:17]
	v_mfma_f32_16x16x32_bf16 v[10:13], v[168:171], v[204:207], v[10:13]
	v_mfma_f32_16x16x32_bf16 v[6:9], v[160:163], v[228:231], v[6:9]
	v_mfma_f32_16x16x32_bf16 v[2:5], v[168:171], v[228:231], v[2:5]
	s_setprio 0
	s_barrier
	v_add_u32_e32 v152, s74, v137
	v_add_u32_e32 v168, s73, v137
	ds_read_b128 v[140:143], v152
	ds_read_b128 v[144:147], v152 offset:1024
	ds_read_b128 v[148:151], v152 offset:2048
	ds_read_b128 v[152:155], v152 offset:3072
	ds_read_b128 v[156:159], v168
	ds_read_b128 v[160:163], v168 offset:1024
	ds_read_b128 v[164:167], v168 offset:2048
	ds_read_b128 v[168:171], v168 offset:3072
	s_mov_b32 m0, s62
	v_lshl_add_u64 v[216:217], s[50:51], 0, v[134:135]
	ds_read_b128 v[172:175], v139 offset:32768
	ds_read_b128 v[176:179], v139 offset:33792
	ds_read_b128 v[180:183], v139 offset:34816
	ds_read_b128 v[196:199], v139 offset:35840
	ds_read_b128 v[200:203], v139 offset:36864
	ds_read_b128 v[204:207], v139 offset:37888
	ds_read_b128 v[208:211], v139 offset:38912
	ds_read_b128 v[228:231], v139 offset:39936
	global_load_lds_dwordx4 v[216:217], off
	v_lshl_add_u64 v[216:217], s[50:51], 0, v[132:133]
	s_mov_b32 m0, s63
	s_nop 0
	global_load_lds_dwordx4 v[216:217], off
	s_waitcnt vmcnt(8)
	s_waitcnt lgkmcnt(0)
	s_barrier
	s_setprio 1
	s_waitcnt lgkmcnt(0)
	v_mfma_f32_16x16x32_bf16 v[126:129], v[140:143], v[172:175], v[126:129]
	v_mfma_f32_16x16x32_bf16 v[122:125], v[148:151], v[172:175], v[122:125]
	v_mfma_f32_16x16x32_bf16 v[118:121], v[140:143], v[180:183], v[118:121]
	v_mfma_f32_16x16x32_bf16 v[114:117], v[148:151], v[180:183], v[114:117]
	v_mfma_f32_16x16x32_bf16 v[102:105], v[140:143], v[200:203], v[102:105]
	v_mfma_f32_16x16x32_bf16 v[98:101], v[148:151], v[200:203], v[98:101]
	v_mfma_f32_16x16x32_bf16 v[86:89], v[140:143], v[208:211], v[86:89]
	v_mfma_f32_16x16x32_bf16 v[82:85], v[148:151], v[208:211], v[82:85]
	v_mfma_f32_16x16x32_bf16 v[126:129], v[144:147], v[176:179], v[126:129]
	v_mfma_f32_16x16x32_bf16 v[122:125], v[152:155], v[176:179], v[122:125]
	v_mfma_f32_16x16x32_bf16 v[118:121], v[144:147], v[196:199], v[118:121]
	v_mfma_f32_16x16x32_bf16 v[114:117], v[152:155], v[196:199], v[114:117]
	v_mfma_f32_16x16x32_bf16 v[102:105], v[144:147], v[204:207], v[102:105]
	v_mfma_f32_16x16x32_bf16 v[98:101], v[152:155], v[204:207], v[98:101]
	v_mfma_f32_16x16x32_bf16 v[86:89], v[144:147], v[228:231], v[86:89]
	v_mfma_f32_16x16x32_bf16 v[82:85], v[152:155], v[228:231], v[82:85]
	v_mfma_f32_16x16x32_bf16 v[110:113], v[156:159], v[172:175], v[110:113]
	v_mfma_f32_16x16x32_bf16 v[106:109], v[164:167], v[172:175], v[106:109]
	v_mfma_f32_16x16x32_bf16 v[94:97], v[156:159], v[180:183], v[94:97]
	v_mfma_f32_16x16x32_bf16 v[90:93], v[164:167], v[180:183], v[90:93]
	v_mfma_f32_16x16x32_bf16 v[78:81], v[156:159], v[200:203], v[78:81]
	v_mfma_f32_16x16x32_bf16 v[74:77], v[164:167], v[200:203], v[74:77]
	v_mfma_f32_16x16x32_bf16 v[70:73], v[156:159], v[208:211], v[70:73]
	v_mfma_f32_16x16x32_bf16 v[66:69], v[164:167], v[208:211], v[66:69]
	v_mfma_f32_16x16x32_bf16 v[110:113], v[160:163], v[176:179], v[110:113]
	v_mfma_f32_16x16x32_bf16 v[106:109], v[168:171], v[176:179], v[106:109]
	v_mfma_f32_16x16x32_bf16 v[94:97], v[160:163], v[196:199], v[94:97]
	v_mfma_f32_16x16x32_bf16 v[90:93], v[168:171], v[196:199], v[90:93]
	v_mfma_f32_16x16x32_bf16 v[78:81], v[160:163], v[204:207], v[78:81]
	v_mfma_f32_16x16x32_bf16 v[74:77], v[168:171], v[204:207], v[74:77]
	v_mfma_f32_16x16x32_bf16 v[70:73], v[160:163], v[228:231], v[70:73]
	v_mfma_f32_16x16x32_bf16 v[66:69], v[168:171], v[228:231], v[66:69]
	s_setprio 0
	s_barrier
; #define PG8_STAGE(bufoff, gbase, voff) do { _Pragma("unroll") for (int _i = 0; _i < 2; ++_i) \
;         __builtin_amdgcn_global_load_lds((const unsigned*)((const char*)(gbase) + (voff)[_i]), (LAS unsigned*)(lds + (bufoff) + ldsw + _i * 8192), 16, 0, 0); } while (0)
; #define PG8_LDA(dst, b, h) do { _Pragma("unroll") for (int m = 0; m < 4; ++m) _Pragma("unroll") for (int k = 0; k < 2; ++k) dst[m][k] = *(const LAS bf16x8*)(lds + PG8_SA(b, h) + aoff + m * 2048 + k * 1024); } while (0)
; #define PG8_MMA(ai, bj, At, Bt) do { __builtin_amdgcn_s_setprio(1); _Pragma("unroll") for (int m = 0; m < 4; ++m) _Pragma("unroll") for (int n = 0; n < 2; ++n) _Pragma("unroll") for (int k = 0; k < 2; ++k) \
;         acc[ai][bj][m][n] = __builtin_amdgcn_mfma_f32_16x16x32_bf16(Bt[n][k], At[m][k], acc[ai][bj][m][n], 0, 0, 0); __builtin_amdgcn_s_setprio(0); } while (0)
; #define PG8_WAIT_V(n) asm volatile("s_waitcnt vmcnt(" #n ")" ::: "memory")
; #define PG8_WAIT_L(n) asm volatile("s_waitcnt lgkmcnt(" #n ")" ::: "memory")
; #define PG8_BAR __builtin_amdgcn_s_barrier()
; #define PG8_SCHED __builtin_amdgcn_sched_barrier(0)
; template <class Epi>
; DI void gemm_phase(LAS unsigned char* lds, const Gemm g, const Epi& E, const int tid) {
;     ...
;             PG8_LDA(At, 1, 1); PG8_STAGE(PG8_SB(1, 0), b3, voffB); PG8_STAGE(PG8_SB(1, 1), b3 + hstepB, voffB); PG8_STAGE(PG8_SA(1, 0), a3, voffA);
;             PG8_WAIT_V(8); PG8_WAIT_L(0); PG8_BAR; PG8_MMA(1, 0, At, B0); PG8_MMA(1, 1, At, B1); PG8_BAR; PG8_SCHED;
;         }
;         if (wr == 0) PG8_BAR;
	s_mov_b32 m0, s72
	v_lshl_add_u64 v[186:187], v[186:187], 0, s[8:9]
	ds_read_b128 v[172:175], v139 offset:49152
	ds_read_b128 v[176:179], v139 offset:50176
	ds_read_b128 v[180:183], v139 offset:51200
	ds_read_b128 v[196:199], v139 offset:52224
	ds_read_b128 v[200:203], v139 offset:53248
	ds_read_b128 v[204:207], v139 offset:54272
	ds_read_b128 v[208:211], v139 offset:55296
	ds_read_b128 v[228:231], v139 offset:56320
	global_load_lds_dwordx4 v[186:187], off
	v_lshl_add_u64 v[186:187], v[188:189], 0, s[8:9]
	s_mov_b32 m0, s71
	s_nop 0
	global_load_lds_dwordx4 v[186:187], off
	v_lshl_add_u64 v[186:187], s[48:49], 0, v[0:1]
	s_mov_b32 m0, s82
	s_nop 0
	global_load_lds_dwordx4 v[186:187], off
	v_lshl_add_u64 v[186:187], s[48:49], 0, v[130:131]
	s_mov_b32 m0, s81
	s_nop 0
	global_load_lds_dwordx4 v[186:187], off
	v_lshl_add_u64 v[186:187], v[212:213], 0, s[8:9]
	s_mov_b32 m0, s64
	s_nop 0
	global_load_lds_dwordx4 v[186:187], off
	v_lshl_add_u64 v[186:187], v[214:215], 0, s[8:9]
	s_mov_b32 m0, s65
	s_nop 0
	global_load_lds_dwordx4 v[186:187], off
	s_waitcnt vmcnt(8)
	s_waitcnt lgkmcnt(0)
	s_barrier
	s_setprio 1
	s_waitcnt lgkmcnt(0)
	v_mfma_f32_16x16x32_bf16 v[62:65], v[140:143], v[172:175], v[62:65]
	v_mfma_f32_16x16x32_bf16 v[58:61], v[148:151], v[172:175], v[58:61]
	v_mfma_f32_16x16x32_bf16 v[54:57], v[140:143], v[180:183], v[54:57]
	v_mfma_f32_16x16x32_bf16 v[50:53], v[148:151], v[180:183], v[50:53]
	v_mfma_f32_16x16x32_bf16 v[38:41], v[140:143], v[200:203], v[38:41]
	v_mfma_f32_16x16x32_bf16 v[34:37], v[148:151], v[200:203], v[34:37]
	v_mfma_f32_16x16x32_bf16 v[22:25], v[140:143], v[208:211], v[22:25]
	v_mfma_f32_16x16x32_bf16 v[18:21], v[148:151], v[208:211], v[18:21]
	v_mfma_f32_16x16x32_bf16 v[62:65], v[144:147], v[176:179], v[62:65]
	v_mfma_f32_16x16x32_bf16 v[58:61], v[152:155], v[176:179], v[58:61]
	v_mfma_f32_16x16x32_bf16 v[54:57], v[144:147], v[196:199], v[54:57]
	v_mfma_f32_16x16x32_bf16 v[50:53], v[152:155], v[196:199], v[50:53]
	v_mfma_f32_16x16x32_bf16 v[38:41], v[144:147], v[204:207], v[38:41]
	v_mfma_f32_16x16x32_bf16 v[34:37], v[152:155], v[204:207], v[34:37]
	v_mfma_f32_16x16x32_bf16 v[22:25], v[144:147], v[228:231], v[22:25]
	v_mfma_f32_16x16x32_bf16 v[18:21], v[152:155], v[228:231], v[18:21]
	v_mfma_f32_16x16x32_bf16 v[46:49], v[156:159], v[172:175], v[46:49]
	v_mfma_f32_16x16x32_bf16 v[42:45], v[164:167], v[172:175], v[42:45]
	v_mfma_f32_16x16x32_bf16 v[30:33], v[156:159], v[180:183], v[30:33]
	v_mfma_f32_16x16x32_bf16 v[26:29], v[164:167], v[180:183], v[26:29]
	v_mfma_f32_16x16x32_bf16 v[14:17], v[156:159], v[200:203], v[14:17]
	v_mfma_f32_16x16x32_bf16 v[10:13], v[164:167], v[200:203], v[10:13]
	v_mfma_f32_16x16x32_bf16 v[6:9], v[156:159], v[208:211], v[6:9]
	v_mfma_f32_16x16x32_bf16 v[2:5], v[164:167], v[208:211], v[2:5]
	v_mfma_f32_16x16x32_bf16 v[46:49], v[160:163], v[176:179], v[46:49]
	v_mfma_f32_16x16x32_bf16 v[42:45], v[168:171], v[176:179], v[42:45]
	v_mfma_f32_16x16x32_bf16 v[30:33], v[160:163], v[196:199], v[30:33]
	v_mfma_f32_16x16x32_bf16 v[26:29], v[168:171], v[196:199], v[26:29]
	v_mfma_f32_16x16x32_bf16 v[14:17], v[160:163], v[204:207], v[14:17]
	v_mfma_f32_16x16x32_bf16 v[10:13], v[168:171], v[204:207], v[10:13]
	v_mfma_f32_16x16x32_bf16 v[6:9], v[160:163], v[228:231], v[6:9]
	v_mfma_f32_16x16x32_bf16 v[2:5], v[168:171], v[228:231], v[2:5]
	s_setprio 0
	s_barrier
	s_movk_i32 s50, 0x100
	s_andn2_b64 vcc, exec, s[38:39]
	s_mov_b64 s[48:49], -1
	s_mov_b64 s[38:39], 0
	s_cbranch_vccz .LBB0_360
	s_and_b64 vcc, exec, s[24:25]
	s_cbranch_vccz .LBB0_363
	s_barrier

; DI float bf2f(bf16_t b) { return __uint_as_float(((unsigned)b) << 16); }
; DI float sigmoidf_(float x) { return __builtin_amdgcn_rcpf(1.f + __builtin_amdgcn_exp2f(-LOG2E * x)); }
; DI float siluf_(float x) { return x * __builtin_amdgcn_rcpf(1.f + __builtin_amdgcn_exp2f(-LOG2E * x)); }
;     ...
;           for (int e = 0; e < 19; ++e) { const int ti = tt0 + e - 3; const bool ok = (s0 + ti >= 0); const float vv = bf2f(src[(long)(ok ? ti : 0) * PLD]); xr[part][e] = ok ? vv : 0.f; } } }
;     __syncthreads();
;     if (tid < 64) {
;         const float al = a.small[(size_t)(t0 + tid) * 16 + h], bl = a.small[(size_t)(t0 + tid) * 16 + 4 + h];
;         const float xx = al + a.dtb[h]; const float sp = xx > 20.f ? xx : log1pf(__expf(xx));
;         float g = -__expf(a.alog[h]) * sp;
;         for (int o = 1; o < 64; o <<= 1) { const float t = __shfl_up(g, o); if (lane >= o) g += t; }
;         gcs[tid] = g; betas[tid] = sigmoidf_(bl); egs[tid] = __expf(g);
;     }
;     for (int e = tid; e < 64 * 68; e += NTHR) Tm[e] = 0.f;
;     __syncthreads();
;     {
;         const int seg = tid >> 7, c = tid & 127, tt0 = seg * 16;
;         float y[3][16];
; #pragma unroll
;         for (int part = 0; part < 3; ++part) { const int col = part * 512 + h * 128 + c;
;             const float w0 = a.convw[col], w1 = a.convw[1536 + col], w2 = a.convw[2 * 1536 + col], w3 = a.convw[3 * 1536 + col];
; #pragma unroll
;             for (int e = 0; e < 16; ++e) y[part][e] = siluf_(w0 * xr[part][e] + w1 * xr[part][e + 1] + w2 * xr[part][e + 2] + w3 * xr[part][e + 3]); }
.LBB0_404:
	s_or_b64 exec, exec, s[78:79]
	v_or_b32_e32 v0, s4, v19
	v_lshlrev_b32_e32 v0, 2, v0
	v_lshl_add_u64 v[4:5], s[14:15], 0, v[0:1]
	v_add_co_u32_e64 v6, s[0:1], s87, v4
	s_waitcnt lgkmcnt(0)
	s_nop 0
	v_addc_co_u32_e64 v7, s[0:1], 0, v5, s[0:1]
	s_barrier
	global_load_dword v85, v[6:7], off offset:2048
	global_load_dword v86, v0, s[14:15]
	v_add_co_u32_e64 v8, s[0:1], s76, v4
	s_waitcnt vmcnt(25)
	v_lshlrev_b32_e32 v79, 16, v79
	v_addc_co_u32_e64 v9, s[0:1], 0, v5, s[0:1]
	global_load_dword v87, v[8:9], off offset:-4096
	global_load_dword v88, v[8:9], off offset:2048
	v_lshlrev_b32_e32 v78, 16, v78
	v_lshlrev_b32_e32 v61, 16, v61
	v_cndmask_b32_e64 v79, 0, v79, s[46:47]
	s_waitcnt vmcnt(24)
	v_lshlrev_b32_e32 v80, 16, v80
	v_cndmask_b32_e64 v78, 0, v78, s[44:45]
	v_cndmask_b32_e64 v90, 0, v61, s[62:63]
	v_lshlrev_b32_e32 v10, 16, v10
	v_lshlrev_b32_e32 v2, 16, v2
	v_lshlrev_b32_e32 v62, 16, v62
	v_cndmask_b32_e64 v80, 0, v80, s[48:49]
	s_waitcnt vmcnt(18)
	v_lshlrev_b32_e32 v64, 16, v64
	v_cndmask_b32_e64 v84, v10, 0, s[38:39]
	v_cndmask_b32_e64 v2, 0, v2, s[50:51]
	v_cndmask_b32_e64 v91, 0, v62, s[64:65]
	v_lshlrev_b32_e32 v63, 16, v63
	v_cndmask_b32_e64 v93, 0, v64, s[70:71]
	v_cndmask_b32_e64 v92, 0, v63, s[68:69]
	v_lshlrev_b32_e32 v11, 16, v11
	v_cndmask_b32_e64 v89, 0, v11, s[42:43]
	v_lshlrev_b32_e32 v3, 16, v3
	v_lshlrev_b32_e32 v37, 16, v37
	v_cndmask_b32_e64 v3, 0, v3, s[52:53]
	v_cndmask_b32_e64 v37, 0, v37, s[54:55]
	s_waitcnt vmcnt(12)
	v_lshlrev_b32_e32 v81, 16, v81
	v_cndmask_b32_e64 v94, 0, v81, s[72:73]
	v_lshlrev_b32_e32 v55, 16, v55
	v_cndmask_b32_e64 v55, 0, v55, s[56:57]
	s_waitcnt vmcnt(10)
	v_lshlrev_b32_e32 v83, 16, v83
	v_cndmask_b32_e64 v96, 0, v83, s[66:67]
	v_lshlrev_b32_e32 v59, 16, v59
	v_cndmask_b32_e64 v59, 0, v59, s[58:59]
	v_lshlrev_b32_e32 v82, 16, v82
	v_cndmask_b32_e64 v95, 0, v82, s[74:75]
	v_lshlrev_b32_e32 v60, 16, v60
	v_cndmask_b32_e64 v60, 0, v60, s[60:61]
	v_lshlrev_b32_e32 v36, 16, v36
	v_cndmask_b32_e64 v36, 0, v36, s[40:41]
	s_movk_i32 s0, 0x3000
	v_add_co_u32_e64 v10, s[0:1], s0, v4
	s_waitcnt vmcnt(3)
	v_mul_f32_e32 v61, v79, v85
	s_waitcnt vmcnt(2)
	v_fmac_f32_e32 v61, v78, v86
	v_mul_f32_e32 v62, v80, v85
	v_mul_f32_e32 v64, v84, v85
	v_fmac_f32_e32 v62, v79, v86
	v_mul_f32_e32 v63, v2, v85
	s_waitcnt vmcnt(1)
	v_fmac_f32_e32 v61, v80, v87
	s_waitcnt vmcnt(0)
	v_fmac_f32_e32 v61, v2, v88
	v_fmac_f32_e32 v64, v2, v86
	v_fmac_f32_e32 v62, v2, v87
	v_mul_f32_e32 v2, 0xbfb8aa3b, v61
	v_exp_f32_e32 v2, v2
	v_fmac_f32_e32 v62, v84, v88
	v_mul_f32_e32 v78, 0xbfb8aa3b, v62
	v_mul_f32_e32 v97, v89, v85
	v_exp_f32_e32 v78, v78
	v_add_f32_e32 v2, 1.0, v2
	v_fmac_f32_e32 v97, v84, v86
	v_rcp_f32_e32 v2, v2
	v_fmac_f32_e32 v64, v89, v87
	v_fmac_f32_e32 v97, v3, v87
	v_fmac_f32_e32 v64, v3, v88
	v_fmac_f32_e32 v97, v37, v88
	v_fmac_f32_e32 v63, v80, v86
	v_mul_f32_e32 v80, 0xbfb8aa3b, v64
	v_mul_f32_e32 v81, 0xbfb8aa3b, v97
	v_add_f32_e32 v78, 1.0, v78
	v_fmac_f32_e32 v63, v84, v87
	v_exp_f32_e32 v80, v80
	v_exp_f32_e32 v81, v81
	v_rcp_f32_e32 v78, v78
	v_mul_f32_e32 v84, v61, v2
	v_mul_f32_e32 v61, v3, v85
	v_fmac_f32_e32 v61, v89, v86
	v_fmac_f32_e32 v63, v89, v88
	v_fmac_f32_e32 v61, v37, v87
	v_mul_f32_e32 v79, 0xbfb8aa3b, v63
	v_fmac_f32_e32 v61, v55, v88
	v_exp_f32_e32 v79, v79
	v_add_f32_e32 v80, 1.0, v80
	v_mul_f32_e32 v83, v62, v78
	v_add_f32_e32 v2, 1.0, v81
	v_mul_f32_e32 v62, 0xbfb8aa3b, v61
	v_rcp_f32_e32 v80, v80
	v_rcp_f32_e32 v2, v2
	v_exp_f32_e32 v62, v62
	v_add_f32_e32 v79, 1.0, v79
	v_rcp_f32_e32 v79, v79
	v_mul_f32_e32 v81, v64, v80
	v_mul_f32_e32 v80, v97, v2
	v_add_f32_e32 v2, 1.0, v62
	v_mul_f32_e32 v62, v37, v85
	v_fmac_f32_e32 v62, v3, v86
	v_fmac_f32_e32 v62, v55, v87
	v_fmac_f32_e32 v62, v59, v88
	v_mul_f32_e32 v82, v63, v79
	v_mul_f32_e32 v3, 0xbfb8aa3b, v62
	v_mul_f32_e32 v63, v55, v85
	v_exp_f32_e32 v3, v3
	v_fmac_f32_e32 v63, v37, v86
	v_fmac_f32_e32 v63, v59, v87
	v_fmac_f32_e32 v63, v60, v88
	v_mul_f32_e32 v37, 0xbfb8aa3b, v63
	v_exp_f32_e32 v37, v37
	v_add_f32_e32 v3, 1.0, v3
	v_mul_f32_e32 v89, v59, v85
	v_rcp_f32_e32 v3, v3
	v_fmac_f32_e32 v89, v55, v86
	v_fmac_f32_e32 v89, v60, v87
	v_fmac_f32_e32 v89, v36, v88
	v_add_f32_e32 v37, 1.0, v37
	v_mul_f32_e32 v55, 0xbfb8aa3b, v89
	v_rcp_f32_e32 v2, v2
	v_rcp_f32_e32 v37, v37
	v_exp_f32_e32 v55, v55
	v_mul_f32_e32 v78, v62, v3
	v_mul_f32_e32 v3, v60, v85
	v_fmac_f32_e32 v3, v59, v86
	v_fmac_f32_e32 v3, v36, v87
	v_fmac_f32_e32 v3, v90, v88
	v_mul_f32_e32 v79, v61, v2
	v_mul_f32_e32 v64, v63, v37
	v_add_f32_e32 v2, 1.0, v55
	v_mul_f32_e32 v37, 0xbfb8aa3b, v3
	v_mul_f32_e32 v55, v36, v85
	v_exp_f32_e32 v37, v37
	v_fmac_f32_e32 v55, v60, v86
	v_fmac_f32_e32 v55, v90, v87
	v_fmac_f32_e32 v55, v91, v88
	v_mul_f32_e32 v59, 0xbfb8aa3b, v55
	v_exp_f32_e32 v59, v59
	v_add_f32_e32 v37, 1.0, v37
	v_mul_f32_e32 v60, v90, v85
	v_rcp_f32_e32 v37, v37
	v_fmac_f32_e32 v60, v36, v86
	v_fmac_f32_e32 v60, v91, v87
	v_fmac_f32_e32 v60, v92, v88
	v_add_f32_e32 v59, 1.0, v59
	v_mul_f32_e32 v36, 0xbfb8aa3b, v60
	v_rcp_f32_e32 v2, v2
	v_rcp_f32_e32 v59, v59
	v_exp_f32_e32 v36, v36
	v_mul_f32_e32 v62, v3, v37
	v_mul_f32_e32 v3, v91, v85
	v_mul_f32_e32 v37, v92, v85
	v_fmac_f32_e32 v3, v90, v86
	v_fmac_f32_e32 v37, v91, v86
	v_fmac_f32_e32 v3, v92, v87
	v_fmac_f32_e32 v37, v93, v87
	v_fmac_f32_e32 v3, v93, v88
	v_fmac_f32_e32 v37, v94, v88
	v_mul_f32_e32 v63, v89, v2
	v_mul_f32_e32 v61, v55, v59
	v_add_f32_e32 v2, 1.0, v36
	v_mul_f32_e32 v36, 0xbfb8aa3b, v3
	v_mul_f32_e32 v55, 0xbfb8aa3b, v37
	v_rcp_f32_e32 v2, v2
	v_exp_f32_e32 v36, v36
	v_exp_f32_e32 v55, v55
	v_mul_f32_e32 v89, v93, v85
	v_fmac_f32_e32 v89, v92, v86
; DI float siluf_(float x) { return x * __builtin_amdgcn_rcpf(1.f + __builtin_amdgcn_exp2f(-LOG2E * x)); }
; #define TR_STEP(o, n) { const bool up = (lane & (o)) != 0; _Pragma("unroll") for (int i = 0; i < (n) / 2; ++i) { const float av = v[i], bv = v[i + (n) / 2]; const float snd = up ? av : bv, kp = up ? bv : av; v[i] = kp + __shfl_xor(snd, (o)); } }
;     ...
;             for (int e = 0; e < 16; ++e) y[part][e] = siluf_(w0 * xr[part][e] + w1 * xr[part][e + 1] + w2 * xr[part][e + 2] + w3 * xr[part][e + 3]); }
;         float* ssq = R1;
; #pragma unroll
;         for (int part = 0; part < 2; ++part) {
;             float v[16];
; #pragma unroll
;             for (int e = 0; e < 16; ++e) v[e] = y[part][e] * y[part][e];
;     ...
;             TR_STEP(1, 16) TR_STEP(2, 8) TR_STEP(4, 4) TR_STEP(8, 2)
;     ...
;             float tot = v[0]; tot += __shfl_xor(tot, 16); tot += __shfl_xor(tot, 32);
;             if (lane < 16) { const int e = ((lane & 1) << 3) | ((lane & 2) << 1) | ((lane & 4) >> 1) | ((lane & 8) >> 3); ssq[(part * 64 + tt0 + e) * 2 + (wv & 1)] = tot; }
	v_fmac_f32_e32 v89, v94, v87
	v_fmac_f32_e32 v89, v95, v88
	v_mul_f32_e32 v60, v60, v2
	v_add_f32_e32 v2, 1.0, v36
	v_add_f32_e32 v36, 1.0, v55
	v_mul_f32_e32 v55, 0xbfb8aa3b, v89
	v_mul_f32_e32 v85, v94, v85
	v_exp_f32_e32 v55, v55
	v_fmac_f32_e32 v85, v93, v86
	v_fmac_f32_e32 v85, v95, v87
	v_fmac_f32_e32 v85, v96, v88
	v_mul_f32_e32 v59, 0xbfb8aa3b, v85
	v_exp_f32_e32 v59, v59
	v_add_f32_e32 v55, 1.0, v55
	v_rcp_f32_e32 v36, v36
	v_rcp_f32_e32 v86, v55
	v_addc_co_u32_e64 v11, s[0:1], 0, v5, s[0:1]
	v_rcp_f32_e32 v2, v2
	s_movk_i32 s0, 0x2000
	v_add_f32_e32 v55, 1.0, v59
	v_add_co_u32_e64 v88, s[0:1], s0, v4
	v_rcp_f32_e32 v87, v55
	v_mul_f32_e32 v55, v37, v36
	v_mul_f32_e32 v37, v89, v86
	v_addc_co_u32_e64 v89, s[0:1], 0, v5, s[0:1]
	s_movk_i32 s0, 0x5000
	v_mul_f32_e32 v59, v3, v2
	global_load_dword v3, v0, s[14:15] offset:2048
	global_load_dword v2, v[88:89], off
	s_nop 0
	global_load_dword v0, v[10:11], off offset:2048
	v_add_co_u32_e64 v10, s[0:1], s0, v4
	v_mul_f32_e32 v36, v85, v87
	s_nop 0
	v_addc_co_u32_e64 v11, s[0:1], 0, v5, s[0:1]
	global_load_dword v4, v[10:11], off
	global_load_dword v86, v[6:7], off
	global_load_dword v87, v[88:89], off offset:2048
	s_nop 0
	global_load_dword v89, v[8:9], off
	global_load_dword v88, v[10:11], off offset:2048
	v_and_b32_e32 v5, 1, v38
	v_and_b32_e32 v6, 64, v218
	v_cmp_eq_u32_e64 s[82:83], 0, v5
	v_xor_b32_e32 v5, 1, v218
	v_add_u32_e32 v6, 64, v6
	v_cmp_lt_i32_e64 s[0:1], v5, v6
	v_mul_f32_e32 v7, v84, v84
	v_mul_f32_e32 v96, v63, v63
	v_cndmask_b32_e64 v5, v218, v5, s[0:1]
	v_lshlrev_b32_e32 v93, 2, v5
	v_cndmask_b32_e64 v104, v7, v96, s[82:83]
	v_cndmask_b32_e64 v7, v96, v7, s[82:83]
	s_nop 1
	v_mov_b32_dpp v96, v104 quad_perm:[1,0,3,2] row_mask:0xf bank_mask:0xf
	v_mul_f32_e32 v8, v83, v83
	v_mul_f32_e32 v10, v81, v81
	v_mul_f32_e32 v11, v80, v80
	v_mul_f32_e32 v97, v62, v62
	v_mul_f32_e32 v99, v60, v60
	v_mul_f32_e32 v100, v59, v59
	v_cndmask_b32_e64 v104, v8, v97, s[82:83]
	s_waitcnt lgkmcnt(0)
	v_add_f32_e32 v7, v7, v96
	v_cndmask_b32_e64 v8, v97, v8, s[82:83]
	v_cndmask_b32_e64 v96, v10, v99, s[82:83]
	v_cndmask_b32_e64 v97, v11, v100, s[82:83]
	s_nop 1
	v_mov_b32_dpp v96, v96 quad_perm:[1,0,3,2] row_mask:0xf bank_mask:0xf
	s_nop 1
	v_mov_b32_dpp v97, v97 quad_perm:[1,0,3,2] row_mask:0xf bank_mask:0xf
	v_mul_f32_e32 v9, v82, v82
	v_mul_f32_e32 v85, v79, v79
	v_mul_f32_e32 v94, v78, v78
	v_mul_f32_e32 v95, v64, v64
	v_mul_f32_e32 v98, v61, v61
	v_mul_f32_e32 v101, v55, v55
	v_mul_f32_e32 v102, v37, v37
	v_mul_f32_e32 v103, v36, v36
	v_cndmask_b32_e64 v10, v99, v10, s[82:83]
	v_cndmask_b32_e64 v11, v100, v11, s[82:83]
	v_cndmask_b32_e64 v105, v9, v98, s[82:83]
	v_cndmask_b32_e64 v9, v98, v9, s[82:83]
	v_cndmask_b32_e64 v98, v85, v101, s[82:83]
	s_waitcnt lgkmcnt(1)
	v_add_f32_e32 v10, v10, v96
	s_waitcnt lgkmcnt(0)
	v_add_f32_e32 v11, v11, v97
	v_cndmask_b32_e64 v96, v94, v102, s[82:83]
	v_cndmask_b32_e64 v97, v95, v103, s[82:83]
	s_nop 1
	v_mov_b32_dpp v104, v104 quad_perm:[1,0,3,2] row_mask:0xf bank_mask:0xf
	s_nop 1
	v_mov_b32_dpp v105, v105 quad_perm:[1,0,3,2] row_mask:0xf bank_mask:0xf
	s_nop 1
	v_mov_b32_dpp v98, v98 quad_perm:[1,0,3,2] row_mask:0xf bank_mask:0xf
	s_nop 1
	v_mov_b32_dpp v96, v96 quad_perm:[1,0,3,2] row_mask:0xf bank_mask:0xf
	s_nop 1
	v_mov_b32_dpp v97, v97 quad_perm:[1,0,3,2] row_mask:0xf bank_mask:0xf
	v_and_b32_e32 v5, 2, v38
	v_cmp_eq_u32_e64 s[78:79], 0, v5
	v_xor_b32_e32 v5, 2, v218
	v_cmp_lt_i32_e64 s[0:1], v5, v6
	v_cndmask_b32_e64 v85, v101, v85, s[82:83]
	v_cndmask_b32_e64 v94, v102, v94, s[82:83]
	v_cndmask_b32_e64 v95, v103, v95, s[82:83]
	v_cndmask_b32_e64 v5, v218, v5, s[0:1]
	s_waitcnt lgkmcnt(4)
	v_add_f32_e32 v8, v8, v104
	s_waitcnt lgkmcnt(3)
	v_add_f32_e32 v9, v9, v105
	s_waitcnt lgkmcnt(2)
	v_add_f32_e32 v85, v85, v98
	s_waitcnt lgkmcnt(1)
	v_add_f32_e32 v94, v94, v96
	s_waitcnt lgkmcnt(0)
	v_add_f32_e32 v95, v95, v97
	v_lshlrev_b32_e32 v92, 2, v5
	v_cndmask_b32_e64 v98, v7, v11, s[78:79]
	v_cndmask_b32_e64 v7, v11, v7, s[78:79]
	v_cndmask_b32_e64 v11, v8, v85, s[78:79]
	v_cndmask_b32_e64 v8, v85, v8, s[78:79]
	v_cndmask_b32_e64 v85, v9, v94, s[78:79]
	v_cndmask_b32_e64 v96, v10, v95, s[78:79]
	v_and_b32_e32 v5, 4, v38
	s_nop 1
	v_mov_b32_dpp v98, v98 quad_perm:[2,3,0,1] row_mask:0xf bank_mask:0xf
	s_nop 1
	v_mov_b32_dpp v11, v11 quad_perm:[2,3,0,1] row_mask:0xf bank_mask:0xf
	s_nop 1
	v_mov_b32_dpp v85, v85 quad_perm:[2,3,0,1] row_mask:0xf bank_mask:0xf
	s_nop 1
	v_mov_b32_dpp v96, v96 quad_perm:[2,3,0,1] row_mask:0xf bank_mask:0xf
	v_cmp_eq_u32_e64 s[0:1], 0, v5
	v_xor_b32_e32 v5, 4, v218
	v_cmp_lt_i32_e64 s[80:81], v5, v6
	v_cndmask_b32_e64 v9, v94, v9, s[78:79]
	v_cndmask_b32_e64 v10, v95, v10, s[78:79]
	v_cndmask_b32_e64 v5, v218, v5, s[80:81]
	v_lshlrev_b32_e32 v90, 2, v5
	v_and_b32_e32 v5, 8, v38
	v_cmp_eq_u32_e64 s[80:81], 0, v5
	v_xor_b32_e32 v5, 8, v218
	s_waitcnt lgkmcnt(3)
	v_add_f32_e32 v7, v7, v98
	s_waitcnt lgkmcnt(2)
	v_add_f32_e32 v8, v8, v11
	s_waitcnt lgkmcnt(1)
	v_add_f32_e32 v9, v9, v85
	s_waitcnt lgkmcnt(0)
	v_add_f32_e32 v10, v10, v96
	v_cmp_lt_i32_e64 s[84:85], v5, v6
	v_cndmask_b32_e64 v11, v7, v9, s[0:1]
	v_cndmask_b32_e64 v85, v8, v10, s[0:1]
	v_cndmask_b32_e64 v5, v218, v5, s[84:85]
	ds_bpermute_b32 v11, v90, v11
	ds_bpermute_b32 v85, v90, v85
	v_lshlrev_b32_e32 v91, 2, v5
	v_xor_b32_e32 v5, 16, v218
	v_cmp_lt_i32_e64 s[84:85], v5, v6
	s_nop 1
	v_cndmask_b32_e64 v5, v218, v5, s[84:85]
	v_lshlrev_b32_e32 v94, 2, v5
	v_cndmask_b32_e64 v5, v9, v7, s[0:1]
	v_cndmask_b32_e64 v7, v10, v8, s[0:1]
	s_waitcnt lgkmcnt(1)
	v_add_f32_e32 v5, v5, v11
	s_waitcnt lgkmcnt(0)
	v_add_f32_e32 v7, v7, v85
	v_cndmask_b32_e64 v8, v5, v7, s[80:81]
	s_nop 1
	v_mov_b32_dpp v8, v8 row_ror:8 row_mask:0xf bank_mask:0xf
	v_cndmask_b32_e64 v5, v7, v5, s[80:81]
	v_xor_b32_e32 v9, 32, v218
	v_cmp_lt_i32_e64 s[84:85], v9, v6
	v_bfe_u32 v85, v38, 6, 1
	s_waitcnt lgkmcnt(0)
	v_add_f32_e32 v5, v5, v8
	v_mov_b32_e32 v7, v5
	s_nop 1
	v_permlane16_swap_b32_e32 v7, v5
	v_cndmask_b32_e64 v6, v218, v9, s[84:85]
	v_lshlrev_b32_e32 v95, 2, v6
	v_bfrev_b32_e32 v6, v38
	v_lshrrev_b32_e32 v8, 28, v6
	s_waitcnt lgkmcnt(0)
	v_add_f32_e32 v5, v5, v7
	ds_bpermute_b32 v6, v95, v5
	v_or_b32_e32 v7, v20, v8
	v_lshl_add_u32 v8, v85, 2, 0
	v_cmp_gt_u32_e64 s[84:85], 16, v18
	v_lshl_add_u32 v96, v7, 3, v8
	s_and_saveexec_b64 s[34:35], s[84:85]
	s_cbranch_execz .LBB0_406
	s_waitcnt lgkmcnt(0)
	v_add_f32_e32 v5, v5, v6
	ds_write_b32 v96, v5 offset:36864
; DI float siluf_(float x) { return x * __builtin_amdgcn_rcpf(1.f + __builtin_amdgcn_exp2f(-LOG2E * x)); }
; #define TR_STEP(o, n) { const bool up = (lane & (o)) != 0; _Pragma("unroll") for (int i = 0; i < (n) / 2; ++i) { const float av = v[i], bv = v[i + (n) / 2]; const float snd = up ? av : bv, kp = up ? bv : av; v[i] = kp + __shfl_xor(snd, (o)); } }
;     ...
;         for (int part = 0; part < 3; ++part) { const int col = part * 512 + h * 128 + c;
;             const float w0 = a.convw[col], w1 = a.convw[1536 + col], w2 = a.convw[2 * 1536 + col], w3 = a.convw[3 * 1536 + col];
; #pragma unroll
;             for (int e = 0; e < 16; ++e) y[part][e] = siluf_(w0 * xr[part][e] + w1 * xr[part][e + 1] + w2 * xr[part][e + 2] + w3 * xr[part][e + 3]); }
;         float* ssq = R1;
; #pragma unroll
;         for (int part = 0; part < 2; ++part) {
;             float v[16];
; #pragma unroll
;             for (int e = 0; e < 16; ++e) v[e] = y[part][e] * y[part][e];
;     ...
;             TR_STEP(1, 16) TR_STEP(2, 8) TR_STEP(4, 4) TR_STEP(8, 2)
.LBB0_406:
	s_or_b64 exec, exec, s[34:35]
	v_lshlrev_b32_e32 v5, 16, v76
	s_waitcnt lgkmcnt(0)
	v_lshlrev_b32_e32 v6, 16, v77
	v_cndmask_b32_e64 v7, 0, v6, s[46:47]
	v_cndmask_b32_e64 v6, 0, v5, s[44:45]
	v_lshlrev_b32_e32 v5, 16, v14
	v_lshlrev_b32_e32 v8, 16, v15
	v_cndmask_b32_e64 v11, 0, v8, s[50:51]
	v_cndmask_b32_e64 v10, 0, v5, s[48:49]
	v_lshlrev_b32_e32 v5, 16, v17
	v_lshlrev_b32_e32 v8, 16, v65
	v_cndmask_b32_e64 v77, 0, v8, s[42:43]
	v_cndmask_b32_e64 v76, v5, 0, s[38:39]
	v_lshlrev_b32_e32 v5, 16, v12
	v_lshlrev_b32_e32 v8, 16, v66
	v_cndmask_b32_e64 v9, 0, v8, s[54:55]
	v_cndmask_b32_e64 v8, 0, v5, s[52:53]
	v_lshlrev_b32_e32 v5, 16, v69
	v_lshlrev_b32_e32 v12, 16, v67
	v_cndmask_b32_e64 v99, 0, v5, s[60:61]
	v_lshlrev_b32_e32 v5, 16, v13
	v_cndmask_b32_e64 v67, 0, v12, s[56:57]
	v_cndmask_b32_e64 v101, 0, v5, s[40:41]
	v_lshlrev_b32_e32 v5, 16, v16
	v_lshlrev_b32_e32 v12, 16, v72
	v_lshlrev_b32_e32 v14, 16, v68
	v_cndmask_b32_e64 v103, 0, v12, s[64:65]
	v_cndmask_b32_e64 v102, 0, v5, s[62:63]
	v_lshlrev_b32_e32 v5, 16, v70
	v_lshlrev_b32_e32 v12, 16, v71
	v_lshlrev_b32_e32 v13, 16, v74
	v_cndmask_b32_e64 v69, 0, v14, s[58:59]
	v_lshlrev_b32_e32 v14, 16, v75
	v_cndmask_b32_e64 v71, 0, v12, s[70:71]
	v_cndmask_b32_e64 v70, 0, v5, s[68:69]
	v_lshlrev_b32_e32 v5, 16, v73
	v_cndmask_b32_e64 v73, 0, v13, s[72:73]
	v_pk_mov_b32 v[12:13], v[76:77], v[8:9] op_sel:[1,0]
	v_cndmask_b32_e64 v75, 0, v14, s[74:75]
	s_waitcnt vmcnt(6)
	v_pk_mul_f32 v[14:15], v[12:13], v[2:3] op_sel_hi:[1,0]
	v_mov_b32_e32 v104, v3
	v_pk_fma_f32 v[14:15], v[76:77], v[104:105], v[14:15] op_sel_hi:[1,0,1]
	v_mov_b32_e32 v66, v9
	s_waitcnt vmcnt(5)
	v_pk_fma_f32 v[14:15], v[8:9], v[0:1], v[14:15] op_sel_hi:[1,0,1]
	v_pk_mul_f32 v[108:109], v[66:67], v[2:3] op_sel_hi:[1,0]
	s_waitcnt vmcnt(4)
	v_pk_fma_f32 v[14:15], v[66:67], v[4:5], v[14:15] op_sel_hi:[1,0,1]
	v_mov_b32_e32 v68, v67
	v_mul_f32_e32 v16, 0xbfb8aa3b, v14
	v_exp_f32_e32 v16, v16
	v_mul_f32_e32 v17, 0xbfb8aa3b, v15
	v_exp_f32_e32 v17, v17
	v_cndmask_b32_e64 v107, 0, v5, s[66:67]
	v_add_f32_e32 v5, 1.0, v16
	v_pk_fma_f32 v[8:9], v[8:9], v[104:105], v[108:109] op_sel_hi:[1,0,1]
	v_mov_b32_e32 v98, v69
	v_rcp_f32_e32 v16, v5
	v_add_f32_e32 v5, 1.0, v17
	v_pk_fma_f32 v[8:9], v[68:69], v[0:1], v[8:9] op_sel_hi:[1,0,1]
	v_pk_mov_b32 v[110:111], v[10:11], v[76:77] op_sel:[1,0]
	v_pk_fma_f32 v[8:9], v[98:99], v[4:5], v[8:9] op_sel_hi:[1,0,1]
	v_mov_b32_e32 v100, v99
	v_mul_f32_e32 v17, 0xbfb8aa3b, v8
	v_exp_f32_e32 v65, v17
	v_mul_f32_e32 v17, 0xbfb8aa3b, v9
	v_exp_f32_e32 v66, v17
	v_rcp_f32_e32 v17, v5
	v_add_f32_e32 v5, 1.0, v65
	v_rcp_f32_e32 v108, v5
	v_add_f32_e32 v5, 1.0, v66
	v_rcp_f32_e32 v109, v5
	v_pk_mul_f32 v[14:15], v[14:15], v[16:17]
	v_mov_b32_e32 v66, v69
	v_mov_b32_e32 v69, v99
	v_pk_mul_f32 v[8:9], v[8:9], v[108:109]
	v_pk_mov_b32 v[108:109], v[6:7], v[10:11] op_sel:[1,0]
	v_pk_mul_f32 v[68:69], v[68:69], v[2:3] op_sel:[0,1] op_sel_hi:[1,0]
	v_pk_mul_f32 v[108:109], v[108:109], v[2:3] op_sel_hi:[1,0]
	v_pk_fma_f32 v[66:67], v[66:67], v[2:3], v[68:69] op_sel_hi:[0,1,1]
	v_pk_fma_f32 v[6:7], v[6:7], v[104:105], v[108:109] op_sel_hi:[1,0,1]
	v_mov_b32_e32 v16, v101
	v_pk_fma_f32 v[6:7], v[10:11], v[0:1], v[6:7] op_sel_hi:[1,0,1]
	v_pk_fma_f32 v[66:67], v[100:101], v[0:1], v[66:67] op_sel_hi:[1,0,1]
	v_pk_fma_f32 v[6:7], v[110:111], v[4:5], v[6:7] op_sel_hi:[1,0,1]
	v_pk_mul_f32 v[110:111], v[110:111], v[2:3] op_sel_hi:[1,0]
	v_mul_f32_e32 v5, 0xbfb8aa3b, v6
	v_exp_f32_e32 v5, v5
	v_mul_f32_e32 v17, 0xbfb8aa3b, v7
	v_exp_f32_e32 v65, v17
	v_pk_fma_f32 v[10:11], v[10:11], v[104:105], v[110:111] op_sel_hi:[1,0,1]
	v_add_f32_e32 v5, 1.0, v5
	v_rcp_f32_e32 v108, v5
	v_add_f32_e32 v5, 1.0, v65
	v_pk_fma_f32 v[10:11], v[76:77], v[0:1], v[10:11] op_sel_hi:[1,0,1]
	v_rcp_f32_e32 v109, v5
	v_pk_fma_f32 v[10:11], v[12:13], v[4:5], v[10:11] op_sel_hi:[1,0,1]
	v_mov_b32_e32 v17, v102
	v_mul_f32_e32 v5, 0xbfb8aa3b, v10
	v_exp_f32_e32 v5, v5
	v_mul_f32_e32 v12, 0xbfb8aa3b, v11
	v_exp_f32_e32 v65, v12
	v_pk_mul_f32 v[12:13], v[6:7], v[108:109]
	v_add_f32_e32 v5, 1.0, v5
	v_rcp_f32_e32 v6, v5
	v_add_f32_e32 v5, 1.0, v65
	v_pk_fma_f32 v[66:67], v[16:17], v[4:5], v[66:67] op_sel_hi:[1,0,1]
	v_rcp_f32_e32 v7, v5
	v_mul_f32_e32 v5, 0xbfb8aa3b, v66
	v_exp_f32_e32 v5, v5
	v_mul_f32_e32 v16, 0xbfb8aa3b, v67
	v_exp_f32_e32 v65, v16
	v_pk_mov_b32 v[68:69], v[98:99], v[102:103] op_sel:[1,0]
	v_pk_mul_f32 v[16:17], v[10:11], v[6:7]
	v_mov_b32_e32 v10, v101
	v_pk_mul_f32 v[68:69], v[68:69], v[2:3] op_sel:[0,1] op_sel_hi:[1,0]
	v_add_f32_e32 v5, 1.0, v5
	v_pk_fma_f32 v[10:11], v[10:11], v[2:3], v[68:69] op_sel_hi:[0,1,1]
	v_rcp_f32_e32 v6, v5
	v_add_f32_e32 v5, 1.0, v65
	v_pk_fma_f32 v[10:11], v[102:103], v[0:1], v[10:11] op_sel_hi:[1,0,1]
	v_pk_mov_b32 v[68:69], v[102:103], v[70:71] op_sel:[1,0]
	v_mov_b32_e32 v72, v71
	v_pk_fma_f32 v[76:77], v[68:69], v[4:5], v[10:11] op_sel_hi:[1,0,1]
	v_mov_b32_e32 v74, v73
	v_mul_f32_e32 v3, 0xbfb8aa3b, v76
	v_exp_f32_e32 v3, v3
	v_mul_f32_e32 v7, 0xbfb8aa3b, v77
	v_exp_f32_e32 v10, v7
	v_rcp_f32_e32 v7, v5
	v_add_f32_e32 v3, 1.0, v3
	v_rcp_f32_e32 v98, v3
	v_add_f32_e32 v3, 1.0, v10
	v_pk_mul_f32 v[10:11], v[68:69], v[2:3] op_sel_hi:[1,0]
	v_rcp_f32_e32 v99, v3
	v_pk_fma_f32 v[10:11], v[102:103], v[104:105], v[10:11] op_sel_hi:[1,0,1]
	v_mov_b32_e32 v106, v75
	v_pk_fma_f32 v[10:11], v[70:71], v[0:1], v[10:11] op_sel_hi:[1,0,1]
	s_nop 0
	v_pk_fma_f32 v[68:69], v[72:73], v[4:5], v[10:11] op_sel_hi:[1,0,1]
	s_nop 0
	v_mul_f32_e32 v5, 0xbfb8aa3b, v68
	v_exp_f32_e32 v5, v5
	v_mul_f32_e32 v10, 0xbfb8aa3b, v69
	v_exp_f32_e32 v10, v10
	v_add_f32_e32 v3, 1.0, v5
	v_rcp_f32_e32 v100, v3
	v_pk_mul_f32 v[2:3], v[72:73], v[2:3] op_sel_hi:[1,0]
	v_add_f32_e32 v5, 1.0, v10
	v_pk_fma_f32 v[2:3], v[70:71], v[104:105], v[2:3] op_sel_hi:[1,0,1]
	v_pk_mul_f32 v[10:11], v[66:67], v[6:7]
	v_pk_fma_f32 v[2:3], v[74:75], v[0:1], v[2:3] op_sel_hi:[1,0,1]
	v_pk_mul_f32 v[66:67], v[12:13], v[12:13]
	v_pk_fma_f32 v[2:3], v[106:107], v[4:5], v[2:3] op_sel_hi:[1,0,1]
	v_pk_mul_f32 v[74:75], v[10:11], v[10:11]
	v_mul_f32_e32 v0, 0xbfb8aa3b, v2
	v_exp_f32_e32 v0, v0
	v_mul_f32_e32 v4, 0xbfb8aa3b, v3
	v_exp_f32_e32 v4, v4
	v_rcp_f32_e32 v101, v5
	v_add_f32_e32 v0, 1.0, v0
	v_rcp_f32_e32 v70, v0
	v_add_f32_e32 v0, 1.0, v4
	v_rcp_f32_e32 v71, v0
	v_cndmask_b32_e64 v0, v66, v74, s[82:83]
	v_cndmask_b32_e64 v65, v74, v66, s[82:83]
	s_nop 1
	v_mov_b32_dpp v0, v0 quad_perm:[1,0,3,2] row_mask:0xf bank_mask:0xf
	v_cndmask_b32_e64 v66, v67, v75, s[82:83]
	s_nop 1
	v_mov_b32_dpp v66, v66 quad_perm:[1,0,3,2] row_mask:0xf bank_mask:0xf
	v_pk_mul_f32 v[6:7], v[76:77], v[98:99]
	v_pk_mul_f32 v[4:5], v[68:69], v[100:101]
	v_pk_mul_f32 v[68:69], v[16:17], v[16:17]
	v_pk_mul_f32 v[76:77], v[6:7], v[6:7]
	v_pk_mul_f32 v[2:3], v[2:3], v[70:71]
	v_pk_mul_f32 v[70:71], v[14:15], v[14:15]
	v_pk_mul_f32 v[98:99], v[4:5], v[4:5]
	s_waitcnt lgkmcnt(1)
; #define TR_STEP(o, n) { const bool up = (lane & (o)) != 0; _Pragma("unroll") for (int i = 0; i < (n) / 2; ++i) { const float av = v[i], bv = v[i + (n) / 2]; const float snd = up ? av : bv, kp = up ? bv : av; v[i] = kp + __shfl_xor(snd, (o)); } }
;     ...
;             TR_STEP(1, 16) TR_STEP(2, 8) TR_STEP(4, 4) TR_STEP(8, 2)
;     ...
;             float tot = v[0]; tot += __shfl_xor(tot, 16); tot += __shfl_xor(tot, 32);
;             if (lane < 16) { const int e = ((lane & 1) << 3) | ((lane & 2) << 1) | ((lane & 4) >> 1) | ((lane & 8) >> 3); ssq[(part * 64 + tt0 + e) * 2 + (wv & 1)] = tot; }
	v_add_f32_e32 v0, v65, v0
	v_cndmask_b32_e64 v65, v75, v67, s[82:83]
	v_cndmask_b32_e64 v67, v69, v77, s[82:83]
	v_cndmask_b32_e64 v74, v68, v76, s[82:83]
	s_waitcnt lgkmcnt(0)
	v_add_f32_e32 v65, v65, v66
	v_cndmask_b32_e64 v66, v76, v68, s[82:83]
	v_cndmask_b32_e64 v68, v77, v69, s[82:83]
	s_nop 1
	v_mov_b32_dpp v67, v67 quad_perm:[1,0,3,2] row_mask:0xf bank_mask:0xf
	v_cndmask_b32_e64 v69, v70, v98, s[82:83]
	s_nop 1
	v_mov_b32_dpp v74, v74 quad_perm:[1,0,3,2] row_mask:0xf bank_mask:0xf
	s_nop 1
	v_mov_b32_dpp v69, v69 quad_perm:[1,0,3,2] row_mask:0xf bank_mask:0xf
	v_pk_mul_f32 v[72:73], v[8:9], v[8:9]
	v_pk_mul_f32 v[100:101], v[2:3], v[2:3]
	s_waitcnt lgkmcnt(2)
	v_add_f32_e32 v67, v68, v67
	v_cndmask_b32_e64 v68, v98, v70, s[82:83]
	v_cndmask_b32_e64 v70, v72, v100, s[82:83]
	s_waitcnt lgkmcnt(1)
	v_add_f32_e32 v66, v66, v74
	v_cndmask_b32_e64 v74, v71, v99, s[82:83]
	s_waitcnt lgkmcnt(0)
	v_add_f32_e32 v68, v68, v69
	v_cndmask_b32_e64 v69, v99, v71, s[82:83]
	v_cndmask_b32_e64 v71, v100, v72, s[82:83]
	s_nop 1
	v_mov_b32_dpp v70, v70 quad_perm:[1,0,3,2] row_mask:0xf bank_mask:0xf
	v_cndmask_b32_e64 v72, v73, v101, s[82:83]
	s_nop 1
	v_mov_b32_dpp v74, v74 quad_perm:[1,0,3,2] row_mask:0xf bank_mask:0xf
	s_nop 1
	v_mov_b32_dpp v72, v72 quad_perm:[1,0,3,2] row_mask:0xf bank_mask:0xf
	s_waitcnt lgkmcnt(2)
	v_add_f32_e32 v70, v71, v70
	v_cndmask_b32_e64 v71, v101, v73, s[82:83]
	s_waitcnt lgkmcnt(1)
	v_add_f32_e32 v69, v69, v74
	s_waitcnt lgkmcnt(0)
	v_add_f32_e32 v71, v71, v72
	v_cndmask_b32_e64 v74, v0, v68, s[78:79]
	v_cndmask_b32_e64 v0, v68, v0, s[78:79]
	v_cndmask_b32_e64 v68, v65, v69, s[78:79]
	v_cndmask_b32_e64 v65, v69, v65, s[78:79]
	v_cndmask_b32_e64 v69, v66, v70, s[78:79]
	v_cndmask_b32_e64 v72, v67, v71, s[78:79]
	s_nop 1
	v_mov_b32_dpp v74, v74 quad_perm:[2,3,0,1] row_mask:0xf bank_mask:0xf
	s_nop 1
	v_mov_b32_dpp v68, v68 quad_perm:[2,3,0,1] row_mask:0xf bank_mask:0xf
	s_nop 1
	v_mov_b32_dpp v69, v69 quad_perm:[2,3,0,1] row_mask:0xf bank_mask:0xf
	s_nop 1
	v_mov_b32_dpp v72, v72 quad_perm:[2,3,0,1] row_mask:0xf bank_mask:0xf
	v_cndmask_b32_e64 v66, v70, v66, s[78:79]
	v_cndmask_b32_e64 v67, v71, v67, s[78:79]
	s_waitcnt lgkmcnt(3)
	v_add_f32_e32 v0, v0, v74
	s_waitcnt lgkmcnt(2)
	v_add_f32_e32 v65, v65, v68
	s_waitcnt lgkmcnt(1)
	v_add_f32_e32 v66, v66, v69
	s_waitcnt lgkmcnt(0)
	v_add_f32_e32 v67, v67, v72
	v_cndmask_b32_e64 v68, v0, v66, s[0:1]
	v_cndmask_b32_e64 v69, v65, v67, s[0:1]
	ds_bpermute_b32 v68, v90, v68
	ds_bpermute_b32 v69, v90, v69
	v_cndmask_b32_e64 v0, v66, v0, s[0:1]
	v_cndmask_b32_e64 v65, v67, v65, s[0:1]
	s_waitcnt lgkmcnt(1)
	v_add_f32_e32 v0, v0, v68
	s_waitcnt lgkmcnt(0)
	v_add_f32_e32 v65, v65, v69
	v_cndmask_b32_e64 v66, v0, v65, s[80:81]
	s_nop 1
	v_mov_b32_dpp v66, v66 row_ror:8 row_mask:0xf bank_mask:0xf
	v_cndmask_b32_e64 v0, v65, v0, s[80:81]
	s_waitcnt lgkmcnt(0)
	v_add_f32_e32 v0, v0, v66
	v_mov_b32_e32 v65, v0
	s_nop 1
	v_permlane16_swap_b32_e32 v65, v0
	s_waitcnt lgkmcnt(0)
	v_add_f32_e32 v0, v0, v65
	ds_bpermute_b32 v65, v95, v0
	s_and_saveexec_b64 s[0:1], s[84:85]
	s_cbranch_execz .LBB0_408
	s_waitcnt lgkmcnt(0)
	v_add_f32_e32 v0, v0, v65
	ds_write_b32 v96, v0 offset:37376

; #define PG8_STAGE(bufoff, gbase, voff) do { _Pragma("unroll") for (int _i = 0; _i < 2; ++_i) \
;         __builtin_amdgcn_global_load_lds((const unsigned*)((const char*)(gbase) + (voff)[_i]), (LAS unsigned*)(lds + (bufoff) + ldsw + _i * 8192), 16, 0, 0); } while (0)
; #define PG8_LDA(dst, b, h) do { _Pragma("unroll") for (int m = 0; m < 4; ++m) _Pragma("unroll") for (int k = 0; k < 2; ++k) dst[m][k] = *(const LAS bf16x8*)(lds + PG8_SA(b, h) + aoff + m * 2048 + k * 1024); } while (0)
; #define PG8_LDB(dst, b, h) do { _Pragma("unroll") for (int n = 0; n < 2; ++n) _Pragma("unroll") for (int k = 0; k < 2; ++k) dst[n][k] = *(const LAS bf16x8*)(lds + PG8_SB(b, h) + boff + n * 2048 + k * 1024); } while (0)
; #define PG8_MMA(ai, bj, At, Bt) do { __builtin_amdgcn_s_setprio(1); _Pragma("unroll") for (int m = 0; m < 4; ++m) _Pragma("unroll") for (int n = 0; n < 2; ++n) _Pragma("unroll") for (int k = 0; k < 2; ++k) \
;         acc[ai][bj][m][n] = __builtin_amdgcn_mfma_f32_16x16x32_bf16(Bt[n][k], At[m][k], acc[ai][bj][m][n], 0, 0, 0); __builtin_amdgcn_s_setprio(0); } while (0)
; #define PG8_WAIT_V(n) asm volatile("s_waitcnt vmcnt(" #n ")" ::: "memory")
; #define PG8_WAIT_L(n) asm volatile("s_waitcnt lgkmcnt(" #n ")" ::: "memory")
; #define PG8_BAR __builtin_amdgcn_s_barrier()
; #define PG8_SCHED __builtin_amdgcn_sched_barrier(0)
; template <class Epi>
; DI void gemm_phase(LAS unsigned char* lds, const Gemm g, const Epi& E, const int tid) {
;     ...
;             const char* a1 = cA + (size_t)(t + 1) * kstepA;
;             const char* a2 = last ? nA : cA + (size_t)(t + 2) * kstepA; const char* b2 = last ? nB : cB + (size_t)(t + 2) * kstep;
;             const char* a3 = a2 + kstepA; const char* b3 = b2 + kstep;
;             PG8_LDB(B0, 0, 0); PG8_LDB(B1, 0, 1); PG8_SCHED; PG8_LDA(At, 0, 0); PG8_STAGE(PG8_SA(1, 1), a1 + hstepA, voffA);
;             PG8_WAIT_V(8); PG8_WAIT_L(0); PG8_BAR; PG8_MMA(0, 0, At, B0); PG8_MMA(0, 1, At, B1); PG8_BAR; PG8_SCHED;
;             PG8_LDA(At, 0, 1); PG8_STAGE(PG8_SB(0, 0), b2, voffB); PG8_STAGE(PG8_SB(0, 1), b2 + hstepB, voffB); PG8_STAGE(PG8_SA(0, 0), a2, voffA);
;             PG8_WAIT_V(8); PG8_WAIT_L(0); PG8_BAR; PG8_MMA(1, 0, At, B0); PG8_MMA(1, 1, At, B1); PG8_BAR; PG8_SCHED;
.LBB0_523:
	s_add_u32 s12, s0, 0xfffc0080
	s_addc_u32 s40, s1, -1
	s_add_i32 s65, 0, 0x10000
	s_cmp_eq_u32 s64, 12
	s_cselect_b32 s49, s35, s40
	s_cselect_b32 s48, s60, s12
	v_add_u32_e32 v0, s65, v151
	s_cselect_b32 s41, s43, s63
	s_cselect_b32 s40, s61, s62
	s_add_i32 s12, 0, 0x14000
	ds_read_b128 v[142:145], v0
	ds_read_b128 v[146:149], v0 offset:1024
	ds_read_b128 v[154:157], v0 offset:2048
	ds_read_b128 v[158:161], v0 offset:3072
	v_add_u32_e32 v0, s12, v151
	ds_read_b128 v[162:165], v0
	ds_read_b128 v[166:169], v0 offset:1024
	ds_read_b128 v[170:173], v0 offset:2048
	ds_read_b128 v[174:177], v0 offset:3072
	v_lshl_add_u64 v[182:183], s[0:1], 0, v[138:139]
	s_add_i32 m0, s53, 0xc000
	ds_read_b128 v[178:181], v153
	ds_read_b128 v[196:199], v153 offset:1024
	ds_read_b128 v[200:203], v153 offset:2048
	ds_read_b128 v[204:207], v153 offset:3072
	ds_read_b128 v[208:211], v153 offset:4096
	ds_read_b128 v[228:231], v153 offset:5120
	ds_read_b128 v[232:235], v153 offset:6144
	ds_read_b128 v[236:239], v153 offset:7168
	global_load_lds_dwordx4 v[182:183], off
	v_lshl_add_u64 v[182:183], s[0:1], 0, v[140:141]
	s_add_i32 m0, s53, 0xe000
	s_nop 0
	global_load_lds_dwordx4 v[182:183], off
	s_waitcnt vmcnt(8)
	s_waitcnt lgkmcnt(0)
	s_barrier
	s_setprio 1
	s_waitcnt lgkmcnt(0)
	v_mfma_f32_16x16x32_bf16 v[126:129], v[142:145], v[178:181], v[126:129]
	v_mfma_f32_16x16x32_bf16 v[122:125], v[154:157], v[178:181], v[122:125]
	v_mfma_f32_16x16x32_bf16 v[110:113], v[142:145], v[200:203], v[110:113]
	v_mfma_f32_16x16x32_bf16 v[106:109], v[154:157], v[200:203], v[106:109]
	v_mfma_f32_16x16x32_bf16 v[94:97], v[142:145], v[208:211], v[94:97]
	v_mfma_f32_16x16x32_bf16 v[90:93], v[154:157], v[208:211], v[90:93]
	v_mfma_f32_16x16x32_bf16 v[78:81], v[142:145], v[232:235], v[78:81]
	v_mfma_f32_16x16x32_bf16 v[74:77], v[154:157], v[232:235], v[74:77]
	v_mfma_f32_16x16x32_bf16 v[126:129], v[146:149], v[196:199], v[126:129]
	v_mfma_f32_16x16x32_bf16 v[122:125], v[158:161], v[196:199], v[122:125]
	v_mfma_f32_16x16x32_bf16 v[110:113], v[146:149], v[204:207], v[110:113]
	v_mfma_f32_16x16x32_bf16 v[106:109], v[158:161], v[204:207], v[106:109]
	v_mfma_f32_16x16x32_bf16 v[94:97], v[146:149], v[228:231], v[94:97]
	v_mfma_f32_16x16x32_bf16 v[90:93], v[158:161], v[228:231], v[90:93]
	v_mfma_f32_16x16x32_bf16 v[78:81], v[146:149], v[236:239], v[78:81]
	v_mfma_f32_16x16x32_bf16 v[74:77], v[158:161], v[236:239], v[74:77]
	v_mfma_f32_16x16x32_bf16 v[118:121], v[162:165], v[178:181], v[118:121]
	v_mfma_f32_16x16x32_bf16 v[114:117], v[170:173], v[178:181], v[114:117]
	v_mfma_f32_16x16x32_bf16 v[102:105], v[162:165], v[200:203], v[102:105]
	v_mfma_f32_16x16x32_bf16 v[98:101], v[170:173], v[200:203], v[98:101]
	v_mfma_f32_16x16x32_bf16 v[86:89], v[162:165], v[208:211], v[86:89]
	v_mfma_f32_16x16x32_bf16 v[82:85], v[170:173], v[208:211], v[82:85]
	v_mfma_f32_16x16x32_bf16 v[70:73], v[162:165], v[232:235], v[70:73]
	v_mfma_f32_16x16x32_bf16 v[66:69], v[170:173], v[232:235], v[66:69]
	v_mfma_f32_16x16x32_bf16 v[118:121], v[166:169], v[196:199], v[118:121]
	v_mfma_f32_16x16x32_bf16 v[114:117], v[174:177], v[196:199], v[114:117]
	v_mfma_f32_16x16x32_bf16 v[102:105], v[166:169], v[204:207], v[102:105]
	v_mfma_f32_16x16x32_bf16 v[98:101], v[174:177], v[204:207], v[98:101]
	v_mfma_f32_16x16x32_bf16 v[86:89], v[166:169], v[228:231], v[86:89]
	v_mfma_f32_16x16x32_bf16 v[82:85], v[174:177], v[228:231], v[82:85]
	v_mfma_f32_16x16x32_bf16 v[70:73], v[166:169], v[236:239], v[70:73]
	v_mfma_f32_16x16x32_bf16 v[66:69], v[174:177], v[236:239], v[66:69]
	s_setprio 0
	s_barrier
	s_add_i32 s65, s65, s52
	v_lshl_add_u64 v[182:183], s[40:41], 0, v[134:135]
	s_mov_b32 m0, s65
	ds_read_b128 v[178:181], v153 offset:16384
	ds_read_b128 v[196:199], v153 offset:17408
	ds_read_b128 v[200:203], v153 offset:18432
	ds_read_b128 v[204:207], v153 offset:19456
	ds_read_b128 v[208:211], v153 offset:20480
	ds_read_b128 v[228:231], v153 offset:21504
	ds_read_b128 v[232:235], v153 offset:22528
	ds_read_b128 v[236:239], v153 offset:23552
	global_load_lds_dwordx4 v[182:183], off
	s_add_i32 m0, s65, 0x2000
	s_add_u32 s66, s40, 0x40000
	v_lshl_add_u64 v[186:187], s[40:41], 0, v[130:131]
	s_addc_u32 s67, s41, 0
	s_add_i32 s12, s12, s52
	global_load_lds_dwordx4 v[186:187], off
	v_lshl_add_u64 v[188:189], s[66:67], 0, v[134:135]
	s_mov_b32 m0, s12
	v_lshl_add_u64 v[212:213], s[48:49], 0, v[132:133]
	global_load_lds_dwordx4 v[188:189], off
	v_lshl_add_u64 v[188:189], s[66:67], 0, v[130:131]
	s_add_i32 m0, s12, 0x2000
	s_nop 0
	global_load_lds_dwordx4 v[188:189], off
	v_lshl_add_u64 v[188:189], s[48:49], 0, v[136:137]
	s_mov_b32 m0, s53
	s_nop 0
	global_load_lds_dwordx4 v[188:189], off
	s_mov_b32 m0, s54
	s_nop 0
	global_load_lds_dwordx4 v[212:213], off
	s_waitcnt vmcnt(8)
	s_waitcnt lgkmcnt(0)
	s_barrier
; #define PG8_STAGE(bufoff, gbase, voff) do { _Pragma("unroll") for (int _i = 0; _i < 2; ++_i) \
;         __builtin_amdgcn_global_load_lds((const unsigned*)((const char*)(gbase) + (voff)[_i]), (LAS unsigned*)(lds + (bufoff) + ldsw + _i * 8192), 16, 0, 0); } while (0)
; #define PG8_LDA(dst, b, h) do { _Pragma("unroll") for (int m = 0; m < 4; ++m) _Pragma("unroll") for (int k = 0; k < 2; ++k) dst[m][k] = *(const LAS bf16x8*)(lds + PG8_SA(b, h) + aoff + m * 2048 + k * 1024); } while (0)
; #define PG8_LDB(dst, b, h) do { _Pragma("unroll") for (int n = 0; n < 2; ++n) _Pragma("unroll") for (int k = 0; k < 2; ++k) dst[n][k] = *(const LAS bf16x8*)(lds + PG8_SB(b, h) + boff + n * 2048 + k * 1024); } while (0)
; #define PG8_MMA(ai, bj, At, Bt) do { __builtin_amdgcn_s_setprio(1); _Pragma("unroll") for (int m = 0; m < 4; ++m) _Pragma("unroll") for (int n = 0; n < 2; ++n) _Pragma("unroll") for (int k = 0; k < 2; ++k) \
;         acc[ai][bj][m][n] = __builtin_amdgcn_mfma_f32_16x16x32_bf16(Bt[n][k], At[m][k], acc[ai][bj][m][n], 0, 0, 0); __builtin_amdgcn_s_setprio(0); } while (0)
; #define PG8_WAIT_V(n) asm volatile("s_waitcnt vmcnt(" #n ")" ::: "memory")
; #define PG8_WAIT_L(n) asm volatile("s_waitcnt lgkmcnt(" #n ")" ::: "memory")
; #define PG8_BAR __builtin_amdgcn_s_barrier()
; #define PG8_SCHED __builtin_amdgcn_sched_barrier(0)
; template <class Epi>
; DI void gemm_phase(LAS unsigned char* lds, const Gemm g, const Epi& E, const int tid) {
;     ...
;             PG8_WAIT_V(8); PG8_WAIT_L(0); PG8_BAR; PG8_MMA(1, 0, At, B0); PG8_MMA(1, 1, At, B1); PG8_BAR; PG8_SCHED;
;             PG8_LDB(B0, 1, 0); PG8_LDB(B1, 1, 1); PG8_SCHED; PG8_LDA(At, 1, 0); PG8_STAGE(PG8_SA(0, 1), a2 + hstepA, voffA);
;             PG8_WAIT_V(8); PG8_WAIT_L(0); PG8_BAR; PG8_MMA(0, 0, At, B0); PG8_MMA(0, 1, At, B1); PG8_BAR; PG8_SCHED;
	s_setprio 1
	s_waitcnt lgkmcnt(0)
	v_mfma_f32_16x16x32_bf16 v[62:65], v[142:145], v[178:181], v[62:65]
	v_mfma_f32_16x16x32_bf16 v[58:61], v[154:157], v[178:181], v[58:61]
	v_mfma_f32_16x16x32_bf16 v[46:49], v[142:145], v[200:203], v[46:49]
	v_mfma_f32_16x16x32_bf16 v[42:45], v[154:157], v[200:203], v[42:45]
	v_mfma_f32_16x16x32_bf16 v[30:33], v[142:145], v[208:211], v[30:33]
	v_mfma_f32_16x16x32_bf16 v[26:29], v[154:157], v[208:211], v[26:29]
	v_mfma_f32_16x16x32_bf16 v[14:17], v[142:145], v[232:235], v[14:17]
	v_mfma_f32_16x16x32_bf16 v[10:13], v[154:157], v[232:235], v[10:13]
	v_mfma_f32_16x16x32_bf16 v[62:65], v[146:149], v[196:199], v[62:65]
	v_mfma_f32_16x16x32_bf16 v[58:61], v[158:161], v[196:199], v[58:61]
	v_mfma_f32_16x16x32_bf16 v[46:49], v[146:149], v[204:207], v[46:49]
	v_mfma_f32_16x16x32_bf16 v[42:45], v[158:161], v[204:207], v[42:45]
	v_mfma_f32_16x16x32_bf16 v[30:33], v[146:149], v[228:231], v[30:33]
	v_mfma_f32_16x16x32_bf16 v[26:29], v[158:161], v[228:231], v[26:29]
	v_mfma_f32_16x16x32_bf16 v[14:17], v[146:149], v[236:239], v[14:17]
	v_mfma_f32_16x16x32_bf16 v[10:13], v[158:161], v[236:239], v[10:13]
	v_mfma_f32_16x16x32_bf16 v[54:57], v[162:165], v[178:181], v[54:57]
	v_mfma_f32_16x16x32_bf16 v[50:53], v[170:173], v[178:181], v[50:53]
	v_mfma_f32_16x16x32_bf16 v[38:41], v[162:165], v[200:203], v[38:41]
	v_mfma_f32_16x16x32_bf16 v[34:37], v[170:173], v[200:203], v[34:37]
	v_mfma_f32_16x16x32_bf16 v[22:25], v[162:165], v[208:211], v[22:25]
	v_mfma_f32_16x16x32_bf16 v[18:21], v[170:173], v[208:211], v[18:21]
	v_mfma_f32_16x16x32_bf16 v[6:9], v[162:165], v[232:235], v[6:9]
	v_mfma_f32_16x16x32_bf16 v[2:5], v[170:173], v[232:235], v[2:5]
	v_mfma_f32_16x16x32_bf16 v[54:57], v[166:169], v[196:199], v[54:57]
	v_mfma_f32_16x16x32_bf16 v[50:53], v[174:177], v[196:199], v[50:53]
	v_mfma_f32_16x16x32_bf16 v[38:41], v[166:169], v[204:207], v[38:41]
	v_mfma_f32_16x16x32_bf16 v[34:37], v[174:177], v[204:207], v[34:37]
	v_mfma_f32_16x16x32_bf16 v[22:25], v[166:169], v[228:231], v[22:25]
	v_mfma_f32_16x16x32_bf16 v[18:21], v[174:177], v[228:231], v[18:21]
	v_mfma_f32_16x16x32_bf16 v[6:9], v[166:169], v[236:239], v[6:9]
	v_mfma_f32_16x16x32_bf16 v[2:5], v[174:177], v[236:239], v[2:5]
	s_setprio 0
	s_barrier
	s_add_i32 s12, 0, 0x18000
	v_add_u32_e32 v0, s12, v151
	s_add_i32 s65, 0, 0x1c000
	ds_read_b128 v[142:145], v0
	ds_read_b128 v[146:149], v0 offset:1024
	ds_read_b128 v[154:157], v0 offset:2048
	ds_read_b128 v[158:161], v0 offset:3072
	v_add_u32_e32 v0, s65, v151
	ds_read_b128 v[162:165], v0
	ds_read_b128 v[166:169], v0 offset:1024
	ds_read_b128 v[170:173], v0 offset:2048
	ds_read_b128 v[174:177], v0 offset:3072
	s_add_u32 s48, s48, 0x40000
	s_addc_u32 s49, s49, 0
	s_mov_b32 m0, s55
	v_lshl_add_u64 v[214:215], s[48:49], 0, v[136:137]
	ds_read_b128 v[178:181], v153 offset:32768
	ds_read_b128 v[196:199], v153 offset:33792
	ds_read_b128 v[200:203], v153 offset:34816
	ds_read_b128 v[204:207], v153 offset:35840
	ds_read_b128 v[208:211], v153 offset:36864
	ds_read_b128 v[228:231], v153 offset:37888
	ds_read_b128 v[232:235], v153 offset:38912
	ds_read_b128 v[236:239], v153 offset:39936
	global_load_lds_dwordx4 v[214:215], off
	v_lshl_add_u64 v[214:215], s[48:49], 0, v[132:133]
	s_mov_b32 m0, s56
	s_nop 0
	global_load_lds_dwordx4 v[214:215], off
	s_waitcnt vmcnt(8)
	s_waitcnt lgkmcnt(0)
	s_barrier
	s_setprio 1
	s_waitcnt lgkmcnt(0)
	v_mfma_f32_16x16x32_bf16 v[126:129], v[142:145], v[178:181], v[126:129]
	v_mfma_f32_16x16x32_bf16 v[122:125], v[154:157], v[178:181], v[122:125]
	v_mfma_f32_16x16x32_bf16 v[110:113], v[142:145], v[200:203], v[110:113]
	v_mfma_f32_16x16x32_bf16 v[106:109], v[154:157], v[200:203], v[106:109]
	v_mfma_f32_16x16x32_bf16 v[94:97], v[142:145], v[208:211], v[94:97]
	v_mfma_f32_16x16x32_bf16 v[90:93], v[154:157], v[208:211], v[90:93]
	v_mfma_f32_16x16x32_bf16 v[78:81], v[142:145], v[232:235], v[78:81]
	v_mfma_f32_16x16x32_bf16 v[74:77], v[154:157], v[232:235], v[74:77]
	v_mfma_f32_16x16x32_bf16 v[126:129], v[146:149], v[196:199], v[126:129]
	v_mfma_f32_16x16x32_bf16 v[122:125], v[158:161], v[196:199], v[122:125]
	v_mfma_f32_16x16x32_bf16 v[110:113], v[146:149], v[204:207], v[110:113]
	v_mfma_f32_16x16x32_bf16 v[106:109], v[158:161], v[204:207], v[106:109]
	v_mfma_f32_16x16x32_bf16 v[94:97], v[146:149], v[228:231], v[94:97]
	v_mfma_f32_16x16x32_bf16 v[90:93], v[158:161], v[228:231], v[90:93]
	v_mfma_f32_16x16x32_bf16 v[78:81], v[146:149], v[236:239], v[78:81]
	v_mfma_f32_16x16x32_bf16 v[74:77], v[158:161], v[236:239], v[74:77]
	v_mfma_f32_16x16x32_bf16 v[118:121], v[162:165], v[178:181], v[118:121]
	v_mfma_f32_16x16x32_bf16 v[114:117], v[170:173], v[178:181], v[114:117]
	v_mfma_f32_16x16x32_bf16 v[102:105], v[162:165], v[200:203], v[102:105]
	v_mfma_f32_16x16x32_bf16 v[98:101], v[170:173], v[200:203], v[98:101]
	v_mfma_f32_16x16x32_bf16 v[86:89], v[162:165], v[208:211], v[86:89]
	v_mfma_f32_16x16x32_bf16 v[82:85], v[170:173], v[208:211], v[82:85]
	v_mfma_f32_16x16x32_bf16 v[70:73], v[162:165], v[232:235], v[70:73]
	v_mfma_f32_16x16x32_bf16 v[66:69], v[170:173], v[232:235], v[66:69]
	v_mfma_f32_16x16x32_bf16 v[118:121], v[166:169], v[196:199], v[118:121]
	v_mfma_f32_16x16x32_bf16 v[114:117], v[174:177], v[196:199], v[114:117]
	v_mfma_f32_16x16x32_bf16 v[102:105], v[166:169], v[204:207], v[102:105]
	v_mfma_f32_16x16x32_bf16 v[98:101], v[174:177], v[204:207], v[98:101]
	v_mfma_f32_16x16x32_bf16 v[86:89], v[166:169], v[228:231], v[86:89]
	v_mfma_f32_16x16x32_bf16 v[82:85], v[174:177], v[228:231], v[82:85]
	v_mfma_f32_16x16x32_bf16 v[70:73], v[166:169], v[236:239], v[70:73]
	v_mfma_f32_16x16x32_bf16 v[66:69], v[174:177], v[236:239], v[66:69]
	s_setprio 0
	s_barrier
; #define PG8_STAGE(bufoff, gbase, voff) do { _Pragma("unroll") for (int _i = 0; _i < 2; ++_i) \
;         __builtin_amdgcn_global_load_lds((const unsigned*)((const char*)(gbase) + (voff)[_i]), (LAS unsigned*)(lds + (bufoff) + ldsw + _i * 8192), 16, 0, 0); } while (0)
; #define PG8_LDA(dst, b, h) do { _Pragma("unroll") for (int m = 0; m < 4; ++m) _Pragma("unroll") for (int k = 0; k < 2; ++k) dst[m][k] = *(const LAS bf16x8*)(lds + PG8_SA(b, h) + aoff + m * 2048 + k * 1024); } while (0)
; #define PG8_MMA(ai, bj, At, Bt) do { __builtin_amdgcn_s_setprio(1); _Pragma("unroll") for (int m = 0; m < 4; ++m) _Pragma("unroll") for (int n = 0; n < 2; ++n) _Pragma("unroll") for (int k = 0; k < 2; ++k) \
;         acc[ai][bj][m][n] = __builtin_amdgcn_mfma_f32_16x16x32_bf16(Bt[n][k], At[m][k], acc[ai][bj][m][n], 0, 0, 0); __builtin_amdgcn_s_setprio(0); } while (0)
; #define PG8_WAIT_V(n) asm volatile("s_waitcnt vmcnt(" #n ")" ::: "memory")
; #define PG8_WAIT_L(n) asm volatile("s_waitcnt lgkmcnt(" #n ")" ::: "memory")
; #define PG8_BAR __builtin_amdgcn_s_barrier()
; #define PG8_SCHED __builtin_amdgcn_sched_barrier(0)
; template <class Epi>
; DI void gemm_phase(LAS unsigned char* lds, const Gemm g, const Epi& E, const int tid) {
;     ...
;             PG8_LDA(At, 1, 1); PG8_STAGE(PG8_SB(1, 0), b3, voffB); PG8_STAGE(PG8_SB(1, 1), b3 + hstepB, voffB); PG8_STAGE(PG8_SA(1, 0), a3, voffA);
;             PG8_WAIT_V(8); PG8_WAIT_L(0); PG8_BAR; PG8_MMA(1, 0, At, B0); PG8_MMA(1, 1, At, B1); PG8_BAR; PG8_SCHED;
;         }
;         if (wr == 0) PG8_BAR;
	s_add_i32 s12, s12, s52
	v_lshl_add_u64 v[182:183], v[182:183], 0, s[8:9]
	s_mov_b32 m0, s12
	ds_read_b128 v[178:181], v153 offset:49152
	ds_read_b128 v[196:199], v153 offset:50176
	ds_read_b128 v[200:203], v153 offset:51200
	ds_read_b128 v[204:207], v153 offset:52224
	ds_read_b128 v[208:211], v153 offset:53248
	ds_read_b128 v[228:231], v153 offset:54272
	ds_read_b128 v[232:235], v153 offset:55296
	ds_read_b128 v[236:239], v153 offset:56320
	global_load_lds_dwordx4 v[182:183], off
	s_add_i32 m0, s12, 0x2000
	s_add_u32 s40, s40, 0x40080
	v_lshl_add_u64 v[182:183], v[186:187], 0, s[8:9]
	s_addc_u32 s41, s41, 0
	s_add_i32 s12, s65, s52
	global_load_lds_dwordx4 v[182:183], off
	v_lshl_add_u64 v[182:183], s[40:41], 0, v[134:135]
	s_mov_b32 m0, s12
	s_nop 0
	global_load_lds_dwordx4 v[182:183], off
	v_lshl_add_u64 v[182:183], s[40:41], 0, v[130:131]
	s_add_i32 m0, s12, 0x2000
	s_nop 0
	global_load_lds_dwordx4 v[182:183], off
	v_lshl_add_u64 v[182:183], v[188:189], 0, s[8:9]
	s_mov_b32 m0, s57
	s_nop 0
	global_load_lds_dwordx4 v[182:183], off
	v_lshl_add_u64 v[182:183], v[212:213], 0, s[8:9]
	s_mov_b32 m0, s58
	s_nop 0
	global_load_lds_dwordx4 v[182:183], off
	s_waitcnt vmcnt(8)
	s_waitcnt lgkmcnt(0)
	s_barrier
	s_setprio 1
	s_waitcnt lgkmcnt(0)
	v_mfma_f32_16x16x32_bf16 v[62:65], v[142:145], v[178:181], v[62:65]
	v_mfma_f32_16x16x32_bf16 v[58:61], v[154:157], v[178:181], v[58:61]
	v_mfma_f32_16x16x32_bf16 v[46:49], v[142:145], v[200:203], v[46:49]
	v_mfma_f32_16x16x32_bf16 v[42:45], v[154:157], v[200:203], v[42:45]
	v_mfma_f32_16x16x32_bf16 v[30:33], v[142:145], v[208:211], v[30:33]
	v_mfma_f32_16x16x32_bf16 v[26:29], v[154:157], v[208:211], v[26:29]
	v_mfma_f32_16x16x32_bf16 v[14:17], v[142:145], v[232:235], v[14:17]
	v_mfma_f32_16x16x32_bf16 v[10:13], v[154:157], v[232:235], v[10:13]
	v_mfma_f32_16x16x32_bf16 v[62:65], v[146:149], v[196:199], v[62:65]
	v_mfma_f32_16x16x32_bf16 v[58:61], v[158:161], v[196:199], v[58:61]
	v_mfma_f32_16x16x32_bf16 v[46:49], v[146:149], v[204:207], v[46:49]
	v_mfma_f32_16x16x32_bf16 v[42:45], v[158:161], v[204:207], v[42:45]
	v_mfma_f32_16x16x32_bf16 v[30:33], v[146:149], v[228:231], v[30:33]
	v_mfma_f32_16x16x32_bf16 v[26:29], v[158:161], v[228:231], v[26:29]
	v_mfma_f32_16x16x32_bf16 v[14:17], v[146:149], v[236:239], v[14:17]
	v_mfma_f32_16x16x32_bf16 v[10:13], v[158:161], v[236:239], v[10:13]
	v_mfma_f32_16x16x32_bf16 v[54:57], v[162:165], v[178:181], v[54:57]
	v_mfma_f32_16x16x32_bf16 v[50:53], v[170:173], v[178:181], v[50:53]
	v_mfma_f32_16x16x32_bf16 v[38:41], v[162:165], v[200:203], v[38:41]
	v_mfma_f32_16x16x32_bf16 v[34:37], v[170:173], v[200:203], v[34:37]
	v_mfma_f32_16x16x32_bf16 v[22:25], v[162:165], v[208:211], v[22:25]
	v_mfma_f32_16x16x32_bf16 v[18:21], v[170:173], v[208:211], v[18:21]
	v_mfma_f32_16x16x32_bf16 v[6:9], v[162:165], v[232:235], v[6:9]
	v_mfma_f32_16x16x32_bf16 v[2:5], v[170:173], v[232:235], v[2:5]
	v_mfma_f32_16x16x32_bf16 v[54:57], v[166:169], v[196:199], v[54:57]
	v_mfma_f32_16x16x32_bf16 v[50:53], v[174:177], v[196:199], v[50:53]
	v_mfma_f32_16x16x32_bf16 v[38:41], v[166:169], v[204:207], v[38:41]
	v_mfma_f32_16x16x32_bf16 v[34:37], v[174:177], v[204:207], v[34:37]
	v_mfma_f32_16x16x32_bf16 v[22:25], v[166:169], v[228:231], v[22:25]
	v_mfma_f32_16x16x32_bf16 v[18:21], v[174:177], v[228:231], v[18:21]
	v_mfma_f32_16x16x32_bf16 v[6:9], v[166:169], v[236:239], v[6:9]
	v_mfma_f32_16x16x32_bf16 v[2:5], v[174:177], v[236:239], v[2:5]
	s_setprio 0
	s_barrier
	s_add_i32 s64, s64, 2
	s_add_u32 s0, s0, 0x100
	s_addc_u32 s1, s1, 0
	s_add_u32 s62, s62, 0x100
	s_addc_u32 s63, s63, 0
	s_cmp_gt_u32 s64, 13
	s_cbranch_scc0 .LBB0_523
	s_and_b64 vcc, exec, s[24:25]
	s_cbranch_vccz .LBB0_526
	s_barrier
